# v23: v22 plus nt stores for the fused phases' U and YB intermediates (consumed by the same workgroup immediately)
# baseline (speedup 1.0000x reference)
.LBB0_427:
	s_min_u32 s8, s29, 29
	s_ashr_i32 s15, s14, 31
	s_waitcnt vmcnt(0) lgkmcnt(0)
	v_lshlrev_b32_e32 v89, 16, v62
	v_and_b32_e32 v98, 0xffff0000, v62
	v_lshlrev_b32_e32 v99, 16, v63
	v_and_b32_e32 v100, 0xffff0000, v63
	v_lshlrev_b32_e32 v101, 16, v64
	v_and_b32_e32 v102, 0xffff0000, v64
	v_lshlrev_b32_e32 v103, 16, v65
	v_and_b32_e32 v104, 0xffff0000, v65
	v_lshlrev_b32_e32 v76, 16, v61
	v_and_b32_e32 v77, 0xffff0000, v61
	v_lshlrev_b32_e32 v78, 16, v57
	v_and_b32_e32 v79, 0xffff0000, v57
	v_lshlrev_b32_e32 v80, 16, v60
	v_and_b32_e32 v81, 0xffff0000, v60
	v_lshlrev_b32_e32 v60, 16, v56
	v_and_b32_e32 v61, 0xffff0000, v56
	v_lshlrev_b32_e32 v56, 16, v59
	v_and_b32_e32 v57, 0xffff0000, v59
	v_lshlrev_b32_e32 v82, 16, v55
	v_and_b32_e32 v83, 0xffff0000, v55
	v_lshlrev_b32_e32 v84, 16, v58
	v_and_b32_e32 v85, 0xffff0000, v58
	v_lshlrev_b32_e32 v58, 16, v54
	v_and_b32_e32 v59, 0xffff0000, v54
	v_lshlrev_b32_e32 v105, 16, v26
	v_and_b32_e32 v106, 0xffff0000, v26
	v_lshlrev_b32_e32 v107, 16, v27
	v_and_b32_e32 v108, 0xffff0000, v27
	v_lshlrev_b32_e32 v109, 16, v28
	v_and_b32_e32 v110, 0xffff0000, v28
	v_lshlrev_b32_e32 v111, 16, v29
	v_and_b32_e32 v112, 0xffff0000, v29
	v_lshlrev_b32_e32 v54, 16, v25
	v_and_b32_e32 v55, 0xffff0000, v25
	v_lshlrev_b32_e32 v90, 16, v21
	v_and_b32_e32 v91, 0xffff0000, v21
	v_lshlrev_b32_e32 v92, 16, v24
	v_and_b32_e32 v93, 0xffff0000, v24
	v_lshlrev_b32_e32 v24, 16, v20
	v_and_b32_e32 v25, 0xffff0000, v20
	v_lshlrev_b32_e32 v20, 16, v23
	v_and_b32_e32 v21, 0xffff0000, v23
	v_lshlrev_b32_e32 v94, 16, v19
	v_and_b32_e32 v95, 0xffff0000, v19
	v_lshlrev_b32_e32 v96, 16, v22
	v_and_b32_e32 v97, 0xffff0000, v22
	v_lshlrev_b32_e32 v22, 16, v18
	v_and_b32_e32 v23, 0xffff0000, v18
	v_mov_b64_e32 v[26:27], v[34:35]
	v_mov_b64_e32 v[64:65], v[32:33]
	s_lshl_b32 s8, s8, 3
	v_mov_b64_e32 v[28:29], v[36:37]
	v_mov_b64_e32 v[62:63], v[30:31]
	s_lshl_b64 s[0:1], s[14:15], 11
	v_mul_f32_e32 v30, 0xbfb8aa3b, v89
	v_mul_f32_e32 v31, 0xbfb8aa3b, v98
	v_mul_f32_e32 v32, 0xbfb8aa3b, v99
	v_mul_f32_e32 v33, 0xbfb8aa3b, v100
	v_mul_f32_e32 v34, 0xbfb8aa3b, v101
	v_mul_f32_e32 v35, 0xbfb8aa3b, v102
	v_mul_f32_e32 v36, 0xbfb8aa3b, v103
	v_mul_f32_e32 v37, 0xbfb8aa3b, v104
	v_pk_add_f32 v[76:77], v[78:79], v[76:77]
	v_pk_add_f32 v[78:79], v[60:61], v[80:81]
	v_pk_add_f32 v[80:81], v[82:83], v[56:57]
	v_pk_add_f32 v[82:83], v[58:59], v[84:85]
	v_pk_add_f32 v[84:85], v[90:91], v[54:55]
	v_pk_add_f32 v[90:91], v[24:25], v[92:93]
	v_pk_add_f32 v[92:93], v[94:95], v[20:21]
	v_pk_add_f32 v[94:95], v[22:23], v[96:97]
	v_mov_b64_e32 v[18:19], v[46:47]
	v_mov_b64_e32 v[60:61], v[44:45]
	v_mov_b64_e32 v[22:23], v[38:39]
	s_add_i32 s8, s28, s8
	v_mul_f32_e32 v89, 0xbfb8aa3b, v105
	v_mul_f32_e32 v98, 0xbfb8aa3b, v106
	v_mul_f32_e32 v99, 0xbfb8aa3b, v107
	v_mul_f32_e32 v100, 0xbfb8aa3b, v108
	v_mul_f32_e32 v101, 0xbfb8aa3b, v109
	v_mul_f32_e32 v102, 0xbfb8aa3b, v110
	v_mul_f32_e32 v103, 0xbfb8aa3b, v111
	v_mul_f32_e32 v104, 0xbfb8aa3b, v112
	v_mov_b64_e32 v[56:57], v[52:53]
	v_mov_b64_e32 v[20:21], v[48:49]
	v_mov_b64_e32 v[58:59], v[42:43]
	v_mov_b64_e32 v[24:25], v[40:41]
	v_exp_f32_e32 v105, v30
	v_exp_f32_e32 v106, v31
	v_exp_f32_e32 v107, v32
	v_exp_f32_e32 v108, v33
	v_exp_f32_e32 v109, v34
	v_exp_f32_e32 v110, v35
	v_exp_f32_e32 v111, v36
	v_exp_f32_e32 v112, v37
	v_mov_b32_e32 v30, v80
	v_mov_b32_e32 v31, v76
	v_mov_b32_e32 v32, v81
	v_mov_b32_e32 v33, v77
	v_mov_b32_e32 v34, v82
	v_mov_b32_e32 v35, v78
	v_mov_b32_e32 v36, v83
	v_mov_b32_e32 v37, v79
	v_lshl_add_u64 v[96:97], v[74:75], 0, s[0:1]
	v_mov_b32_e32 v38, v92
	v_mov_b32_e32 v39, v84
	v_mov_b32_e32 v40, v93
	v_mov_b32_e32 v41, v85
	v_mov_b32_e32 v42, v94
	v_mov_b32_e32 v43, v90
	v_mov_b32_e32 v44, v95
	v_mov_b32_e32 v45, v91
	s_ashr_i32 s9, s8, 31
	v_mad_i64_i32 v[46:47], s[0:1], s8, v86, v[72:73]
	v_mov_b64_e32 v[54:55], v[50:51]
	v_pk_add_f32 v[48:49], v[30:31], v[32:33]
	v_pk_add_f32 v[50:51], v[34:35], v[36:37]
	v_pk_add_f32 v[38:39], v[38:39], v[40:41]
	v_pk_add_f32 v[40:41], v[42:43], v[44:45]
	s_lshl_b64 s[0:1], s[8:9], 11
	global_load_dwordx4 v[30:33], v[46:47], off
	global_load_dwordx4 v[34:37], v[46:47], off offset:1024
	v_pk_add_f32 v[42:43], v[50:51], v[48:49]
	v_pk_add_f32 v[38:39], v[40:41], v[38:39]
	v_lshl_add_u64 v[40:41], v[68:69], 0, s[0:1]
	v_lshl_add_u64 v[46:47], v[70:71], 0, s[0:1]
	v_add_f32_e32 v113, v42, v43
	v_add_f32_e32 v114, v38, v39
	global_load_dwordx4 v[42:45], v[40:41], off
	s_nop 0
	global_load_dwordx4 v[38:41], v[40:41], off offset:1024
	s_nop 0
	global_load_dwordx4 v[50:53], v[46:47], off
	s_nop 0
	global_load_dwordx4 v[46:49], v[46:47], off offset:1024
	v_exp_f32_e32 v89, v89
	v_exp_f32_e32 v99, v99
	v_add_f32_dpp v113, v113, v113 quad_perm:[1,0,3,2] row_mask:0xf bank_mask:0xf bound_ctrl:1
	v_exp_f32_e32 v98, v98
	v_add_f32_e32 v106, 1.0, v106
	v_add_f32_e32 v89, 1.0, v89
	v_add_f32_dpp v114, v114, v114 quad_perm:[1,0,3,2] row_mask:0xf bank_mask:0xf bound_ctrl:1
	v_add_f32_dpp v122, v113, v113 quad_perm:[2,3,0,1] row_mask:0xf bank_mask:0xf bound_ctrl:1
	v_exp_f32_e32 v100, v100
	v_exp_f32_e32 v101, v101
	v_add_f32_e32 v116, 1.0, v99
	v_rcp_f32_e32 v99, v106
	v_rcp_f32_e32 v106, v89
	v_add_f32_dpp v89, v114, v114 quad_perm:[2,3,0,1] row_mask:0xf bank_mask:0xf bound_ctrl:1
	v_add_f32_dpp v114, v122, v122 row_half_mirror row_mask:0xf bank_mask:0xf bound_ctrl:1
	v_add_f32_e32 v107, 1.0, v107
	v_add_f32_dpp v89, v89, v89 row_half_mirror row_mask:0xf bank_mask:0xf bound_ctrl:1
	v_add_f32_dpp v114, v114, v114 row_mirror row_mask:0xf bank_mask:0xf bound_ctrl:1
	v_add_f32_e32 v108, 1.0, v108
	v_add_f32_dpp v89, v89, v89 row_mirror row_mask:0xf bank_mask:0xf bound_ctrl:1
	v_readlane_b32 s1, v114, 16
	v_readlane_b32 s9, v114, 48
	v_add_f32_e32 v115, 1.0, v98
	v_readlane_b32 s0, v114, 0
	v_readlane_b32 s8, v114, 32
	v_readlane_b32 s10, v89, 0
	v_readlane_b32 s11, v89, 16
	v_readlane_b32 s12, v89, 32
	v_readlane_b32 s13, v89, 48
	v_mov_b32_e32 v89, s1
	v_mov_b32_e32 v114, s9
	v_add_f32_e32 v117, 1.0, v100
	v_add_f32_e32 v118, 1.0, v101
	v_rcp_f32_e32 v100, v107
	v_rcp_f32_e32 v101, v108
	v_rcp_f32_e32 v107, v115
	v_rcp_f32_e32 v108, v116
	v_mov_b32_e32 v115, s11
	v_mov_b32_e32 v116, s13
	v_add_f32_e32 v89, s0, v89
	v_add_f32_e32 v114, s8, v114
	v_exp_f32_e32 v102, v102
	v_add_f32_e32 v115, s10, v115
	v_add_f32_e32 v116, s12, v116
	v_cndmask_b32_e64 v89, v89, v114, s[6:7]
	v_cndmask_b32_e64 v115, v115, v116, s[6:7]
	v_mul_f32_e32 v114, 0x3b800000, v89
	v_exp_f32_e32 v103, v103
	v_exp_f32_e32 v104, v104
	v_mul_f32_e32 v116, 0x3b800000, v115
	v_pk_add_f32 v[82:83], v[82:83], v[114:115] op_sel_hi:[1,0] neg_lo:[0,1] neg_hi:[0,1]
	v_add_f32_e32 v109, 1.0, v109
	v_pk_add_f32 v[80:81], v[80:81], v[114:115] op_sel_hi:[1,0] neg_lo:[0,1] neg_hi:[0,1]
	v_pk_add_f32 v[78:79], v[78:79], v[114:115] op_sel_hi:[1,0] neg_lo:[0,1] neg_hi:[0,1]
	v_pk_add_f32 v[76:77], v[76:77], v[114:115] op_sel_hi:[1,0] neg_lo:[0,1] neg_hi:[0,1]
	v_pk_add_f32 v[94:95], v[94:95], v[116:117] op_sel_hi:[1,0] neg_lo:[0,1] neg_hi:[0,1]
	v_pk_mul_f32 v[114:115], v[82:83], v[82:83]
	v_add_f32_e32 v119, 1.0, v102
	v_rcp_f32_e32 v102, v109
	v_rcp_f32_e32 v109, v117
	v_pk_add_f32 v[92:93], v[92:93], v[116:117] op_sel_hi:[1,0] neg_lo:[0,1] neg_hi:[0,1]
	v_pk_add_f32 v[90:91], v[90:91], v[116:117] op_sel_hi:[1,0] neg_lo:[0,1] neg_hi:[0,1]
	v_pk_add_f32 v[84:85], v[84:85], v[116:117] op_sel_hi:[1,0] neg_lo:[0,1] neg_hi:[0,1]
	v_pk_mul_f32 v[116:117], v[80:81], v[80:81]
	v_pk_mul_f32 v[122:123], v[94:95], v[94:95]
	v_add_f32_e32 v89, v114, v115
	v_add_f32_e32 v110, 1.0, v110
	v_add_f32_e32 v111, 1.0, v111
	v_pk_mul_f32 v[124:125], v[92:93], v[92:93]
	v_add_f32_e32 v114, v122, v123
	v_add_f32_e32 v89, v116, v89
	v_add_f32_e32 v120, 1.0, v103
	v_add_f32_e32 v121, 1.0, v104
	v_rcp_f32_e32 v103, v110
	v_rcp_f32_e32 v104, v111
	v_rcp_f32_e32 v110, v118
	v_rcp_f32_e32 v111, v119
	v_pk_mul_f32 v[118:119], v[78:79], v[78:79]
	v_add_f32_e32 v114, v124, v114
	v_add_f32_e32 v89, v117, v89
	v_add_f32_e32 v105, 1.0, v105
	v_add_f32_e32 v112, 1.0, v112
	v_pk_mul_f32 v[126:127], v[90:91], v[90:91]
	v_add_f32_e32 v114, v125, v114
	v_add_f32_e32 v89, v118, v89
	v_rcp_f32_e32 v98, v105
	v_rcp_f32_e32 v105, v112
	v_rcp_f32_e32 v112, v120
	v_rcp_f32_e32 v113, v121
	v_pk_mul_f32 v[120:121], v[76:77], v[76:77]
	v_add_f32_e32 v114, v126, v114
	v_add_f32_e32 v89, v119, v89
	v_pk_mul_f32 v[128:129], v[84:85], v[84:85]
	v_add_f32_e32 v114, v127, v114
	v_add_f32_e32 v89, v120, v89
	v_add_f32_e32 v114, v128, v114
	v_add_f32_e32 v89, v121, v89
	v_add_f32_e32 v114, v129, v114
	s_add_i32 s29, s29, 1
	v_add_f32_dpp v89, v89, v89 quad_perm:[1,0,3,2] row_mask:0xf bank_mask:0xf bound_ctrl:1
	v_add_f32_dpp v114, v114, v114 quad_perm:[1,0,3,2] row_mask:0xf bank_mask:0xf bound_ctrl:1
	s_add_i32 s14, s14, 8
	v_add_f32_dpp v89, v89, v89 quad_perm:[2,3,0,1] row_mask:0xf bank_mask:0xf bound_ctrl:1
	v_add_f32_dpp v114, v114, v114 quad_perm:[2,3,0,1] row_mask:0xf bank_mask:0xf bound_ctrl:1
	s_cmp_lg_u32 s29, 32
	v_add_f32_dpp v89, v89, v89 row_half_mirror row_mask:0xf bank_mask:0xf bound_ctrl:1
	v_add_f32_dpp v114, v114, v114 row_half_mirror row_mask:0xf bank_mask:0xf bound_ctrl:1
	s_nop 0
	v_add_f32_dpp v89, v89, v89 row_mirror row_mask:0xf bank_mask:0xf bound_ctrl:1
	v_add_f32_dpp v114, v114, v114 row_mirror row_mask:0xf bank_mask:0xf bound_ctrl:1
	v_readlane_b32 s1, v89, 16
	v_readlane_b32 s9, v89, 48
	v_readlane_b32 s0, v89, 0
	v_readlane_b32 s8, v89, 32
	v_readlane_b32 s10, v114, 0
	v_readlane_b32 s11, v114, 16
	v_readlane_b32 s12, v114, 32
	v_readlane_b32 s13, v114, 48
	v_mov_b32_e32 v89, s1
	v_mov_b32_e32 v114, s9
	v_mov_b32_e32 v115, s11
	v_mov_b32_e32 v116, s13
	v_add_f32_e32 v89, s0, v89
	v_add_f32_e32 v114, s8, v114
	v_add_f32_e32 v115, s10, v115
	v_add_f32_e32 v116, s12, v116
	v_cndmask_b32_e64 v89, v89, v114, s[6:7]
	v_cndmask_b32_e64 v114, v115, v116, s[6:7]
	v_fmamk_f32 v89, v89, 0x3b800000, v87
	v_fmamk_f32 v114, v114, 0x3b800000, v87
	v_mul_f32_e32 v115, 0x4f800000, v89
	v_cmp_gt_f32_e64 s[8:9], s26, v89
	v_mul_f32_e32 v116, 0x4f800000, v114
	v_cmp_gt_f32_e32 vcc, s26, v114
	v_cndmask_b32_e64 v89, v89, v115, s[8:9]
	v_sqrt_f32_e32 v115, v89
	v_cndmask_b32_e32 v114, v114, v116, vcc
	v_sqrt_f32_e32 v116, v114
	v_add_u32_e32 v117, -1, v115
	v_add_u32_e32 v118, 1, v115
	v_add_u32_e32 v119, -1, v116
	v_fma_f32 v121, -v117, v115, v89
	v_add_u32_e32 v120, 1, v116
	v_fma_f32 v122, -v118, v115, v89
	v_fma_f32 v123, -v119, v116, v114
	v_cmp_ge_f32_e64 s[10:11], 0, v121
	v_fma_f32 v124, -v120, v116, v114
	v_cmp_lt_f32_e64 s[12:13], 0, v122
	v_cndmask_b32_e64 v115, v115, v117, s[10:11]
	v_cmp_ge_f32_e64 s[10:11], 0, v123
	v_cndmask_b32_e64 v115, v115, v118, s[12:13]
	v_mul_f32_e32 v117, 0x37800000, v115
	v_cndmask_b32_e64 v116, v116, v119, s[10:11]
	v_cmp_lt_f32_e64 s[10:11], 0, v124
	v_cndmask_b32_e64 v115, v115, v117, s[8:9]
	v_cmp_class_f32_e64 s[8:9], v89, v88
	v_cndmask_b32_e64 v116, v116, v120, s[10:11]
	v_mul_f32_e32 v118, 0x37800000, v116
	v_cndmask_b32_e32 v116, v116, v118, vcc
	v_cmp_class_f32_e32 vcc, v114, v88
	v_cndmask_b32_e64 v89, v115, v89, s[8:9]
	s_nop 0
	v_cndmask_b32_e32 v115, v116, v114, vcc
	v_div_scale_f32 v114, s[0:1], v89, v89, 1.0
	v_div_scale_f32 v117, s[0:1], v115, v115, 1.0
	v_rcp_f32_e32 v119, v114
	v_rcp_f32_e32 v120, v117
	v_div_scale_f32 v116, vcc, 1.0, v89, 1.0
	v_fma_f32 v121, -v114, v119, 1.0
	v_fma_f32 v122, -v117, v120, 1.0
	v_fmac_f32_e32 v119, v121, v119
	v_div_scale_f32 v118, s[8:9], 1.0, v115, 1.0
	v_fmac_f32_e32 v120, v122, v120
	v_mul_f32_e32 v121, v116, v119
	v_mul_f32_e32 v122, v118, v120
	v_fma_f32 v123, -v114, v121, v116
	v_fma_f32 v124, -v117, v122, v118
	v_fmac_f32_e32 v121, v123, v119
	v_fmac_f32_e32 v122, v124, v120
	v_fma_f32 v114, -v114, v121, v116
	v_fma_f32 v116, -v117, v122, v118
	v_div_fmas_f32 v114, v114, v119, v121
	s_mov_b64 vcc, s[8:9]
	v_div_fixup_f32 v114, v114, v89, 1.0
	v_div_fmas_f32 v89, v116, v120, v122
	v_pk_mul_f32 v[82:83], v[82:83], v[114:115] op_sel_hi:[1,0]
	v_pk_mul_f32 v[80:81], v[80:81], v[114:115] op_sel_hi:[1,0]
	v_pk_mul_f32 v[78:79], v[78:79], v[114:115] op_sel_hi:[1,0]
	v_pk_mul_f32 v[76:77], v[76:77], v[114:115] op_sel_hi:[1,0]
	v_div_fixup_f32 v114, v89, v115, 1.0
	v_pk_mul_f32 v[82:83], v[2:3], v[82:83]
	v_pk_mul_f32 v[80:81], v[4:5], v[80:81]
	v_pk_mul_f32 v[78:79], v[6:7], v[78:79]
	v_pk_mul_f32 v[76:77], v[8:9], v[76:77]
	v_pk_mul_f32 v[94:95], v[94:95], v[114:115] op_sel_hi:[1,0]
	v_pk_mul_f32 v[92:93], v[92:93], v[114:115] op_sel_hi:[1,0]
	v_pk_mul_f32 v[90:91], v[90:91], v[114:115] op_sel_hi:[1,0]
	v_pk_mul_f32 v[84:85], v[84:85], v[114:115] op_sel_hi:[1,0]
	v_pk_mul_f32 v[82:83], v[98:99], v[82:83]
	v_pk_mul_f32 v[80:81], v[100:101], v[80:81]
	v_pk_mul_f32 v[78:79], v[102:103], v[78:79]
	v_pk_mul_f32 v[98:99], v[104:105], v[76:77]
	v_pk_mul_f32 v[94:95], v[10:11], v[94:95]
	v_pk_mul_f32 v[92:93], v[12:13], v[92:93]
	v_pk_mul_f32 v[90:91], v[14:15], v[90:91]
	v_pk_mul_f32 v[84:85], v[16:17], v[84:85]
	v_cvt_pk_bf16_f32 v76, v82, v83
	v_cvt_pk_bf16_f32 v77, v80, v81
	v_cvt_pk_bf16_f32 v78, v78, v79
	v_cvt_pk_bf16_f32 v79, v98, v99
	v_pk_mul_f32 v[80:81], v[106:107], v[94:95]
	v_pk_mul_f32 v[82:83], v[108:109], v[92:93]
	v_pk_mul_f32 v[90:91], v[110:111], v[90:91]
	v_pk_mul_f32 v[84:85], v[112:113], v[84:85]
	global_store_dwordx4 v[96:97], v[76:79], off nt
	s_nop 1
	v_cvt_pk_bf16_f32 v76, v80, v81
	v_cvt_pk_bf16_f32 v77, v82, v83
	v_cvt_pk_bf16_f32 v78, v90, v91
	v_cvt_pk_bf16_f32 v79, v84, v85
	global_store_dwordx4 v[96:97], v[76:79], off offset:1024 nt
	s_cbranch_scc1 .LBB0_427
	s_add_i32 s27, s27, s74
	s_add_i32 s4, s4, s5
	s_cmpk_gt_i32 s27, 0xff
	s_cbranch_scc0 .LBB0_426

.LBB0_434:
	ds_read_b128 v[146:149], v152
	ds_read_b128 v[156:159], v152 offset:1024
	ds_read_b128 v[160:163], v152 offset:2048
	ds_read_b128 v[164:167], v152 offset:3072
	s_add_u32 s0, s36, 0xfffc0080
	s_addc_u32 s1, s37, -1
	s_cmp_eq_u32 s69, 12
	s_cselect_b32 s41, s60, s1
	s_cselect_b32 s40, s61, s0
	s_cselect_b32 s39, s62, s67
	s_cselect_b32 s38, s63, s66
	s_mov_b32 m0, s50
	v_lshl_add_u64 v[200:201], s[36:37], 0, v[144:145]
	ds_read_b128 v[168:171], v153
	ds_read_b128 v[172:175], v153 offset:1024
	ds_read_b128 v[176:179], v153 offset:2048
	ds_read_b128 v[180:183], v153 offset:3072
	ds_read_b128 v[184:187], v153 offset:4096
	ds_read_b128 v[188:191], v153 offset:5120
	ds_read_b128 v[192:195], v153 offset:6144
	ds_read_b128 v[196:199], v153 offset:7168
	global_load_lds_dwordx4 v[200:201], off
	v_lshl_add_u64 v[200:201], s[36:37], 0, v[142:143]
	s_mov_b32 m0, s51
	s_nop 0
	global_load_lds_dwordx4 v[200:201], off
	s_waitcnt lgkmcnt(8)
	s_waitcnt vmcnt(10)
	s_barrier
	s_waitcnt lgkmcnt(0)
	s_waitcnt lgkmcnt(0)
	v_mfma_f32_16x16x32_bf16 v[126:129], v[146:149], v[168:171], v[126:129]
	v_mfma_f32_16x16x32_bf16 v[122:125], v[160:163], v[168:171], v[122:125]
	v_mfma_f32_16x16x32_bf16 v[114:117], v[146:149], v[176:179], v[114:117]
	v_mfma_f32_16x16x32_bf16 v[106:109], v[160:163], v[176:179], v[106:109]
	v_mfma_f32_16x16x32_bf16 v[98:101], v[146:149], v[184:187], v[98:101]
	v_mfma_f32_16x16x32_bf16 v[90:93], v[160:163], v[184:187], v[90:93]
	v_mfma_f32_16x16x32_bf16 v[82:85], v[146:149], v[192:195], v[82:85]
	v_mfma_f32_16x16x32_bf16 v[74:77], v[160:163], v[192:195], v[74:77]
	v_mfma_f32_16x16x32_bf16 v[126:129], v[156:159], v[172:175], v[126:129]
	v_mfma_f32_16x16x32_bf16 v[122:125], v[164:167], v[172:175], v[122:125]
	v_mfma_f32_16x16x32_bf16 v[114:117], v[156:159], v[180:183], v[114:117]
	v_mfma_f32_16x16x32_bf16 v[106:109], v[164:167], v[180:183], v[106:109]
	v_mfma_f32_16x16x32_bf16 v[98:101], v[156:159], v[188:191], v[98:101]
	v_mfma_f32_16x16x32_bf16 v[90:93], v[164:167], v[188:191], v[90:93]
	v_mfma_f32_16x16x32_bf16 v[82:85], v[156:159], v[196:199], v[82:85]
	v_mfma_f32_16x16x32_bf16 v[74:77], v[164:167], v[196:199], v[74:77]
	s_barrier
	s_mov_b32 m0, s52
	v_lshl_add_u64 v[216:217], s[38:39], 0, v[138:139]
	ds_read_b128 v[200:203], v154
	ds_read_b128 v[204:207], v154 offset:1024
	ds_read_b128 v[208:211], v154 offset:2048
	ds_read_b128 v[212:215], v154 offset:3072
	global_load_lds_dwordx4 v[216:217], off
	v_lshl_add_u64 v[218:219], s[38:39], 0, v[134:135]
	s_mov_b32 m0, s53
	s_nop 0
	global_load_lds_dwordx4 v[218:219], off
	s_waitcnt vmcnt(10)
	s_barrier
	s_waitcnt lgkmcnt(0)
	s_waitcnt lgkmcnt(0)
	v_mfma_f32_16x16x32_bf16 v[118:121], v[200:203], v[168:171], v[118:121]
	v_mfma_f32_16x16x32_bf16 v[110:113], v[208:211], v[168:171], v[110:113]
	v_mfma_f32_16x16x32_bf16 v[102:105], v[200:203], v[176:179], v[102:105]
	v_mfma_f32_16x16x32_bf16 v[94:97], v[208:211], v[176:179], v[94:97]
	v_mfma_f32_16x16x32_bf16 v[86:89], v[200:203], v[184:187], v[86:89]
	v_mfma_f32_16x16x32_bf16 v[78:81], v[208:211], v[184:187], v[78:81]
	v_mfma_f32_16x16x32_bf16 v[70:73], v[200:203], v[192:195], v[70:73]
	v_mfma_f32_16x16x32_bf16 v[66:69], v[208:211], v[192:195], v[66:69]
	v_mfma_f32_16x16x32_bf16 v[118:121], v[204:207], v[172:175], v[118:121]
	v_mfma_f32_16x16x32_bf16 v[110:113], v[212:215], v[172:175], v[110:113]
	v_mfma_f32_16x16x32_bf16 v[102:105], v[204:207], v[180:183], v[102:105]
	v_mfma_f32_16x16x32_bf16 v[94:97], v[212:215], v[180:183], v[94:97]
	v_mfma_f32_16x16x32_bf16 v[86:89], v[204:207], v[188:191], v[86:89]
	v_mfma_f32_16x16x32_bf16 v[78:81], v[212:215], v[188:191], v[78:81]
	v_mfma_f32_16x16x32_bf16 v[70:73], v[204:207], v[196:199], v[70:73]
	v_mfma_f32_16x16x32_bf16 v[66:69], v[212:215], v[196:199], v[66:69]
	s_mov_b32 m0, s6
	v_lshl_add_u64 v[220:221], s[40:41], 0, v[140:141]
	s_barrier
	ds_read_b128 v[168:171], v153 offset:16384
	ds_read_b128 v[172:175], v153 offset:17408
	ds_read_b128 v[176:179], v153 offset:18432
	ds_read_b128 v[180:183], v153 offset:19456
	ds_read_b128 v[184:187], v153 offset:20480
	ds_read_b128 v[188:191], v153 offset:21504
	ds_read_b128 v[192:195], v153 offset:22528
	ds_read_b128 v[196:199], v153 offset:23552
	global_load_lds_dwordx4 v[220:221], off
	v_lshl_add_u64 v[222:223], s[40:41], 0, v[136:137]
	s_mov_b32 m0, s7
	s_nop 0
	global_load_lds_dwordx4 v[222:223], off
	s_waitcnt vmcnt(10)
	s_barrier
	s_waitcnt lgkmcnt(0)
	s_waitcnt lgkmcnt(0)
	v_mfma_f32_16x16x32_bf16 v[62:65], v[146:149], v[168:171], v[62:65]
	v_mfma_f32_16x16x32_bf16 v[58:61], v[160:163], v[168:171], v[58:61]
	v_mfma_f32_16x16x32_bf16 v[50:53], v[146:149], v[176:179], v[50:53]
	v_mfma_f32_16x16x32_bf16 v[42:45], v[160:163], v[176:179], v[42:45]
	v_mfma_f32_16x16x32_bf16 v[34:37], v[146:149], v[184:187], v[34:37]
	v_mfma_f32_16x16x32_bf16 v[26:29], v[160:163], v[184:187], v[26:29]
	v_mfma_f32_16x16x32_bf16 v[18:21], v[146:149], v[192:195], v[18:21]
	v_mfma_f32_16x16x32_bf16 v[10:13], v[160:163], v[192:195], v[10:13]
	v_mfma_f32_16x16x32_bf16 v[62:65], v[156:159], v[172:175], v[62:65]
	v_mfma_f32_16x16x32_bf16 v[58:61], v[164:167], v[172:175], v[58:61]
	v_mfma_f32_16x16x32_bf16 v[50:53], v[156:159], v[180:183], v[50:53]
	v_mfma_f32_16x16x32_bf16 v[42:45], v[164:167], v[180:183], v[42:45]
	v_mfma_f32_16x16x32_bf16 v[34:37], v[156:159], v[188:191], v[34:37]
	v_mfma_f32_16x16x32_bf16 v[26:29], v[164:167], v[188:191], v[26:29]
	v_mfma_f32_16x16x32_bf16 v[18:21], v[156:159], v[196:199], v[18:21]
	v_mfma_f32_16x16x32_bf16 v[10:13], v[164:167], v[196:199], v[10:13]
	s_barrier
	s_add_u32 s0, s38, 0x40000
	s_addc_u32 s1, s39, 0
	s_mov_b32 m0, s54
	v_lshl_add_u64 v[146:147], s[0:1], 0, v[138:139]
	global_load_lds_dwordx4 v[146:147], off
	v_lshl_add_u64 v[146:147], s[0:1], 0, v[134:135]
	s_add_i32 m0, s54, 0x2000
	s_nop 0
	global_load_lds_dwordx4 v[146:147], off
	s_waitcnt vmcnt(10)
	s_barrier
	v_mfma_f32_16x16x32_bf16 v[54:57], v[200:203], v[168:171], v[54:57]
	v_mfma_f32_16x16x32_bf16 v[46:49], v[208:211], v[168:171], v[46:49]
	v_mfma_f32_16x16x32_bf16 v[38:41], v[200:203], v[176:179], v[38:41]
	v_mfma_f32_16x16x32_bf16 v[30:33], v[208:211], v[176:179], v[30:33]
	v_mfma_f32_16x16x32_bf16 v[22:25], v[200:203], v[184:187], v[22:25]
	v_mfma_f32_16x16x32_bf16 v[14:17], v[208:211], v[184:187], v[14:17]
	v_mfma_f32_16x16x32_bf16 v[6:9], v[200:203], v[192:195], v[6:9]
	v_mfma_f32_16x16x32_bf16 v[2:5], v[208:211], v[192:195], v[2:5]
	v_mfma_f32_16x16x32_bf16 v[54:57], v[204:207], v[172:175], v[54:57]
	v_mfma_f32_16x16x32_bf16 v[46:49], v[212:215], v[172:175], v[46:49]
	v_mfma_f32_16x16x32_bf16 v[38:41], v[204:207], v[180:183], v[38:41]
	v_mfma_f32_16x16x32_bf16 v[30:33], v[212:215], v[180:183], v[30:33]
	v_mfma_f32_16x16x32_bf16 v[22:25], v[204:207], v[188:191], v[22:25]
	v_mfma_f32_16x16x32_bf16 v[14:17], v[212:215], v[188:191], v[14:17]
	v_mfma_f32_16x16x32_bf16 v[6:9], v[204:207], v[196:199], v[6:9]
	v_mfma_f32_16x16x32_bf16 v[2:5], v[212:215], v[196:199], v[2:5]
	s_add_i32 s70, 0, 0x18000
	v_add_u32_e32 v155, s70, v151
	s_barrier
	ds_read_b128 v[146:149], v155
	ds_read_b128 v[156:159], v155 offset:1024
	ds_read_b128 v[160:163], v155 offset:2048
	ds_read_b128 v[164:167], v155 offset:3072
	s_add_u32 s0, s40, 0x40000
	s_addc_u32 s1, s41, 0
	s_mov_b32 m0, s29
	v_lshl_add_u64 v[200:201], s[0:1], 0, v[140:141]
	ds_read_b128 v[168:171], v153 offset:32768
	ds_read_b128 v[172:175], v153 offset:33792
	ds_read_b128 v[176:179], v153 offset:34816
	ds_read_b128 v[180:183], v153 offset:35840
	ds_read_b128 v[184:187], v153 offset:36864
	ds_read_b128 v[188:191], v153 offset:37888
	ds_read_b128 v[192:195], v153 offset:38912
	ds_read_b128 v[196:199], v153 offset:39936
	global_load_lds_dwordx4 v[200:201], off
	v_lshl_add_u64 v[200:201], s[0:1], 0, v[136:137]
	s_mov_b32 m0, s42
	s_nop 0
	global_load_lds_dwordx4 v[200:201], off
	s_waitcnt lgkmcnt(8)
	s_waitcnt vmcnt(10)
	s_barrier
	s_waitcnt lgkmcnt(0)
	s_waitcnt lgkmcnt(0)
	v_mfma_f32_16x16x32_bf16 v[126:129], v[146:149], v[168:171], v[126:129]
	v_mfma_f32_16x16x32_bf16 v[122:125], v[160:163], v[168:171], v[122:125]
	v_mfma_f32_16x16x32_bf16 v[114:117], v[146:149], v[176:179], v[114:117]
	v_mfma_f32_16x16x32_bf16 v[106:109], v[160:163], v[176:179], v[106:109]
	v_mfma_f32_16x16x32_bf16 v[98:101], v[146:149], v[184:187], v[98:101]
	v_mfma_f32_16x16x32_bf16 v[90:93], v[160:163], v[184:187], v[90:93]
	v_mfma_f32_16x16x32_bf16 v[82:85], v[146:149], v[192:195], v[82:85]
	v_mfma_f32_16x16x32_bf16 v[74:77], v[160:163], v[192:195], v[74:77]
	v_mfma_f32_16x16x32_bf16 v[126:129], v[156:159], v[172:175], v[126:129]
	v_mfma_f32_16x16x32_bf16 v[122:125], v[164:167], v[172:175], v[122:125]
	v_mfma_f32_16x16x32_bf16 v[114:117], v[156:159], v[180:183], v[114:117]
	v_mfma_f32_16x16x32_bf16 v[106:109], v[164:167], v[180:183], v[106:109]
	v_mfma_f32_16x16x32_bf16 v[98:101], v[156:159], v[188:191], v[98:101]
	v_mfma_f32_16x16x32_bf16 v[90:93], v[164:167], v[188:191], v[90:93]
	v_mfma_f32_16x16x32_bf16 v[82:85], v[156:159], v[196:199], v[82:85]
	v_mfma_f32_16x16x32_bf16 v[74:77], v[164:167], v[196:199], v[74:77]
	s_barrier
	s_add_i32 s40, 0, 0x1c000
	s_add_i32 s0, s70, s5
	v_add_u32_e32 v155, s40, v151
	v_lshl_add_u64 v[216:217], v[216:217], 0, s[26:27]
	s_mov_b32 m0, s0
	ds_read_b128 v[200:203], v155
	ds_read_b128 v[204:207], v155 offset:1024
	ds_read_b128 v[208:211], v155 offset:2048
	ds_read_b128 v[212:215], v155 offset:3072
	global_load_lds_dwordx4 v[216:217], off
	v_lshl_add_u64 v[216:217], v[218:219], 0, s[26:27]
	s_add_i32 m0, s0, 0x2000
	s_nop 0
	global_load_lds_dwordx4 v[216:217], off
	s_waitcnt vmcnt(10)
	s_barrier
	s_waitcnt lgkmcnt(0)
	s_waitcnt lgkmcnt(0)
	v_mfma_f32_16x16x32_bf16 v[118:121], v[200:203], v[168:171], v[118:121]
	v_mfma_f32_16x16x32_bf16 v[110:113], v[208:211], v[168:171], v[110:113]
	v_mfma_f32_16x16x32_bf16 v[102:105], v[200:203], v[176:179], v[102:105]
	v_mfma_f32_16x16x32_bf16 v[94:97], v[208:211], v[176:179], v[94:97]
	v_mfma_f32_16x16x32_bf16 v[86:89], v[200:203], v[184:187], v[86:89]
	v_mfma_f32_16x16x32_bf16 v[78:81], v[208:211], v[184:187], v[78:81]
	v_mfma_f32_16x16x32_bf16 v[70:73], v[200:203], v[192:195], v[70:73]
	v_mfma_f32_16x16x32_bf16 v[66:69], v[208:211], v[192:195], v[66:69]
	v_mfma_f32_16x16x32_bf16 v[118:121], v[204:207], v[172:175], v[118:121]
	v_mfma_f32_16x16x32_bf16 v[110:113], v[212:215], v[172:175], v[110:113]
	v_mfma_f32_16x16x32_bf16 v[102:105], v[204:207], v[180:183], v[102:105]
	v_mfma_f32_16x16x32_bf16 v[94:97], v[212:215], v[180:183], v[94:97]
	v_mfma_f32_16x16x32_bf16 v[86:89], v[204:207], v[188:191], v[86:89]
	v_mfma_f32_16x16x32_bf16 v[78:81], v[212:215], v[188:191], v[78:81]
	v_mfma_f32_16x16x32_bf16 v[70:73], v[204:207], v[196:199], v[70:73]
	v_mfma_f32_16x16x32_bf16 v[66:69], v[212:215], v[196:199], v[66:69]
	s_mov_b32 m0, s46
	v_lshl_add_u64 v[216:217], v[220:221], 0, s[26:27]
	s_barrier
	ds_read_b128 v[168:171], v153 offset:49152
	ds_read_b128 v[172:175], v153 offset:50176
	ds_read_b128 v[176:179], v153 offset:51200
	ds_read_b128 v[180:183], v153 offset:52224
	ds_read_b128 v[184:187], v153 offset:53248
	ds_read_b128 v[188:191], v153 offset:54272
	ds_read_b128 v[192:195], v153 offset:55296
	ds_read_b128 v[196:199], v153 offset:56320
	global_load_lds_dwordx4 v[216:217], off
	v_lshl_add_u64 v[216:217], v[222:223], 0, s[26:27]
	s_mov_b32 m0, s47
	s_nop 0
	global_load_lds_dwordx4 v[216:217], off
	s_waitcnt vmcnt(10)
	s_barrier
	s_waitcnt lgkmcnt(0)
	s_waitcnt lgkmcnt(0)
	v_mfma_f32_16x16x32_bf16 v[62:65], v[146:149], v[168:171], v[62:65]
	v_mfma_f32_16x16x32_bf16 v[58:61], v[160:163], v[168:171], v[58:61]
	v_mfma_f32_16x16x32_bf16 v[50:53], v[146:149], v[176:179], v[50:53]
	v_mfma_f32_16x16x32_bf16 v[42:45], v[160:163], v[176:179], v[42:45]
	v_mfma_f32_16x16x32_bf16 v[34:37], v[146:149], v[184:187], v[34:37]
	v_mfma_f32_16x16x32_bf16 v[26:29], v[160:163], v[184:187], v[26:29]
	v_mfma_f32_16x16x32_bf16 v[18:21], v[146:149], v[192:195], v[18:21]
	v_mfma_f32_16x16x32_bf16 v[10:13], v[160:163], v[192:195], v[10:13]
	v_mfma_f32_16x16x32_bf16 v[62:65], v[156:159], v[172:175], v[62:65]
	v_mfma_f32_16x16x32_bf16 v[58:61], v[164:167], v[172:175], v[58:61]
	v_mfma_f32_16x16x32_bf16 v[50:53], v[156:159], v[180:183], v[50:53]
	v_mfma_f32_16x16x32_bf16 v[42:45], v[164:167], v[180:183], v[42:45]
	v_mfma_f32_16x16x32_bf16 v[34:37], v[156:159], v[188:191], v[34:37]
	v_mfma_f32_16x16x32_bf16 v[26:29], v[164:167], v[188:191], v[26:29]
	v_mfma_f32_16x16x32_bf16 v[18:21], v[156:159], v[196:199], v[18:21]
	v_mfma_f32_16x16x32_bf16 v[10:13], v[164:167], v[196:199], v[10:13]
	s_barrier
	s_add_u32 s0, s38, 0x40080
	s_addc_u32 s1, s39, 0
	s_add_i32 s38, s40, s5
	v_lshl_add_u64 v[146:147], s[0:1], 0, v[138:139]
	s_mov_b32 m0, s38
	s_nop 0
	global_load_lds_dwordx4 v[146:147], off
	v_lshl_add_u64 v[146:147], s[0:1], 0, v[134:135]
	s_add_i32 m0, s38, 0x2000
	s_nop 0
	global_load_lds_dwordx4 v[146:147], off
	s_waitcnt vmcnt(10)
	s_barrier
	v_mfma_f32_16x16x32_bf16 v[54:57], v[200:203], v[168:171], v[54:57]
	v_mfma_f32_16x16x32_bf16 v[46:49], v[208:211], v[168:171], v[46:49]
	v_mfma_f32_16x16x32_bf16 v[38:41], v[200:203], v[176:179], v[38:41]
	v_mfma_f32_16x16x32_bf16 v[30:33], v[208:211], v[176:179], v[30:33]
	v_mfma_f32_16x16x32_bf16 v[22:25], v[200:203], v[184:187], v[22:25]
	v_mfma_f32_16x16x32_bf16 v[14:17], v[208:211], v[184:187], v[14:17]
	v_mfma_f32_16x16x32_bf16 v[6:9], v[200:203], v[192:195], v[6:9]
	v_mfma_f32_16x16x32_bf16 v[2:5], v[208:211], v[192:195], v[2:5]
	v_mfma_f32_16x16x32_bf16 v[54:57], v[204:207], v[172:175], v[54:57]
	v_mfma_f32_16x16x32_bf16 v[46:49], v[212:215], v[172:175], v[46:49]
	v_mfma_f32_16x16x32_bf16 v[38:41], v[204:207], v[180:183], v[38:41]
	v_mfma_f32_16x16x32_bf16 v[30:33], v[212:215], v[180:183], v[30:33]
	v_mfma_f32_16x16x32_bf16 v[22:25], v[204:207], v[188:191], v[22:25]
	v_mfma_f32_16x16x32_bf16 v[14:17], v[212:215], v[188:191], v[14:17]
	v_mfma_f32_16x16x32_bf16 v[6:9], v[204:207], v[196:199], v[6:9]
	v_mfma_f32_16x16x32_bf16 v[2:5], v[212:215], v[196:199], v[2:5]
	s_add_i32 s69, s69, 2
	s_add_u32 s66, s66, 0x100
	s_addc_u32 s67, s67, 0
	s_add_u32 s36, s36, 0x100
	s_addc_u32 s37, s37, 0
	s_cmp_gt_u32 s69, 13
	s_barrier
	s_cbranch_scc0 .LBB0_434
	v_mov_b32_e32 v147, v131
	v_mov_b32_e32 v146, v133
	s_lshl_b32 s0, s58, 8
	s_or_b32 s0, s0, s45
	v_lshl_add_u32 v146, v146, 3, s0
	s_lshl_b32 s0, s59, 8
	s_add_i32 s0, s0, s44
	v_add_u32_e32 v155, s0, v147
	v_mov_b32_e32 v148, v155
	v_ashrrev_i32_e32 v147, 31, v146
	v_ashrrev_i32_e32 v149, 31, v148
	v_lshlrev_b64 v[148:149], 10, v[148:149]
	v_lshl_add_u64 v[148:149], v[148:149], 0, v[146:147]
	v_lshlrev_b64 v[148:149], 1, v[148:149]
	v_lshl_add_u64 v[176:177], s[10:11], 0, v[148:149]
	global_load_dwordx4 v[156:159], v[176:177], off
	global_load_dwordx4 v[160:163], v[176:177], off offset:256
	v_add_co_u32_e32 v168, vcc, s49, v176
	v_lshl_add_u64 v[148:149], s[12:13], 0, v[148:149]
	s_nop 0
	v_addc_co_u32_e32 v169, vcc, 0, v177, vcc
	global_load_dwordx4 v[164:167], v[168:169], off
	s_nop 0
	global_load_dwordx4 v[168:171], v[168:169], off offset:256
	v_add_co_u32_e32 v178, vcc, s43, v176
	s_mov_b32 s58, s57
	s_nop 0
	v_addc_co_u32_e32 v179, vcc, 0, v177, vcc
	global_load_dwordx4 v[172:175], v[178:179], off
	v_add_co_u32_e32 v184, vcc, s48, v176
	s_mov_b32 s59, s56
	s_nop 0
	v_addc_co_u32_e32 v185, vcc, 0, v177, vcc
	global_load_dwordx4 v[176:179], v[178:179], off offset:256
	s_nop 0
	global_load_dwordx4 v[180:183], v[184:185], off
	s_nop 0
	global_load_dwordx4 v[184:187], v[184:185], off offset:256
	v_add_co_u32_e32 v188, vcc, s49, v148
	s_waitcnt vmcnt(0) lgkmcnt(0)
	v_lshlrev_b32_e32 v190, 16, v156
	v_and_b32_e32 v191, 0xffff0000, v156
	v_lshlrev_b32_e32 v156, 16, v157
	v_and_b32_e32 v157, 0xffff0000, v157
	v_lshlrev_b32_e32 v192, 16, v158
	v_and_b32_e32 v193, 0xffff0000, v158
	v_lshlrev_b32_e32 v194, 16, v160
	v_and_b32_e32 v195, 0xffff0000, v160
	v_lshlrev_b32_e32 v160, 16, v161
	v_and_b32_e32 v161, 0xffff0000, v161
	v_lshlrev_b32_e32 v196, 16, v162
	v_and_b32_e32 v197, 0xffff0000, v162
	v_lshlrev_b32_e32 v162, 16, v163
	v_and_b32_e32 v163, 0xffff0000, v163
	v_lshlrev_b32_e32 v158, 16, v159
	v_and_b32_e32 v159, 0xffff0000, v159
	v_pk_fma_f32 v[128:129], v[156:157], s[28:29], v[128:129] op_sel_hi:[1,0,1]
	v_pk_fma_f32 v[122:123], v[192:193], s[28:29], v[122:123] op_sel_hi:[1,0,1]
	v_pk_fma_f32 v[120:121], v[160:161], s[28:29], v[120:121] op_sel_hi:[1,0,1]
	v_pk_fma_f32 v[156:157], v[162:163], s[28:29], v[112:113] op_sel_hi:[1,0,1]
	v_lshlrev_b32_e32 v160, 16, v164
	v_and_b32_e32 v161, 0xffff0000, v164
	v_lshlrev_b32_e32 v162, 16, v165
	v_and_b32_e32 v163, 0xffff0000, v165
	v_lshlrev_b32_e32 v164, 16, v166
	v_and_b32_e32 v165, 0xffff0000, v166
	v_lshlrev_b32_e32 v166, 16, v167
	v_and_b32_e32 v167, 0xffff0000, v167
	v_pk_fma_f32 v[126:127], v[190:191], s[28:29], v[126:127] op_sel_hi:[1,0,1]
	v_pk_fma_f32 v[124:125], v[158:159], s[28:29], v[124:125] op_sel_hi:[1,0,1]
	v_cvt_pk_bf16_f32 v112, v122, v123
	v_pk_fma_f32 v[116:117], v[162:163], s[28:29], v[116:117] op_sel_hi:[1,0,1]
	v_pk_fma_f32 v[114:115], v[160:161], s[28:29], v[114:115] op_sel_hi:[1,0,1]
	v_pk_fma_f32 v[122:123], v[166:167], s[28:29], v[108:109] op_sel_hi:[1,0,1]
	v_pk_fma_f32 v[108:109], v[164:165], s[28:29], v[106:107] op_sel_hi:[1,0,1]
	v_addc_co_u32_e32 v189, vcc, 0, v149, vcc
	v_pk_fma_f32 v[118:119], v[194:195], s[28:29], v[118:119] op_sel_hi:[1,0,1]
	v_pk_fma_f32 v[158:159], v[196:197], s[28:29], v[110:111] op_sel_hi:[1,0,1]
	v_cvt_pk_bf16_f32 v110, v126, v127
	v_cvt_pk_bf16_f32 v111, v128, v129
	v_cvt_pk_bf16_f32 v113, v124, v125
	v_cvt_pk_bf16_f32 v106, v114, v115
	v_cvt_pk_bf16_f32 v107, v116, v117
	v_cvt_pk_bf16_f32 v108, v108, v109
	v_cvt_pk_bf16_f32 v109, v122, v123
	v_lshlrev_b32_e32 v190, 16, v168
	v_cvt_pk_bf16_f32 v118, v118, v119
	v_cvt_pk_bf16_f32 v119, v120, v121
	v_cvt_pk_bf16_f32 v120, v158, v159
	v_cvt_pk_bf16_f32 v121, v156, v157
	global_store_dwordx4 v[148:149], v[110:113], off nt
	global_store_dwordx4 v[148:149], v[118:121], off offset:256 nt
	global_store_dwordx4 v[188:189], v[106:109], off nt
	v_and_b32_e32 v191, 0xffff0000, v168
	v_lshlrev_b32_e32 v110, 16, v171
	v_lshlrev_b32_e32 v106, 16, v169
	v_and_b32_e32 v107, 0xffff0000, v169
	v_lshlrev_b32_e32 v108, 16, v170
	v_and_b32_e32 v109, 0xffff0000, v170
	v_and_b32_e32 v111, 0xffff0000, v171
	v_pk_fma_f32 v[104:105], v[106:107], s[28:29], v[104:105] op_sel_hi:[1,0,1]
	v_pk_fma_f32 v[102:103], v[190:191], s[28:29], v[102:103] op_sel_hi:[1,0,1]
	v_pk_fma_f32 v[106:107], v[110:111], s[28:29], v[96:97] op_sel_hi:[1,0,1]
	v_pk_fma_f32 v[96:97], v[108:109], s[28:29], v[94:95] op_sel_hi:[1,0,1]
	v_cvt_pk_bf16_f32 v94, v102, v103
	v_cvt_pk_bf16_f32 v95, v104, v105
	v_cvt_pk_bf16_f32 v96, v96, v97
	v_cvt_pk_bf16_f32 v97, v106, v107
	global_store_dwordx4 v[188:189], v[94:97], off offset:256 nt
	v_lshlrev_b32_e32 v102, 16, v174
	v_and_b32_e32 v103, 0xffff0000, v174
	v_lshlrev_b32_e32 v94, 16, v172
	v_and_b32_e32 v95, 0xffff0000, v172
	v_lshlrev_b32_e32 v96, 16, v173
	v_and_b32_e32 v97, 0xffff0000, v173
	v_lshlrev_b32_e32 v104, 16, v175
	v_and_b32_e32 v105, 0xffff0000, v175
	v_pk_fma_f32 v[94:95], v[94:95], s[28:29], v[98:99] op_sel_hi:[1,0,1]
	v_pk_fma_f32 v[96:97], v[96:97], s[28:29], v[100:101] op_sel_hi:[1,0,1]
	v_pk_fma_f32 v[98:99], v[104:105], s[28:29], v[92:93] op_sel_hi:[1,0,1]
	v_pk_fma_f32 v[92:93], v[102:103], s[28:29], v[90:91] op_sel_hi:[1,0,1]
	v_cvt_pk_bf16_f32 v90, v94, v95
	v_add_co_u32_e32 v94, vcc, s43, v148
	v_cvt_pk_bf16_f32 v91, v96, v97
	v_cvt_pk_bf16_f32 v92, v92, v93
	v_cvt_pk_bf16_f32 v93, v98, v99
	v_addc_co_u32_e32 v95, vcc, 0, v149, vcc
	global_store_dwordx4 v[94:95], v[90:93], off nt
	v_lshlrev_b32_e32 v96, 16, v178
	v_and_b32_e32 v97, 0xffff0000, v178
	v_lshlrev_b32_e32 v90, 16, v176
	v_and_b32_e32 v91, 0xffff0000, v176
	v_lshlrev_b32_e32 v92, 16, v177
	v_and_b32_e32 v93, 0xffff0000, v177
	v_lshlrev_b32_e32 v98, 16, v179
	v_and_b32_e32 v99, 0xffff0000, v179
	v_pk_fma_f32 v[88:89], v[92:93], s[28:29], v[88:89] op_sel_hi:[1,0,1]
	v_pk_fma_f32 v[86:87], v[90:91], s[28:29], v[86:87] op_sel_hi:[1,0,1]
	v_pk_fma_f32 v[90:91], v[98:99], s[28:29], v[80:81] op_sel_hi:[1,0,1]
	v_pk_fma_f32 v[80:81], v[96:97], s[28:29], v[78:79] op_sel_hi:[1,0,1]
	v_cvt_pk_bf16_f32 v78, v86, v87
	v_cvt_pk_bf16_f32 v79, v88, v89
	v_cvt_pk_bf16_f32 v80, v80, v81
	v_cvt_pk_bf16_f32 v81, v90, v91
	global_store_dwordx4 v[94:95], v[78:81], off offset:256 nt
	v_lshlrev_b32_e32 v86, 16, v182
	v_and_b32_e32 v87, 0xffff0000, v182
	v_lshlrev_b32_e32 v78, 16, v180
	v_and_b32_e32 v79, 0xffff0000, v180
	v_lshlrev_b32_e32 v80, 16, v181
	v_and_b32_e32 v81, 0xffff0000, v181
	v_lshlrev_b32_e32 v88, 16, v183
	v_and_b32_e32 v89, 0xffff0000, v183
	v_pk_fma_f32 v[78:79], v[78:79], s[28:29], v[82:83] op_sel_hi:[1,0,1]
	v_pk_fma_f32 v[80:81], v[80:81], s[28:29], v[84:85] op_sel_hi:[1,0,1]
	v_pk_fma_f32 v[82:83], v[88:89], s[28:29], v[76:77] op_sel_hi:[1,0,1]
	v_pk_fma_f32 v[76:77], v[86:87], s[28:29], v[74:75] op_sel_hi:[1,0,1]
	v_cvt_pk_bf16_f32 v74, v78, v79
	v_add_co_u32_e32 v78, vcc, s48, v148
	v_cvt_pk_bf16_f32 v75, v80, v81
	v_cvt_pk_bf16_f32 v76, v76, v77
	v_cvt_pk_bf16_f32 v77, v82, v83
	v_addc_co_u32_e32 v79, vcc, 0, v149, vcc
	global_store_dwordx4 v[78:79], v[74:77], off nt
	v_lshlrev_b32_e32 v80, 16, v186
	v_and_b32_e32 v81, 0xffff0000, v186
	v_lshlrev_b32_e32 v74, 16, v184
	v_and_b32_e32 v75, 0xffff0000, v184
	v_lshlrev_b32_e32 v76, 16, v185
	v_and_b32_e32 v77, 0xffff0000, v185
	v_lshlrev_b32_e32 v82, 16, v187
	v_and_b32_e32 v83, 0xffff0000, v187
	v_pk_fma_f32 v[72:73], v[76:77], s[28:29], v[72:73] op_sel_hi:[1,0,1]
	v_pk_fma_f32 v[70:71], v[74:75], s[28:29], v[70:71] op_sel_hi:[1,0,1]
	v_pk_fma_f32 v[74:75], v[82:83], s[28:29], v[68:69] op_sel_hi:[1,0,1]
	v_pk_fma_f32 v[68:69], v[80:81], s[28:29], v[66:67] op_sel_hi:[1,0,1]
	v_cvt_pk_bf16_f32 v66, v70, v71
	v_cvt_pk_bf16_f32 v67, v72, v73
	v_cvt_pk_bf16_f32 v68, v68, v69
	v_cvt_pk_bf16_f32 v69, v74, v75
	global_store_dwordx4 v[78:79], v[66:69], off offset:256 nt
	s_nop 1
	v_add_u32_e32 v66, 0x80, v155
	s_nop 0
	v_ashrrev_i32_e32 v67, 31, v66
	v_lshlrev_b64 v[66:67], 10, v[66:67]
	v_lshl_add_u64 v[66:67], v[66:67], 0, v[146:147]
	v_lshlrev_b64 v[98:99], 1, v[66:67]
	v_lshl_add_u64 v[90:91], s[10:11], 0, v[98:99]
	global_load_dwordx4 v[66:69], v[90:91], off
	global_load_dwordx4 v[70:73], v[90:91], off offset:256
	v_add_co_u32_e32 v78, vcc, s49, v90
	s_waitcnt vmcnt(0) lgkmcnt(0)
	v_lshlrev_b32_e32 v100, 16, v66
	v_addc_co_u32_e32 v79, vcc, 0, v91, vcc
	global_load_dwordx4 v[74:77], v[78:79], off
	s_nop 0
	global_load_dwordx4 v[78:81], v[78:79], off offset:256
	v_add_co_u32_e32 v86, vcc, s43, v90
	v_and_b32_e32 v101, 0xffff0000, v66
	s_nop 0
	v_addc_co_u32_e32 v87, vcc, 0, v91, vcc
	global_load_dwordx4 v[82:85], v[86:87], off
	s_nop 0
	global_load_dwordx4 v[86:89], v[86:87], off offset:256
	v_add_co_u32_e32 v94, vcc, s48, v90
	v_lshlrev_b32_e32 v66, 16, v67
	s_nop 0
	v_addc_co_u32_e32 v95, vcc, 0, v91, vcc
	global_load_dwordx4 v[90:93], v[94:95], off
	s_nop 0
	global_load_dwordx4 v[94:97], v[94:95], off offset:256
	v_and_b32_e32 v67, 0xffff0000, v67
	v_lshlrev_b32_e32 v102, 16, v68
	v_and_b32_e32 v103, 0xffff0000, v68
	v_lshlrev_b32_e32 v68, 16, v69
	v_and_b32_e32 v69, 0xffff0000, v69
	v_pk_fma_f32 v[64:65], v[66:67], s[28:29], v[64:65] op_sel_hi:[1,0,1]
	v_pk_fma_f32 v[62:63], v[100:101], s[28:29], v[62:63] op_sel_hi:[1,0,1]
	v_pk_fma_f32 v[66:67], v[68:69], s[28:29], v[60:61] op_sel_hi:[1,0,1]
	v_pk_fma_f32 v[60:61], v[102:103], s[28:29], v[58:59] op_sel_hi:[1,0,1]
	v_cvt_pk_bf16_f32 v58, v62, v63
	v_cvt_pk_bf16_f32 v59, v64, v65
	v_cvt_pk_bf16_f32 v60, v60, v61
	v_cvt_pk_bf16_f32 v61, v66, v67
	v_lshl_add_u64 v[62:63], s[12:13], 0, v[98:99]
	global_store_dwordx4 v[62:63], v[58:61], off nt
	v_lshlrev_b32_e32 v64, 16, v72
	v_and_b32_e32 v65, 0xffff0000, v72
	v_lshlrev_b32_e32 v58, 16, v70
	v_and_b32_e32 v59, 0xffff0000, v70
	v_lshlrev_b32_e32 v60, 16, v71
	v_and_b32_e32 v61, 0xffff0000, v71
	v_lshlrev_b32_e32 v66, 16, v73
	v_and_b32_e32 v67, 0xffff0000, v73
	v_pk_fma_f32 v[56:57], v[60:61], s[28:29], v[56:57] op_sel_hi:[1,0,1]
	v_pk_fma_f32 v[54:55], v[58:59], s[28:29], v[54:55] op_sel_hi:[1,0,1]
	v_pk_fma_f32 v[58:59], v[66:67], s[28:29], v[48:49] op_sel_hi:[1,0,1]
	v_pk_fma_f32 v[48:49], v[64:65], s[28:29], v[46:47] op_sel_hi:[1,0,1]
	v_cvt_pk_bf16_f32 v46, v54, v55
	v_cvt_pk_bf16_f32 v47, v56, v57
	v_cvt_pk_bf16_f32 v48, v48, v49
	v_cvt_pk_bf16_f32 v49, v58, v59
	global_store_dwordx4 v[62:63], v[46:49], off offset:256 nt
	s_waitcnt vmcnt(0) lgkmcnt(0)
	v_lshlrev_b32_e32 v54, 16, v76
	v_lshlrev_b32_e32 v46, 16, v74
	v_and_b32_e32 v47, 0xffff0000, v74
	v_lshlrev_b32_e32 v48, 16, v75
	v_and_b32_e32 v49, 0xffff0000, v75
	v_and_b32_e32 v55, 0xffff0000, v76
	v_lshlrev_b32_e32 v56, 16, v77
	v_and_b32_e32 v57, 0xffff0000, v77
	v_pk_fma_f32 v[46:47], v[46:47], s[28:29], v[50:51] op_sel_hi:[1,0,1]
	v_pk_fma_f32 v[48:49], v[48:49], s[28:29], v[52:53] op_sel_hi:[1,0,1]
	v_pk_fma_f32 v[50:51], v[56:57], s[28:29], v[44:45] op_sel_hi:[1,0,1]
	v_pk_fma_f32 v[44:45], v[54:55], s[28:29], v[42:43] op_sel_hi:[1,0,1]
	v_cvt_pk_bf16_f32 v42, v46, v47
	v_add_co_u32_e32 v46, vcc, s49, v62
	v_cvt_pk_bf16_f32 v43, v48, v49
	v_cvt_pk_bf16_f32 v44, v44, v45
	v_cvt_pk_bf16_f32 v45, v50, v51
	v_addc_co_u32_e32 v47, vcc, 0, v63, vcc
	global_store_dwordx4 v[46:47], v[42:45], off nt
	v_lshlrev_b32_e32 v48, 16, v80
	v_and_b32_e32 v49, 0xffff0000, v80
	v_lshlrev_b32_e32 v42, 16, v78
	v_and_b32_e32 v43, 0xffff0000, v78
	v_lshlrev_b32_e32 v44, 16, v79
	v_and_b32_e32 v45, 0xffff0000, v79
	v_lshlrev_b32_e32 v50, 16, v81
	v_and_b32_e32 v51, 0xffff0000, v81
	v_pk_fma_f32 v[40:41], v[44:45], s[28:29], v[40:41] op_sel_hi:[1,0,1]
	v_pk_fma_f32 v[38:39], v[42:43], s[28:29], v[38:39] op_sel_hi:[1,0,1]
	v_pk_fma_f32 v[42:43], v[50:51], s[28:29], v[32:33] op_sel_hi:[1,0,1]
	v_pk_fma_f32 v[32:33], v[48:49], s[28:29], v[30:31] op_sel_hi:[1,0,1]
	v_cvt_pk_bf16_f32 v30, v38, v39
	v_cvt_pk_bf16_f32 v31, v40, v41
	v_cvt_pk_bf16_f32 v32, v32, v33
	v_cvt_pk_bf16_f32 v33, v42, v43
	global_store_dwordx4 v[46:47], v[30:33], off offset:256 nt
	v_lshlrev_b32_e32 v38, 16, v84
	v_and_b32_e32 v39, 0xffff0000, v84
	v_lshlrev_b32_e32 v30, 16, v82
	v_and_b32_e32 v31, 0xffff0000, v82
	v_lshlrev_b32_e32 v32, 16, v83
	v_and_b32_e32 v33, 0xffff0000, v83
	v_lshlrev_b32_e32 v40, 16, v85
	v_and_b32_e32 v41, 0xffff0000, v85
	v_pk_fma_f32 v[30:31], v[30:31], s[28:29], v[34:35] op_sel_hi:[1,0,1]
	v_pk_fma_f32 v[32:33], v[32:33], s[28:29], v[36:37] op_sel_hi:[1,0,1]
	v_pk_fma_f32 v[34:35], v[40:41], s[28:29], v[28:29] op_sel_hi:[1,0,1]
	v_pk_fma_f32 v[28:29], v[38:39], s[28:29], v[26:27] op_sel_hi:[1,0,1]
	v_cvt_pk_bf16_f32 v26, v30, v31
	v_add_co_u32_e32 v30, vcc, s43, v62
	v_cvt_pk_bf16_f32 v27, v32, v33
	v_cvt_pk_bf16_f32 v28, v28, v29
	v_cvt_pk_bf16_f32 v29, v34, v35
	v_addc_co_u32_e32 v31, vcc, 0, v63, vcc
	global_store_dwordx4 v[30:31], v[26:29], off nt
	v_lshlrev_b32_e32 v32, 16, v88
	v_and_b32_e32 v33, 0xffff0000, v88
	v_lshlrev_b32_e32 v26, 16, v86
	v_and_b32_e32 v27, 0xffff0000, v86
	v_lshlrev_b32_e32 v28, 16, v87
	v_and_b32_e32 v29, 0xffff0000, v87
	v_lshlrev_b32_e32 v34, 16, v89
	v_and_b32_e32 v35, 0xffff0000, v89
	v_pk_fma_f32 v[24:25], v[28:29], s[28:29], v[24:25] op_sel_hi:[1,0,1]
	v_pk_fma_f32 v[22:23], v[26:27], s[28:29], v[22:23] op_sel_hi:[1,0,1]
	v_pk_fma_f32 v[26:27], v[34:35], s[28:29], v[16:17] op_sel_hi:[1,0,1]
	v_pk_fma_f32 v[16:17], v[32:33], s[28:29], v[14:15] op_sel_hi:[1,0,1]
	v_cvt_pk_bf16_f32 v14, v22, v23
	v_cvt_pk_bf16_f32 v15, v24, v25
	v_cvt_pk_bf16_f32 v16, v16, v17
	v_cvt_pk_bf16_f32 v17, v26, v27
	global_store_dwordx4 v[30:31], v[14:17], off offset:256 nt
	v_lshlrev_b32_e32 v22, 16, v92
	v_and_b32_e32 v23, 0xffff0000, v92
	v_lshlrev_b32_e32 v14, 16, v90
	v_and_b32_e32 v15, 0xffff0000, v90
	v_lshlrev_b32_e32 v16, 16, v91
	v_and_b32_e32 v17, 0xffff0000, v91
	v_lshlrev_b32_e32 v24, 16, v93
	v_and_b32_e32 v25, 0xffff0000, v93
	v_pk_fma_f32 v[14:15], v[14:15], s[28:29], v[18:19] op_sel_hi:[1,0,1]
	v_pk_fma_f32 v[16:17], v[16:17], s[28:29], v[20:21] op_sel_hi:[1,0,1]
	v_pk_fma_f32 v[18:19], v[24:25], s[28:29], v[12:13] op_sel_hi:[1,0,1]
	v_pk_fma_f32 v[12:13], v[22:23], s[28:29], v[10:11] op_sel_hi:[1,0,1]
	v_cvt_pk_bf16_f32 v10, v14, v15
	v_add_co_u32_e32 v14, vcc, s48, v62
	v_cvt_pk_bf16_f32 v11, v16, v17
	v_cvt_pk_bf16_f32 v12, v12, v13
	v_cvt_pk_bf16_f32 v13, v18, v19
	v_addc_co_u32_e32 v15, vcc, 0, v63, vcc
	global_store_dwordx4 v[14:15], v[10:13], off nt
	v_lshlrev_b32_e32 v16, 16, v96
	v_and_b32_e32 v17, 0xffff0000, v96
	v_lshlrev_b32_e32 v10, 16, v94
	v_and_b32_e32 v11, 0xffff0000, v94
	v_lshlrev_b32_e32 v12, 16, v95
	v_and_b32_e32 v13, 0xffff0000, v95
	v_lshlrev_b32_e32 v18, 16, v97
	v_and_b32_e32 v19, 0xffff0000, v97
	v_pk_fma_f32 v[8:9], v[12:13], s[28:29], v[8:9] op_sel_hi:[1,0,1]
	v_pk_fma_f32 v[6:7], v[10:11], s[28:29], v[6:7] op_sel_hi:[1,0,1]
	v_pk_fma_f32 v[10:11], v[18:19], s[28:29], v[4:5] op_sel_hi:[1,0,1]
	v_pk_fma_f32 v[4:5], v[16:17], s[28:29], v[2:3] op_sel_hi:[1,0,1]
	v_cvt_pk_bf16_f32 v2, v6, v7
	v_cvt_pk_bf16_f32 v3, v8, v9
	v_cvt_pk_bf16_f32 v4, v4, v5
	v_cvt_pk_bf16_f32 v5, v10, v11
	s_and_b64 vcc, exec, s[30:31]
	global_store_dwordx4 v[14:15], v[2:5], off offset:256 nt
	s_cbranch_vccz .LBB0_433
	s_waitcnt vmcnt(0)
	s_cmpk_gt_u32 s4, 0xff
	s_cbranch_scc1 .LBB0_438
	s_barrier

.LBB0_1040:
	s_waitcnt vmcnt(0) lgkmcnt(0)
	v_lshlrev_b32_e32 v100, 16, v89
	v_and_b32_e32 v101, 0xffff0000, v89
	v_lshlrev_b32_e32 v106, 16, v85
	v_and_b32_e32 v107, 0xffff0000, v85
	v_pk_add_f32 v[106:107], v[106:107], v[100:101]
	v_lshlrev_b32_e32 v100, 16, v81
	v_and_b32_e32 v101, 0xffff0000, v81
	v_mul_f32_e32 v81, 0xbfb8aa3b, v100
	v_exp_f32_e32 v81, v81
	v_and_b32_e32 v89, 0xffff0000, v84
	s_min_u32 s0, s11, 29
	s_lshl_b32 s0, s0, 3
	v_add_f32_e32 v81, 1.0, v81
	v_rcp_f32_e32 v108, v81
	v_mul_f32_e32 v81, 0xbfb8aa3b, v101
	v_exp_f32_e32 v81, v81
	s_add_i32 s0, s10, s0
	s_ashr_i32 s1, s0, 31
	s_lshl_b64 s[12:13], s[0:1], 11
	v_add_f32_e32 v81, 1.0, v81
	v_rcp_f32_e32 v109, v81
	v_mad_i64_i32 v[74:75], s[0:1], s0, v102, v[96:97]
	v_mov_b64_e32 v[64:65], v[40:41]
	v_pk_mul_f32 v[100:101], v[108:109], v[100:101]
	v_lshlrev_b32_e32 v108, 16, v88
	v_and_b32_e32 v109, 0xffff0000, v88
	v_lshlrev_b32_e32 v88, 16, v84
	v_pk_add_f32 v[84:85], v[88:89], v[108:109]
	v_lshlrev_b32_e32 v88, 16, v80
	v_and_b32_e32 v89, 0xffff0000, v80
	v_mul_f32_e32 v80, 0xbfb8aa3b, v88
	v_mul_f32_e32 v81, 0xbfb8aa3b, v89
	v_exp_f32_e32 v80, v80
	v_exp_f32_e32 v81, v81
	v_lshlrev_b32_e32 v108, 16, v83
	v_and_b32_e32 v109, 0xffff0000, v83
	v_add_f32_e32 v80, 1.0, v80
	v_add_f32_e32 v81, 1.0, v81
	v_rcp_f32_e32 v80, v80
	v_rcp_f32_e32 v81, v81
	v_mov_b32_e32 v113, v85
	v_mov_b64_e32 v[56:57], v[32:33]
	v_mov_b64_e32 v[62:63], v[38:39]
	v_pk_mul_f32 v[80:81], v[80:81], v[88:89]
	v_lshlrev_b32_e32 v88, 16, v87
	v_and_b32_e32 v89, 0xffff0000, v87
	v_pk_add_f32 v[88:89], v[108:109], v[88:89]
	v_lshlrev_b32_e32 v108, 16, v79
	v_and_b32_e32 v109, 0xffff0000, v79
	v_mul_f32_e32 v79, 0xbfb8aa3b, v108
	v_exp_f32_e32 v79, v79
	v_and_b32_e32 v87, 0xffff0000, v82
	v_mov_b64_e32 v[54:55], v[30:31]
	v_lshl_add_u64 v[30:31], v[92:93], 0, s[12:13]
	v_add_f32_e32 v79, 1.0, v79
	v_rcp_f32_e32 v110, v79
	v_mul_f32_e32 v79, 0xbfb8aa3b, v109
	v_exp_f32_e32 v79, v79
	v_lshl_add_u64 v[38:39], v[94:95], 0, s[12:13]
	s_ashr_i32 s25, s24, 31
	s_lshl_b64 s[26:27], s[24:25], 11
	v_add_f32_e32 v79, 1.0, v79
	v_rcp_f32_e32 v111, v79
	v_mov_b64_e32 v[68:69], v[36:37]
	v_mov_b64_e32 v[60:61], v[28:29]
	v_mov_b64_e32 v[66:67], v[34:35]
	v_pk_mul_f32 v[108:109], v[110:111], v[108:109]
	v_lshlrev_b32_e32 v110, 16, v86
	v_and_b32_e32 v111, 0xffff0000, v86
	v_lshlrev_b32_e32 v86, 16, v82
	v_pk_add_f32 v[82:83], v[86:87], v[110:111]
	v_lshlrev_b32_e32 v86, 16, v78
	v_and_b32_e32 v87, 0xffff0000, v78
	v_mul_f32_e32 v78, 0xbfb8aa3b, v86
	v_mul_f32_e32 v79, 0xbfb8aa3b, v87
	v_exp_f32_e32 v78, v78
	v_exp_f32_e32 v79, v79
	v_mov_b32_e32 v110, v89
	v_mov_b32_e32 v111, v107
	v_add_f32_e32 v78, 1.0, v78
	v_add_f32_e32 v79, 1.0, v79
	v_rcp_f32_e32 v78, v78
	v_rcp_f32_e32 v79, v79
	v_mov_b32_e32 v112, v83
	v_mov_b64_e32 v[58:59], v[26:27]
	global_load_dwordx4 v[26:29], v[30:31], off
	global_load_dwordx4 v[34:37], v[38:39], off
	v_pk_mul_f32 v[78:79], v[78:79], v[86:87]
	v_mov_b32_e32 v86, v88
	v_mov_b32_e32 v87, v106
	v_pk_add_f32 v[86:87], v[86:87], v[110:111]
	v_mov_b32_e32 v110, v82
	v_mov_b32_e32 v111, v84
	v_pk_add_f32 v[110:111], v[110:111], v[112:113]
	global_load_dwordx4 v[70:73], v[74:75], off
	s_nop 0
	global_load_dwordx4 v[30:33], v[30:31], off offset:1024
	s_nop 0
	global_load_dwordx4 v[38:41], v[38:39], off offset:1024
	s_nop 0
	global_load_dwordx4 v[74:77], v[74:75], off offset:1024
	v_pk_add_f32 v[86:87], v[110:111], v[86:87]
	s_add_i32 s11, s11, 1
	v_add_f32_e32 v86, v86, v87
	s_add_i32 s24, s24, 8
	s_cmp_lg_u32 s11, 32
	v_add_f32_dpp v86, v86, v86 quad_perm:[1,0,3,2] row_mask:0xf bank_mask:0xf bound_ctrl:1
	s_nop 1
	v_add_f32_dpp v86, v86, v86 quad_perm:[2,3,0,1] row_mask:0xf bank_mask:0xf bound_ctrl:1
	s_nop 1
	v_add_f32_dpp v86, v86, v86 row_half_mirror row_mask:0xf bank_mask:0xf bound_ctrl:1
	s_nop 1
	v_add_f32_dpp v86, v86, v86 row_mirror row_mask:0xf bank_mask:0xf bound_ctrl:1
	s_nop 0
	v_readlane_b32 s1, v86, 16
	v_readlane_b32 s0, v86, 0
	s_nop 0
	v_mov_b32_e32 v87, s1
	v_readlane_b32 s1, v86, 48
	v_add_f32_e32 v87, s0, v87
	v_readlane_b32 s0, v86, 32
	v_mov_b32_e32 v86, s1
	s_nop 0
	v_add_f32_e32 v86, s0, v86
	v_cndmask_b32_e64 v86, v87, v86, s[8:9]
	v_mul_f32_e32 v86, 0x3b800000, v86
	v_pk_add_f32 v[82:83], v[82:83], v[86:87] op_sel_hi:[1,0] neg_lo:[0,1] neg_hi:[0,1]
	v_pk_add_f32 v[88:89], v[88:89], v[86:87] op_sel_hi:[1,0] neg_lo:[0,1] neg_hi:[0,1]
	v_pk_mul_f32 v[110:111], v[82:83], v[82:83]
	v_pk_mul_f32 v[112:113], v[88:89], v[88:89]
	v_add_f32_e32 v105, v110, v111
	v_pk_add_f32 v[84:85], v[84:85], v[86:87] op_sel_hi:[1,0] neg_lo:[0,1] neg_hi:[0,1]
	v_add_f32_e32 v105, v112, v105
	v_pk_mul_f32 v[114:115], v[84:85], v[84:85]
	v_add_f32_e32 v105, v113, v105
	v_pk_add_f32 v[86:87], v[106:107], v[86:87] op_sel_hi:[1,0] neg_lo:[0,1] neg_hi:[0,1]
	v_add_f32_e32 v105, v114, v105
	v_pk_mul_f32 v[106:107], v[86:87], v[86:87]
	v_add_f32_e32 v105, v115, v105
	v_add_f32_e32 v105, v106, v105
	v_add_f32_e32 v105, v107, v105
	s_nop 1
	v_add_f32_dpp v105, v105, v105 quad_perm:[1,0,3,2] row_mask:0xf bank_mask:0xf bound_ctrl:1
	s_nop 1
	v_add_f32_dpp v105, v105, v105 quad_perm:[2,3,0,1] row_mask:0xf bank_mask:0xf bound_ctrl:1
	s_nop 1
	v_add_f32_dpp v105, v105, v105 row_half_mirror row_mask:0xf bank_mask:0xf bound_ctrl:1
	s_nop 1
	v_add_f32_dpp v105, v105, v105 row_mirror row_mask:0xf bank_mask:0xf bound_ctrl:1
	s_nop 0
	v_readlane_b32 s1, v105, 16
	v_readlane_b32 s0, v105, 0
	s_nop 0
	v_mov_b32_e32 v106, s1
	v_readlane_b32 s1, v105, 48
	v_add_f32_e32 v106, s0, v106
	v_readlane_b32 s0, v105, 32
	v_mov_b32_e32 v105, s1
	s_nop 0
	v_add_f32_e32 v105, s0, v105
	v_cndmask_b32_e64 v105, v106, v105, s[8:9]
	v_fmamk_f32 v105, v105, 0x3b800000, v103
	v_cmp_gt_f32_e32 vcc, s6, v105
	v_mul_f32_e32 v106, 0x4f800000, v105
	s_nop 0
	v_cndmask_b32_e32 v105, v105, v106, vcc
	v_sqrt_f32_e32 v106, v105
	s_nop 0
	v_add_u32_e32 v107, -1, v106
	v_fma_f32 v110, -v107, v106, v105
	v_cmp_ge_f32_e64 s[12:13], 0, v110
	v_add_u32_e32 v110, 1, v106
	s_nop 0
	v_cndmask_b32_e64 v107, v106, v107, s[12:13]
	v_fma_f32 v106, -v110, v106, v105
	v_cmp_lt_f32_e64 s[12:13], 0, v106
	s_nop 1
	v_cndmask_b32_e64 v106, v107, v110, s[12:13]
	v_mul_f32_e32 v107, 0x37800000, v106
	v_cndmask_b32_e32 v106, v106, v107, vcc
	v_cmp_class_f32_e32 vcc, v105, v104
	s_nop 1
	v_cndmask_b32_e32 v105, v106, v105, vcc
	v_div_scale_f32 v106, s[0:1], v105, v105, 1.0
	v_rcp_f32_e32 v107, v106
	s_nop 0
	v_fma_f32 v110, -v106, v107, 1.0
	v_fmac_f32_e32 v107, v110, v107
	v_div_scale_f32 v110, vcc, 1.0, v105, 1.0
	v_mul_f32_e32 v111, v110, v107
	v_fma_f32 v112, -v106, v111, v110
	v_fmac_f32_e32 v111, v112, v107
	v_fma_f32 v106, -v106, v111, v110
	v_div_fmas_f32 v106, v106, v107, v111
	v_div_fixup_f32 v106, v106, v105, 1.0
	v_pk_mul_f32 v[82:83], v[82:83], v[106:107] op_sel_hi:[1,0]
	v_pk_mul_f32 v[84:85], v[84:85], v[106:107] op_sel_hi:[1,0]
	v_pk_mul_f32 v[82:83], v[2:3], v[82:83]
	v_pk_mul_f32 v[84:85], v[6:7], v[84:85]
	v_pk_mul_f32 v[78:79], v[78:79], v[82:83]
	v_pk_mul_f32 v[82:83], v[88:89], v[106:107] op_sel_hi:[1,0]
	v_pk_mul_f32 v[84:85], v[80:81], v[84:85]
	v_pk_mul_f32 v[80:81], v[86:87], v[106:107] op_sel_hi:[1,0]
	v_pk_mul_f32 v[82:83], v[4:5], v[82:83]
	v_pk_mul_f32 v[80:81], v[8:9], v[80:81]
	v_pk_mul_f32 v[82:83], v[108:109], v[82:83]
	v_pk_mul_f32 v[86:87], v[100:101], v[80:81]
	v_cvt_pk_bf16_f32 v80, v78, v79
	v_cvt_pk_bf16_f32 v81, v82, v83
	v_cvt_pk_bf16_f32 v82, v84, v85
	v_cvt_pk_bf16_f32 v83, v86, v87
	v_lshl_add_u64 v[78:79], v[98:99], 0, s[26:27]
	global_store_dwordx4 v[78:79], v[80:83], off nt
	s_nop 1
	v_lshlrev_b32_e32 v80, 16, v53
	v_and_b32_e32 v81, 0xffff0000, v53
	v_lshlrev_b32_e32 v82, 16, v49
	v_and_b32_e32 v83, 0xffff0000, v49
	v_pk_add_f32 v[82:83], v[82:83], v[80:81]
	v_lshlrev_b32_e32 v80, 16, v45
	v_and_b32_e32 v81, 0xffff0000, v45
	v_mul_f32_e32 v45, 0xbfb8aa3b, v80
	v_exp_f32_e32 v45, v45
	v_and_b32_e32 v53, 0xffff0000, v48
	v_add_f32_e32 v45, 1.0, v45
	v_rcp_f32_e32 v84, v45
	v_mul_f32_e32 v45, 0xbfb8aa3b, v81
	v_exp_f32_e32 v45, v45
	s_nop 0
	v_add_f32_e32 v45, 1.0, v45
	v_rcp_f32_e32 v85, v45
	s_nop 0
	v_pk_mul_f32 v[80:81], v[84:85], v[80:81]
	v_lshlrev_b32_e32 v84, 16, v52
	v_and_b32_e32 v85, 0xffff0000, v52
	v_lshlrev_b32_e32 v52, 16, v48
	v_pk_add_f32 v[48:49], v[52:53], v[84:85]
	v_lshlrev_b32_e32 v52, 16, v44
	v_and_b32_e32 v53, 0xffff0000, v44
	v_mul_f32_e32 v44, 0xbfb8aa3b, v52
	v_mul_f32_e32 v45, 0xbfb8aa3b, v53
	v_exp_f32_e32 v44, v44
	v_exp_f32_e32 v45, v45
	v_lshlrev_b32_e32 v84, 16, v47
	v_and_b32_e32 v85, 0xffff0000, v47
	v_add_f32_e32 v44, 1.0, v44
	v_add_f32_e32 v45, 1.0, v45
	v_rcp_f32_e32 v44, v44
	v_rcp_f32_e32 v45, v45
	v_mov_b32_e32 v89, v49
	v_pk_mul_f32 v[44:45], v[44:45], v[52:53]
	v_lshlrev_b32_e32 v52, 16, v51
	v_and_b32_e32 v53, 0xffff0000, v51
	v_pk_add_f32 v[52:53], v[84:85], v[52:53]
	v_lshlrev_b32_e32 v84, 16, v43
	v_and_b32_e32 v85, 0xffff0000, v43
	v_mul_f32_e32 v43, 0xbfb8aa3b, v84
	v_exp_f32_e32 v43, v43
	v_and_b32_e32 v51, 0xffff0000, v46
	v_add_f32_e32 v43, 1.0, v43
	v_rcp_f32_e32 v86, v43
	v_mul_f32_e32 v43, 0xbfb8aa3b, v85
	v_exp_f32_e32 v43, v43
	s_nop 0
	v_add_f32_e32 v43, 1.0, v43
	v_rcp_f32_e32 v87, v43
	s_nop 0
	v_pk_mul_f32 v[84:85], v[86:87], v[84:85]
	v_lshlrev_b32_e32 v86, 16, v50
	v_and_b32_e32 v87, 0xffff0000, v50
	v_lshlrev_b32_e32 v50, 16, v46
	v_pk_add_f32 v[46:47], v[50:51], v[86:87]
	v_lshlrev_b32_e32 v50, 16, v42
	v_and_b32_e32 v51, 0xffff0000, v42
	v_mul_f32_e32 v42, 0xbfb8aa3b, v50
	v_mul_f32_e32 v43, 0xbfb8aa3b, v51
	v_exp_f32_e32 v42, v42
	v_exp_f32_e32 v43, v43
	v_mov_b32_e32 v86, v53
	v_mov_b32_e32 v87, v83
	v_add_f32_e32 v42, 1.0, v42
	v_add_f32_e32 v43, 1.0, v43
	v_rcp_f32_e32 v42, v42
	v_rcp_f32_e32 v43, v43
	v_mov_b32_e32 v88, v47
	v_pk_mul_f32 v[42:43], v[42:43], v[50:51]
	v_mov_b32_e32 v50, v52
	v_mov_b32_e32 v51, v82
	v_pk_add_f32 v[50:51], v[50:51], v[86:87]
	v_mov_b32_e32 v86, v46
	v_mov_b32_e32 v87, v48
	v_pk_add_f32 v[86:87], v[86:87], v[88:89]
	s_nop 0
	v_pk_add_f32 v[50:51], v[86:87], v[50:51]
	s_nop 0
	v_add_f32_e32 v50, v50, v51
	s_nop 1
	v_add_f32_dpp v50, v50, v50 quad_perm:[1,0,3,2] row_mask:0xf bank_mask:0xf bound_ctrl:1
	s_nop 1
	v_add_f32_dpp v50, v50, v50 quad_perm:[2,3,0,1] row_mask:0xf bank_mask:0xf bound_ctrl:1
	s_nop 1
	v_add_f32_dpp v50, v50, v50 row_half_mirror row_mask:0xf bank_mask:0xf bound_ctrl:1
	s_nop 1
	v_add_f32_dpp v50, v50, v50 row_mirror row_mask:0xf bank_mask:0xf bound_ctrl:1
	s_nop 0
	v_readlane_b32 s1, v50, 16
	v_readlane_b32 s0, v50, 0
	s_nop 0
	v_mov_b32_e32 v51, s1
	v_readlane_b32 s1, v50, 48
	v_add_f32_e32 v51, s0, v51
	v_readlane_b32 s0, v50, 32
	v_mov_b32_e32 v50, s1
	s_nop 0
	v_add_f32_e32 v50, s0, v50
	v_cndmask_b32_e64 v50, v51, v50, s[8:9]
	v_mul_f32_e32 v50, 0x3b800000, v50
	v_pk_add_f32 v[46:47], v[46:47], v[50:51] op_sel_hi:[1,0] neg_lo:[0,1] neg_hi:[0,1]
	v_pk_add_f32 v[52:53], v[52:53], v[50:51] op_sel_hi:[1,0] neg_lo:[0,1] neg_hi:[0,1]
	v_pk_mul_f32 v[86:87], v[46:47], v[46:47]
	v_pk_mul_f32 v[88:89], v[52:53], v[52:53]
	v_add_f32_e32 v86, v86, v87
	v_pk_add_f32 v[48:49], v[48:49], v[50:51] op_sel_hi:[1,0] neg_lo:[0,1] neg_hi:[0,1]
	v_add_f32_e32 v86, v88, v86
	v_pk_mul_f32 v[100:101], v[48:49], v[48:49]
	v_add_f32_e32 v86, v89, v86
	v_pk_add_f32 v[50:51], v[82:83], v[50:51] op_sel_hi:[1,0] neg_lo:[0,1] neg_hi:[0,1]
	v_add_f32_e32 v86, v100, v86
	v_pk_mul_f32 v[82:83], v[50:51], v[50:51]
	v_add_f32_e32 v86, v101, v86
	v_add_f32_e32 v82, v82, v86
	v_add_f32_e32 v82, v83, v82
	s_nop 1
	v_add_f32_dpp v82, v82, v82 quad_perm:[1,0,3,2] row_mask:0xf bank_mask:0xf bound_ctrl:1
	s_nop 1
	v_add_f32_dpp v82, v82, v82 quad_perm:[2,3,0,1] row_mask:0xf bank_mask:0xf bound_ctrl:1
	s_nop 1
	v_add_f32_dpp v82, v82, v82 row_half_mirror row_mask:0xf bank_mask:0xf bound_ctrl:1
	s_nop 1
	v_add_f32_dpp v82, v82, v82 row_mirror row_mask:0xf bank_mask:0xf bound_ctrl:1
	s_nop 0
	v_readlane_b32 s1, v82, 16
	v_readlane_b32 s0, v82, 0
	s_nop 0
	v_mov_b32_e32 v83, s1
	v_readlane_b32 s1, v82, 48
	v_add_f32_e32 v83, s0, v83
	v_readlane_b32 s0, v82, 32
	v_mov_b32_e32 v82, s1
	s_nop 0
	v_add_f32_e32 v82, s0, v82
	v_cndmask_b32_e64 v82, v83, v82, s[8:9]
	v_fmamk_f32 v82, v82, 0x3b800000, v103
	v_cmp_gt_f32_e32 vcc, s6, v82
	v_mul_f32_e32 v83, 0x4f800000, v82
	s_nop 0
	v_cndmask_b32_e32 v82, v82, v83, vcc
	v_sqrt_f32_e32 v83, v82
	s_nop 0
	v_add_u32_e32 v86, -1, v83
	v_fma_f32 v87, -v86, v83, v82
	v_cmp_ge_f32_e64 s[12:13], 0, v87
	v_add_u32_e32 v87, 1, v83
	s_nop 0
	v_cndmask_b32_e64 v86, v83, v86, s[12:13]
	v_fma_f32 v83, -v87, v83, v82
	v_cmp_lt_f32_e64 s[12:13], 0, v83
	s_nop 1
	v_cndmask_b32_e64 v83, v86, v87, s[12:13]
	v_mul_f32_e32 v86, 0x37800000, v83
	v_cndmask_b32_e32 v83, v83, v86, vcc
	v_cmp_class_f32_e32 vcc, v82, v104
	s_nop 1
	v_cndmask_b32_e32 v82, v83, v82, vcc
	v_div_scale_f32 v83, s[0:1], v82, v82, 1.0
	v_rcp_f32_e32 v86, v83
	s_nop 0
	v_fma_f32 v87, -v83, v86, 1.0
	v_fmac_f32_e32 v86, v87, v86
	v_div_scale_f32 v87, vcc, 1.0, v82, 1.0
	v_mul_f32_e32 v88, v87, v86
	v_fma_f32 v89, -v83, v88, v87
	v_fmac_f32_e32 v88, v89, v86
	v_fma_f32 v83, -v83, v88, v87
	v_div_fmas_f32 v83, v83, v86, v88
	v_div_fixup_f32 v82, v83, v82, 1.0
	v_pk_mul_f32 v[46:47], v[46:47], v[82:83] op_sel_hi:[1,0]
	v_pk_mul_f32 v[48:49], v[48:49], v[82:83] op_sel_hi:[1,0]
	v_pk_mul_f32 v[46:47], v[10:11], v[46:47]
	v_pk_mul_f32 v[48:49], v[14:15], v[48:49]
	v_pk_mul_f32 v[42:43], v[42:43], v[46:47]
	v_pk_mul_f32 v[46:47], v[52:53], v[82:83] op_sel_hi:[1,0]
	v_pk_mul_f32 v[44:45], v[44:45], v[48:49]
	v_pk_mul_f32 v[48:49], v[50:51], v[82:83] op_sel_hi:[1,0]
	v_pk_mul_f32 v[46:47], v[12:13], v[46:47]
	v_pk_mul_f32 v[48:49], v[16:17], v[48:49]
	v_pk_mul_f32 v[46:47], v[84:85], v[46:47]
	v_pk_mul_f32 v[48:49], v[80:81], v[48:49]
	v_cvt_pk_bf16_f32 v42, v42, v43
	v_cvt_pk_bf16_f32 v43, v46, v47
	v_cvt_pk_bf16_f32 v44, v44, v45
	v_cvt_pk_bf16_f32 v45, v48, v49
	global_store_dwordx4 v[78:79], v[42:45], off offset:1024 nt
	v_mov_b64_e32 v[80:81], v[20:21]
	v_mov_b64_e32 v[78:79], v[18:19]
	v_mov_b64_e32 v[44:45], v[24:25]
	v_mov_b64_e32 v[42:43], v[22:23]
	s_waitcnt vmcnt(0) lgkmcnt(0)
	v_mov_b64_e32 v[22:23], v[74:75]
	v_mov_b64_e32 v[18:19], v[70:71]
	v_mov_b64_e32 v[84:85], v[68:69]
	v_mov_b64_e32 v[46:47], v[62:63]
	v_mov_b64_e32 v[88:89], v[60:61]
	v_mov_b64_e32 v[50:51], v[54:55]
	v_mov_b64_e32 v[24:25], v[76:77]
	v_mov_b64_e32 v[20:21], v[72:73]
	v_mov_b64_e32 v[82:83], v[66:67]
	v_mov_b64_e32 v[48:49], v[64:65]
	v_mov_b64_e32 v[86:87], v[58:59]
	v_mov_b64_e32 v[52:53], v[56:57]
	s_cbranch_scc1 .LBB0_1040
	s_add_i32 s7, s7, s74
	s_add_i32 s4, s4, s5
	s_cmpk_gt_i32 s7, 0xff
	s_cbranch_scc0 .LBB0_1039

.LBB0_1047:
	ds_read_b128 v[130:133], v170
	ds_read_b128 v[134:137], v170 offset:1024
	ds_read_b128 v[138:141], v170 offset:2048
	ds_read_b128 v[142:145], v170 offset:3072
	s_add_u32 s0, s38, 0xfffc0080
	s_addc_u32 s1, s39, -1
	s_cmp_eq_u32 s69, 12
	s_cselect_b32 s43, s60, s1
	s_cselect_b32 s42, s61, s0
	s_cselect_b32 s41, s62, s65
	s_cselect_b32 s40, s63, s64
	s_mov_b32 m0, s50
	v_lshl_add_u64 v[166:167], s[38:39], 0, v[164:165]
	ds_read_b128 v[146:149], v171
	ds_read_b128 v[174:177], v171 offset:1024
	ds_read_b128 v[178:181], v171 offset:2048
	ds_read_b128 v[182:185], v171 offset:3072
	ds_read_b128 v[186:189], v171 offset:4096
	ds_read_b128 v[190:193], v171 offset:5120
	ds_read_b128 v[194:197], v171 offset:6144
	ds_read_b128 v[198:201], v171 offset:7168
	global_load_lds_dwordx4 v[166:167], off
	v_lshl_add_u64 v[166:167], s[38:39], 0, v[162:163]
	s_mov_b32 m0, s51
	s_nop 0
	global_load_lds_dwordx4 v[166:167], off
	s_waitcnt lgkmcnt(8)
	s_waitcnt vmcnt(10)
	s_barrier
	s_waitcnt lgkmcnt(0)
	s_waitcnt lgkmcnt(0)
	v_mfma_f32_16x16x32_bf16 v[126:129], v[130:133], v[146:149], v[126:129]
	v_mfma_f32_16x16x32_bf16 v[122:125], v[138:141], v[146:149], v[122:125]
	v_mfma_f32_16x16x32_bf16 v[118:121], v[130:133], v[178:181], v[118:121]
	v_mfma_f32_16x16x32_bf16 v[110:113], v[138:141], v[178:181], v[110:113]
	v_mfma_f32_16x16x32_bf16 v[98:101], v[130:133], v[186:189], v[98:101]
	v_mfma_f32_16x16x32_bf16 v[90:93], v[138:141], v[186:189], v[90:93]
	v_mfma_f32_16x16x32_bf16 v[82:85], v[130:133], v[194:197], v[82:85]
	v_mfma_f32_16x16x32_bf16 v[74:77], v[138:141], v[194:197], v[74:77]
	v_mfma_f32_16x16x32_bf16 v[126:129], v[134:137], v[174:177], v[126:129]
	v_mfma_f32_16x16x32_bf16 v[122:125], v[142:145], v[174:177], v[122:125]
	v_mfma_f32_16x16x32_bf16 v[118:121], v[134:137], v[182:185], v[118:121]
	v_mfma_f32_16x16x32_bf16 v[110:113], v[142:145], v[182:185], v[110:113]
	v_mfma_f32_16x16x32_bf16 v[98:101], v[134:137], v[190:193], v[98:101]
	v_mfma_f32_16x16x32_bf16 v[90:93], v[142:145], v[190:193], v[90:93]
	v_mfma_f32_16x16x32_bf16 v[82:85], v[134:137], v[198:201], v[82:85]
	v_mfma_f32_16x16x32_bf16 v[74:77], v[142:145], v[198:201], v[74:77]
	s_barrier
	s_mov_b32 m0, s52
	v_lshl_add_u64 v[166:167], s[40:41], 0, v[158:159]
	ds_read_b128 v[202:205], v172
	ds_read_b128 v[206:209], v172 offset:1024
	ds_read_b128 v[210:213], v172 offset:2048
	ds_read_b128 v[214:217], v172 offset:3072
	global_load_lds_dwordx4 v[166:167], off
	v_lshl_add_u64 v[218:219], s[40:41], 0, v[154:155]
	s_mov_b32 m0, s53
	s_nop 0
	global_load_lds_dwordx4 v[218:219], off
	s_waitcnt vmcnt(10)
	s_barrier
	s_waitcnt lgkmcnt(0)
	s_waitcnt lgkmcnt(0)
	v_mfma_f32_16x16x32_bf16 v[114:117], v[202:205], v[146:149], v[114:117]
	v_mfma_f32_16x16x32_bf16 v[106:109], v[210:213], v[146:149], v[106:109]
	v_mfma_f32_16x16x32_bf16 v[102:105], v[202:205], v[178:181], v[102:105]
	v_mfma_f32_16x16x32_bf16 v[94:97], v[210:213], v[178:181], v[94:97]
	v_mfma_f32_16x16x32_bf16 v[86:89], v[202:205], v[186:189], v[86:89]
	v_mfma_f32_16x16x32_bf16 v[78:81], v[210:213], v[186:189], v[78:81]
	v_mfma_f32_16x16x32_bf16 v[70:73], v[202:205], v[194:197], v[70:73]
	v_mfma_f32_16x16x32_bf16 v[66:69], v[210:213], v[194:197], v[66:69]
	v_mfma_f32_16x16x32_bf16 v[114:117], v[206:209], v[174:177], v[114:117]
	v_mfma_f32_16x16x32_bf16 v[106:109], v[214:217], v[174:177], v[106:109]
	v_mfma_f32_16x16x32_bf16 v[102:105], v[206:209], v[182:185], v[102:105]
	v_mfma_f32_16x16x32_bf16 v[94:97], v[214:217], v[182:185], v[94:97]
	v_mfma_f32_16x16x32_bf16 v[86:89], v[206:209], v[190:193], v[86:89]
	v_mfma_f32_16x16x32_bf16 v[78:81], v[214:217], v[190:193], v[78:81]
	v_mfma_f32_16x16x32_bf16 v[70:73], v[206:209], v[198:201], v[70:73]
	v_mfma_f32_16x16x32_bf16 v[66:69], v[214:217], v[198:201], v[66:69]
	s_mov_b32 m0, s6
	v_lshl_add_u64 v[220:221], s[42:43], 0, v[160:161]
	s_barrier
	ds_read_b128 v[146:149], v171 offset:16384
	ds_read_b128 v[174:177], v171 offset:17408
	ds_read_b128 v[178:181], v171 offset:18432
	ds_read_b128 v[182:185], v171 offset:19456
	ds_read_b128 v[186:189], v171 offset:20480
	ds_read_b128 v[190:193], v171 offset:21504
	ds_read_b128 v[194:197], v171 offset:22528
	ds_read_b128 v[198:201], v171 offset:23552
	global_load_lds_dwordx4 v[220:221], off
	v_lshl_add_u64 v[222:223], s[42:43], 0, v[156:157]
	s_mov_b32 m0, s7
	s_nop 0
	global_load_lds_dwordx4 v[222:223], off
	s_waitcnt vmcnt(10)
	s_barrier
	s_waitcnt lgkmcnt(0)
	s_waitcnt lgkmcnt(0)
	v_mfma_f32_16x16x32_bf16 v[62:65], v[130:133], v[146:149], v[62:65]
	v_mfma_f32_16x16x32_bf16 v[58:61], v[138:141], v[146:149], v[58:61]
	v_mfma_f32_16x16x32_bf16 v[50:53], v[130:133], v[178:181], v[50:53]
	v_mfma_f32_16x16x32_bf16 v[42:45], v[138:141], v[178:181], v[42:45]
	v_mfma_f32_16x16x32_bf16 v[34:37], v[130:133], v[186:189], v[34:37]
	v_mfma_f32_16x16x32_bf16 v[26:29], v[138:141], v[186:189], v[26:29]
	v_mfma_f32_16x16x32_bf16 v[18:21], v[130:133], v[194:197], v[18:21]
	v_mfma_f32_16x16x32_bf16 v[10:13], v[138:141], v[194:197], v[10:13]
	v_mfma_f32_16x16x32_bf16 v[62:65], v[134:137], v[174:177], v[62:65]
	v_mfma_f32_16x16x32_bf16 v[58:61], v[142:145], v[174:177], v[58:61]
	v_mfma_f32_16x16x32_bf16 v[50:53], v[134:137], v[182:185], v[50:53]
	v_mfma_f32_16x16x32_bf16 v[42:45], v[142:145], v[182:185], v[42:45]
	v_mfma_f32_16x16x32_bf16 v[34:37], v[134:137], v[190:193], v[34:37]
	v_mfma_f32_16x16x32_bf16 v[26:29], v[142:145], v[190:193], v[26:29]
	v_mfma_f32_16x16x32_bf16 v[18:21], v[134:137], v[198:201], v[18:21]
	v_mfma_f32_16x16x32_bf16 v[10:13], v[142:145], v[198:201], v[10:13]
	s_barrier
	s_add_u32 s0, s40, 0x40000
	s_addc_u32 s1, s41, 0
	s_mov_b32 m0, s54
	v_lshl_add_u64 v[130:131], s[0:1], 0, v[158:159]
	global_load_lds_dwordx4 v[130:131], off
	v_lshl_add_u64 v[130:131], s[0:1], 0, v[154:155]
	s_add_i32 m0, s54, 0x2000
	s_nop 0
	global_load_lds_dwordx4 v[130:131], off
	s_waitcnt vmcnt(10)
	s_barrier
	v_mfma_f32_16x16x32_bf16 v[54:57], v[202:205], v[146:149], v[54:57]
	v_mfma_f32_16x16x32_bf16 v[46:49], v[210:213], v[146:149], v[46:49]
	v_mfma_f32_16x16x32_bf16 v[38:41], v[202:205], v[178:181], v[38:41]
	v_mfma_f32_16x16x32_bf16 v[30:33], v[210:213], v[178:181], v[30:33]
	v_mfma_f32_16x16x32_bf16 v[22:25], v[202:205], v[186:189], v[22:25]
	v_mfma_f32_16x16x32_bf16 v[14:17], v[210:213], v[186:189], v[14:17]
	v_mfma_f32_16x16x32_bf16 v[6:9], v[202:205], v[194:197], v[6:9]
	v_mfma_f32_16x16x32_bf16 v[2:5], v[210:213], v[194:197], v[2:5]
	v_mfma_f32_16x16x32_bf16 v[54:57], v[206:209], v[174:177], v[54:57]
	v_mfma_f32_16x16x32_bf16 v[46:49], v[214:217], v[174:177], v[46:49]
	v_mfma_f32_16x16x32_bf16 v[38:41], v[206:209], v[182:185], v[38:41]
	v_mfma_f32_16x16x32_bf16 v[30:33], v[214:217], v[182:185], v[30:33]
	v_mfma_f32_16x16x32_bf16 v[22:25], v[206:209], v[190:193], v[22:25]
	v_mfma_f32_16x16x32_bf16 v[14:17], v[214:217], v[190:193], v[14:17]
	v_mfma_f32_16x16x32_bf16 v[6:9], v[206:209], v[198:201], v[6:9]
	v_mfma_f32_16x16x32_bf16 v[2:5], v[214:217], v[198:201], v[2:5]
	s_add_i32 s70, 0, 0x18000
	v_add_u32_e32 v142, s70, v169
	s_barrier
	ds_read_b128 v[130:133], v142
	ds_read_b128 v[134:137], v142 offset:1024
	ds_read_b128 v[138:141], v142 offset:2048
	ds_read_b128 v[142:145], v142 offset:3072
	s_add_u32 s0, s42, 0x40000
	s_addc_u32 s1, s43, 0
	s_mov_b32 m0, s10
	v_lshl_add_u64 v[202:203], s[0:1], 0, v[160:161]
	ds_read_b128 v[146:149], v171 offset:32768
	ds_read_b128 v[174:177], v171 offset:33792
	ds_read_b128 v[178:181], v171 offset:34816
	ds_read_b128 v[182:185], v171 offset:35840
	ds_read_b128 v[186:189], v171 offset:36864
	ds_read_b128 v[190:193], v171 offset:37888
	ds_read_b128 v[194:197], v171 offset:38912
	ds_read_b128 v[198:201], v171 offset:39936
	global_load_lds_dwordx4 v[202:203], off
	v_lshl_add_u64 v[202:203], s[0:1], 0, v[156:157]
	s_mov_b32 m0, s11
	s_nop 0
	global_load_lds_dwordx4 v[202:203], off
	s_waitcnt lgkmcnt(8)
	s_waitcnt vmcnt(10)
	s_barrier
	s_waitcnt lgkmcnt(0)
	s_waitcnt lgkmcnt(0)
	v_mfma_f32_16x16x32_bf16 v[126:129], v[130:133], v[146:149], v[126:129]
	v_mfma_f32_16x16x32_bf16 v[122:125], v[138:141], v[146:149], v[122:125]
	v_mfma_f32_16x16x32_bf16 v[118:121], v[130:133], v[178:181], v[118:121]
	v_mfma_f32_16x16x32_bf16 v[110:113], v[138:141], v[178:181], v[110:113]
	v_mfma_f32_16x16x32_bf16 v[98:101], v[130:133], v[186:189], v[98:101]
	v_mfma_f32_16x16x32_bf16 v[90:93], v[138:141], v[186:189], v[90:93]
	v_mfma_f32_16x16x32_bf16 v[82:85], v[130:133], v[194:197], v[82:85]
	v_mfma_f32_16x16x32_bf16 v[74:77], v[138:141], v[194:197], v[74:77]
	v_mfma_f32_16x16x32_bf16 v[126:129], v[134:137], v[174:177], v[126:129]
	v_mfma_f32_16x16x32_bf16 v[122:125], v[142:145], v[174:177], v[122:125]
	v_mfma_f32_16x16x32_bf16 v[118:121], v[134:137], v[182:185], v[118:121]
	v_mfma_f32_16x16x32_bf16 v[110:113], v[142:145], v[182:185], v[110:113]
	v_mfma_f32_16x16x32_bf16 v[98:101], v[134:137], v[190:193], v[98:101]
	v_mfma_f32_16x16x32_bf16 v[90:93], v[142:145], v[190:193], v[90:93]
	v_mfma_f32_16x16x32_bf16 v[82:85], v[134:137], v[198:201], v[82:85]
	v_mfma_f32_16x16x32_bf16 v[74:77], v[142:145], v[198:201], v[74:77]
	s_barrier
	s_add_i32 s42, 0, 0x1c000
	s_add_i32 s0, s70, s5
	v_add_u32_e32 v173, s42, v169
	v_lshl_add_u64 v[166:167], v[166:167], 0, s[28:29]
	s_mov_b32 m0, s0
	ds_read_b128 v[202:205], v173
	ds_read_b128 v[206:209], v173 offset:1024
	ds_read_b128 v[210:213], v173 offset:2048
	ds_read_b128 v[214:217], v173 offset:3072
	global_load_lds_dwordx4 v[166:167], off
	v_lshl_add_u64 v[166:167], v[218:219], 0, s[28:29]
	s_add_i32 m0, s0, 0x2000
	s_nop 0
	global_load_lds_dwordx4 v[166:167], off
	s_waitcnt vmcnt(10)
	s_barrier
	s_waitcnt lgkmcnt(0)
	s_waitcnt lgkmcnt(0)
	v_mfma_f32_16x16x32_bf16 v[114:117], v[202:205], v[146:149], v[114:117]
	v_mfma_f32_16x16x32_bf16 v[106:109], v[210:213], v[146:149], v[106:109]
	v_mfma_f32_16x16x32_bf16 v[102:105], v[202:205], v[178:181], v[102:105]
	v_mfma_f32_16x16x32_bf16 v[94:97], v[210:213], v[178:181], v[94:97]
	v_mfma_f32_16x16x32_bf16 v[86:89], v[202:205], v[186:189], v[86:89]
	v_mfma_f32_16x16x32_bf16 v[78:81], v[210:213], v[186:189], v[78:81]
	v_mfma_f32_16x16x32_bf16 v[70:73], v[202:205], v[194:197], v[70:73]
	v_mfma_f32_16x16x32_bf16 v[66:69], v[210:213], v[194:197], v[66:69]
	v_mfma_f32_16x16x32_bf16 v[114:117], v[206:209], v[174:177], v[114:117]
	v_mfma_f32_16x16x32_bf16 v[106:109], v[214:217], v[174:177], v[106:109]
	v_mfma_f32_16x16x32_bf16 v[102:105], v[206:209], v[182:185], v[102:105]
	v_mfma_f32_16x16x32_bf16 v[94:97], v[214:217], v[182:185], v[94:97]
	v_mfma_f32_16x16x32_bf16 v[86:89], v[206:209], v[190:193], v[86:89]
	v_mfma_f32_16x16x32_bf16 v[78:81], v[214:217], v[190:193], v[78:81]
	v_mfma_f32_16x16x32_bf16 v[70:73], v[206:209], v[198:201], v[70:73]
	v_mfma_f32_16x16x32_bf16 v[66:69], v[214:217], v[198:201], v[66:69]
	s_mov_b32 m0, s48
	v_lshl_add_u64 v[166:167], v[220:221], 0, s[28:29]
	s_barrier
	ds_read_b128 v[146:149], v171 offset:49152
	ds_read_b128 v[174:177], v171 offset:50176
	ds_read_b128 v[178:181], v171 offset:51200
	ds_read_b128 v[182:185], v171 offset:52224
	ds_read_b128 v[186:189], v171 offset:53248
	ds_read_b128 v[190:193], v171 offset:54272
	ds_read_b128 v[194:197], v171 offset:55296
	ds_read_b128 v[198:201], v171 offset:56320
	global_load_lds_dwordx4 v[166:167], off
	v_lshl_add_u64 v[166:167], v[222:223], 0, s[28:29]
	s_mov_b32 m0, s49
	s_nop 0
	global_load_lds_dwordx4 v[166:167], off
	s_waitcnt vmcnt(10)
	s_barrier
	s_waitcnt lgkmcnt(0)
	s_waitcnt lgkmcnt(0)
	v_mfma_f32_16x16x32_bf16 v[62:65], v[130:133], v[146:149], v[62:65]
	v_mfma_f32_16x16x32_bf16 v[58:61], v[138:141], v[146:149], v[58:61]
	v_mfma_f32_16x16x32_bf16 v[50:53], v[130:133], v[178:181], v[50:53]
	v_mfma_f32_16x16x32_bf16 v[42:45], v[138:141], v[178:181], v[42:45]
	v_mfma_f32_16x16x32_bf16 v[34:37], v[130:133], v[186:189], v[34:37]
	v_mfma_f32_16x16x32_bf16 v[26:29], v[138:141], v[186:189], v[26:29]
	v_mfma_f32_16x16x32_bf16 v[18:21], v[130:133], v[194:197], v[18:21]
	v_mfma_f32_16x16x32_bf16 v[10:13], v[138:141], v[194:197], v[10:13]
	v_mfma_f32_16x16x32_bf16 v[62:65], v[134:137], v[174:177], v[62:65]
	v_mfma_f32_16x16x32_bf16 v[58:61], v[142:145], v[174:177], v[58:61]
	v_mfma_f32_16x16x32_bf16 v[50:53], v[134:137], v[182:185], v[50:53]
	v_mfma_f32_16x16x32_bf16 v[42:45], v[142:145], v[182:185], v[42:45]
	v_mfma_f32_16x16x32_bf16 v[34:37], v[134:137], v[190:193], v[34:37]
	v_mfma_f32_16x16x32_bf16 v[26:29], v[142:145], v[190:193], v[26:29]
	v_mfma_f32_16x16x32_bf16 v[18:21], v[134:137], v[198:201], v[18:21]
	v_mfma_f32_16x16x32_bf16 v[10:13], v[142:145], v[198:201], v[10:13]
	s_barrier
	s_add_u32 s0, s40, 0x40080
	s_addc_u32 s1, s41, 0
	s_add_i32 s40, s42, s5
	v_lshl_add_u64 v[130:131], s[0:1], 0, v[158:159]
	s_mov_b32 m0, s40
	s_nop 0
	global_load_lds_dwordx4 v[130:131], off
	v_lshl_add_u64 v[130:131], s[0:1], 0, v[154:155]
	s_add_i32 m0, s40, 0x2000
	s_nop 0
	global_load_lds_dwordx4 v[130:131], off
	s_waitcnt vmcnt(10)
	s_barrier
	v_mfma_f32_16x16x32_bf16 v[54:57], v[202:205], v[146:149], v[54:57]
	v_mfma_f32_16x16x32_bf16 v[46:49], v[210:213], v[146:149], v[46:49]
	v_mfma_f32_16x16x32_bf16 v[38:41], v[202:205], v[178:181], v[38:41]
	v_mfma_f32_16x16x32_bf16 v[30:33], v[210:213], v[178:181], v[30:33]
	v_mfma_f32_16x16x32_bf16 v[22:25], v[202:205], v[186:189], v[22:25]
	v_mfma_f32_16x16x32_bf16 v[14:17], v[210:213], v[186:189], v[14:17]
	v_mfma_f32_16x16x32_bf16 v[6:9], v[202:205], v[194:197], v[6:9]
	v_mfma_f32_16x16x32_bf16 v[2:5], v[210:213], v[194:197], v[2:5]
	v_mfma_f32_16x16x32_bf16 v[54:57], v[206:209], v[174:177], v[54:57]
	v_mfma_f32_16x16x32_bf16 v[46:49], v[214:217], v[174:177], v[46:49]
	v_mfma_f32_16x16x32_bf16 v[38:41], v[206:209], v[182:185], v[38:41]
	v_mfma_f32_16x16x32_bf16 v[30:33], v[214:217], v[182:185], v[30:33]
	v_mfma_f32_16x16x32_bf16 v[22:25], v[206:209], v[190:193], v[22:25]
	v_mfma_f32_16x16x32_bf16 v[14:17], v[214:217], v[190:193], v[14:17]
	v_mfma_f32_16x16x32_bf16 v[6:9], v[206:209], v[198:201], v[6:9]
	v_mfma_f32_16x16x32_bf16 v[2:5], v[214:217], v[198:201], v[2:5]
	s_add_i32 s69, s69, 2
	s_add_u32 s64, s64, 0x100
	s_addc_u32 s65, s65, 0
	s_add_u32 s38, s38, 0x100
	s_addc_u32 s39, s39, 0
	s_cmp_gt_u32 s69, 13
	s_barrier
	s_cbranch_scc0 .LBB0_1047
	s_lshl_b32 s0, s58, 8
	v_mov_b32_e32 v130, v151
	v_mov_b32_e32 v131, v153
	s_or_b32 s0, s0, s45
	s_mov_b32 s58, s57
	v_lshl_add_u32 v166, v131, 3, s0
	s_lshl_b32 s0, s59, 8
	s_add_i32 s0, s0, s44
	v_add_u32_e32 v173, s0, v130
	v_mov_b32_e32 v130, v173
	v_ashrrev_i32_e32 v167, 31, v166
	v_ashrrev_i32_e32 v131, 31, v130
	v_lshlrev_b64 v[130:131], 10, v[130:131]
	v_lshl_add_u64 v[130:131], v[130:131], 0, v[166:167]
	v_lshlrev_b64 v[186:187], 1, v[130:131]
	v_lshl_add_u64 v[130:131], s[12:13], 0, v[186:187]
	global_load_dwordx4 v[174:177], v[130:131], off
	global_load_dwordx4 v[178:181], v[130:131], off offset:256
	v_add_co_u32_e32 v132, vcc, s47, v130
	s_mov_b32 s59, s56
	s_nop 0
	v_addc_co_u32_e32 v133, vcc, 0, v131, vcc
	global_load_dwordx4 v[182:185], v[132:133], off
	global_load_dwordx4 v[146:149], v[132:133], off offset:256
	v_add_co_u32_e32 v132, vcc, s31, v130
	s_waitcnt vmcnt(0) lgkmcnt(0)
	v_lshlrev_b32_e32 v188, 16, v174
	v_addc_co_u32_e32 v133, vcc, 0, v131, vcc
	global_load_dwordx4 v[142:145], v[132:133], off
	global_load_dwordx4 v[138:141], v[132:133], off offset:256
	v_add_co_u32_e32 v130, vcc, s46, v130
	v_and_b32_e32 v189, 0xffff0000, v174
	s_nop 0
	v_addc_co_u32_e32 v131, vcc, 0, v131, vcc
	global_load_dwordx4 v[134:137], v[130:131], off
	s_nop 0
	global_load_dwordx4 v[130:133], v[130:131], off offset:256
	v_lshlrev_b32_e32 v174, 16, v175
	v_and_b32_e32 v175, 0xffff0000, v175
	v_lshlrev_b32_e32 v190, 16, v176
	v_and_b32_e32 v191, 0xffff0000, v176
	v_lshlrev_b32_e32 v176, 16, v177
	v_and_b32_e32 v177, 0xffff0000, v177
	v_pk_fma_f32 v[128:129], v[174:175], s[30:31], v[128:129] op_sel_hi:[1,0,1]
	v_pk_fma_f32 v[126:127], v[188:189], s[30:31], v[126:127] op_sel_hi:[1,0,1]
	v_pk_fma_f32 v[174:175], v[176:177], s[30:31], v[124:125] op_sel_hi:[1,0,1]
	v_pk_fma_f32 v[122:123], v[190:191], s[30:31], v[122:123] op_sel_hi:[1,0,1]
	v_cvt_pk_bf16_f32 v124, v126, v127
	v_cvt_pk_bf16_f32 v125, v128, v129
	v_cvt_pk_bf16_f32 v126, v122, v123
	v_cvt_pk_bf16_f32 v127, v174, v175
	v_lshl_add_u64 v[122:123], s[24:25], 0, v[186:187]
	global_store_dwordx4 v[122:123], v[124:127], off nt
	v_lshlrev_b32_e32 v128, 16, v180
	v_and_b32_e32 v129, 0xffff0000, v180
	v_lshlrev_b32_e32 v124, 16, v178
	v_and_b32_e32 v125, 0xffff0000, v178
	v_lshlrev_b32_e32 v126, 16, v179
	v_and_b32_e32 v127, 0xffff0000, v179
	v_lshlrev_b32_e32 v174, 16, v181
	v_and_b32_e32 v175, 0xffff0000, v181
	v_pk_fma_f32 v[116:117], v[126:127], s[30:31], v[116:117] op_sel_hi:[1,0,1]
	v_pk_fma_f32 v[114:115], v[124:125], s[30:31], v[114:115] op_sel_hi:[1,0,1]
	v_pk_fma_f32 v[124:125], v[174:175], s[30:31], v[108:109] op_sel_hi:[1,0,1]
	v_pk_fma_f32 v[108:109], v[128:129], s[30:31], v[106:107] op_sel_hi:[1,0,1]
	v_cvt_pk_bf16_f32 v106, v114, v115
	v_cvt_pk_bf16_f32 v107, v116, v117
	v_cvt_pk_bf16_f32 v108, v108, v109
	v_cvt_pk_bf16_f32 v109, v124, v125
	global_store_dwordx4 v[122:123], v[106:109], off offset:256 nt
	v_lshlrev_b32_e32 v114, 16, v184
	v_and_b32_e32 v115, 0xffff0000, v184
	v_lshlrev_b32_e32 v106, 16, v182
	v_and_b32_e32 v107, 0xffff0000, v182
	v_lshlrev_b32_e32 v108, 16, v183
	v_and_b32_e32 v109, 0xffff0000, v183
	v_lshlrev_b32_e32 v116, 16, v185
	v_and_b32_e32 v117, 0xffff0000, v185
	v_pk_fma_f32 v[108:109], v[108:109], s[30:31], v[120:121] op_sel_hi:[1,0,1]
	v_pk_fma_f32 v[106:107], v[106:107], s[30:31], v[118:119] op_sel_hi:[1,0,1]
	v_pk_fma_f32 v[110:111], v[114:115], s[30:31], v[110:111] op_sel_hi:[1,0,1]
	v_pk_fma_f32 v[112:113], v[116:117], s[30:31], v[112:113] op_sel_hi:[1,0,1]
	v_cvt_pk_bf16_f32 v106, v106, v107
	v_cvt_pk_bf16_f32 v107, v108, v109
	v_cvt_pk_bf16_f32 v108, v110, v111
	v_add_co_u32_e32 v110, vcc, s47, v122
	v_cvt_pk_bf16_f32 v109, v112, v113
	s_nop 0
	v_addc_co_u32_e32 v111, vcc, 0, v123, vcc
	global_store_dwordx4 v[110:111], v[106:109], off nt
	v_lshlrev_b32_e32 v112, 16, v148
	v_and_b32_e32 v113, 0xffff0000, v148
	v_lshlrev_b32_e32 v106, 16, v146
	v_and_b32_e32 v107, 0xffff0000, v146
	v_lshlrev_b32_e32 v108, 16, v147
	v_and_b32_e32 v109, 0xffff0000, v147
	v_lshlrev_b32_e32 v114, 16, v149
	v_and_b32_e32 v115, 0xffff0000, v149
	v_pk_fma_f32 v[104:105], v[108:109], s[30:31], v[104:105] op_sel_hi:[1,0,1]
	v_pk_fma_f32 v[102:103], v[106:107], s[30:31], v[102:103] op_sel_hi:[1,0,1]
	v_pk_fma_f32 v[106:107], v[114:115], s[30:31], v[96:97] op_sel_hi:[1,0,1]
	v_pk_fma_f32 v[96:97], v[112:113], s[30:31], v[94:95] op_sel_hi:[1,0,1]
	v_cvt_pk_bf16_f32 v94, v102, v103
	v_cvt_pk_bf16_f32 v95, v104, v105
	v_cvt_pk_bf16_f32 v96, v96, v97
	v_cvt_pk_bf16_f32 v97, v106, v107
	global_store_dwordx4 v[110:111], v[94:97], off offset:256 nt
	s_waitcnt vmcnt(0) lgkmcnt(0)
	v_lshlrev_b32_e32 v102, 16, v144
	v_lshlrev_b32_e32 v94, 16, v142
	v_and_b32_e32 v95, 0xffff0000, v142
	v_lshlrev_b32_e32 v96, 16, v143
	v_and_b32_e32 v97, 0xffff0000, v143
	v_and_b32_e32 v103, 0xffff0000, v144
	v_lshlrev_b32_e32 v104, 16, v145
	v_and_b32_e32 v105, 0xffff0000, v145
	v_pk_fma_f32 v[94:95], v[94:95], s[30:31], v[98:99] op_sel_hi:[1,0,1]
	v_pk_fma_f32 v[96:97], v[96:97], s[30:31], v[100:101] op_sel_hi:[1,0,1]
	v_pk_fma_f32 v[98:99], v[104:105], s[30:31], v[92:93] op_sel_hi:[1,0,1]
	v_pk_fma_f32 v[92:93], v[102:103], s[30:31], v[90:91] op_sel_hi:[1,0,1]
	v_cvt_pk_bf16_f32 v90, v94, v95
	v_add_co_u32_e32 v94, vcc, s31, v122
	v_cvt_pk_bf16_f32 v91, v96, v97
	v_cvt_pk_bf16_f32 v92, v92, v93
	v_cvt_pk_bf16_f32 v93, v98, v99
	v_addc_co_u32_e32 v95, vcc, 0, v123, vcc
	global_store_dwordx4 v[94:95], v[90:93], off nt
	v_lshlrev_b32_e32 v96, 16, v140
	v_and_b32_e32 v97, 0xffff0000, v140
	v_lshlrev_b32_e32 v90, 16, v138
	v_and_b32_e32 v91, 0xffff0000, v138
	v_lshlrev_b32_e32 v92, 16, v139
	v_and_b32_e32 v93, 0xffff0000, v139
	v_lshlrev_b32_e32 v98, 16, v141
	v_and_b32_e32 v99, 0xffff0000, v141
	v_pk_fma_f32 v[88:89], v[92:93], s[30:31], v[88:89] op_sel_hi:[1,0,1]
	v_pk_fma_f32 v[86:87], v[90:91], s[30:31], v[86:87] op_sel_hi:[1,0,1]
	v_pk_fma_f32 v[90:91], v[98:99], s[30:31], v[80:81] op_sel_hi:[1,0,1]
	v_pk_fma_f32 v[80:81], v[96:97], s[30:31], v[78:79] op_sel_hi:[1,0,1]
	v_cvt_pk_bf16_f32 v78, v86, v87
	v_cvt_pk_bf16_f32 v79, v88, v89
	v_cvt_pk_bf16_f32 v80, v80, v81
	v_cvt_pk_bf16_f32 v81, v90, v91
	global_store_dwordx4 v[94:95], v[78:81], off offset:256 nt
	v_lshlrev_b32_e32 v86, 16, v136
	v_and_b32_e32 v87, 0xffff0000, v136
	v_lshlrev_b32_e32 v78, 16, v134
	v_and_b32_e32 v79, 0xffff0000, v134
	v_lshlrev_b32_e32 v80, 16, v135
	v_and_b32_e32 v81, 0xffff0000, v135
	v_lshlrev_b32_e32 v88, 16, v137
	v_and_b32_e32 v89, 0xffff0000, v137
	v_pk_fma_f32 v[78:79], v[78:79], s[30:31], v[82:83] op_sel_hi:[1,0,1]
	v_pk_fma_f32 v[80:81], v[80:81], s[30:31], v[84:85] op_sel_hi:[1,0,1]
	v_pk_fma_f32 v[82:83], v[88:89], s[30:31], v[76:77] op_sel_hi:[1,0,1]
	v_pk_fma_f32 v[76:77], v[86:87], s[30:31], v[74:75] op_sel_hi:[1,0,1]
	v_cvt_pk_bf16_f32 v74, v78, v79
	v_add_co_u32_e32 v78, vcc, s46, v122
	v_cvt_pk_bf16_f32 v75, v80, v81
	v_cvt_pk_bf16_f32 v76, v76, v77
	v_cvt_pk_bf16_f32 v77, v82, v83
	v_addc_co_u32_e32 v79, vcc, 0, v123, vcc
	global_store_dwordx4 v[78:79], v[74:77], off nt
	v_lshlrev_b32_e32 v80, 16, v132
	v_and_b32_e32 v81, 0xffff0000, v132
	v_lshlrev_b32_e32 v74, 16, v130
	v_and_b32_e32 v75, 0xffff0000, v130
	v_lshlrev_b32_e32 v76, 16, v131
	v_and_b32_e32 v77, 0xffff0000, v131
	v_lshlrev_b32_e32 v82, 16, v133
	v_and_b32_e32 v83, 0xffff0000, v133
	v_pk_fma_f32 v[72:73], v[76:77], s[30:31], v[72:73] op_sel_hi:[1,0,1]
	v_pk_fma_f32 v[70:71], v[74:75], s[30:31], v[70:71] op_sel_hi:[1,0,1]
	v_pk_fma_f32 v[74:75], v[82:83], s[30:31], v[68:69] op_sel_hi:[1,0,1]
	v_pk_fma_f32 v[68:69], v[80:81], s[30:31], v[66:67] op_sel_hi:[1,0,1]
	v_cvt_pk_bf16_f32 v66, v70, v71
	v_cvt_pk_bf16_f32 v67, v72, v73
	v_cvt_pk_bf16_f32 v68, v68, v69
	v_cvt_pk_bf16_f32 v69, v74, v75
	global_store_dwordx4 v[78:79], v[66:69], off offset:256 nt
	s_nop 1
	v_add_u32_e32 v66, 0x80, v173
	s_nop 0
	v_ashrrev_i32_e32 v67, 31, v66
	v_lshlrev_b64 v[66:67], 10, v[66:67]
	v_lshl_add_u64 v[66:67], v[66:67], 0, v[166:167]
	v_lshlrev_b64 v[98:99], 1, v[66:67]
	v_lshl_add_u64 v[90:91], s[12:13], 0, v[98:99]
	global_load_dwordx4 v[66:69], v[90:91], off
	global_load_dwordx4 v[70:73], v[90:91], off offset:256
	v_add_co_u32_e32 v78, vcc, s47, v90
	s_waitcnt vmcnt(0) lgkmcnt(0)
	v_lshlrev_b32_e32 v100, 16, v66
	v_addc_co_u32_e32 v79, vcc, 0, v91, vcc
	global_load_dwordx4 v[74:77], v[78:79], off
	s_nop 0
	global_load_dwordx4 v[78:81], v[78:79], off offset:256
	v_add_co_u32_e32 v86, vcc, s31, v90
	v_and_b32_e32 v101, 0xffff0000, v66
	s_nop 0
	v_addc_co_u32_e32 v87, vcc, 0, v91, vcc
	global_load_dwordx4 v[82:85], v[86:87], off
	s_nop 0
	global_load_dwordx4 v[86:89], v[86:87], off offset:256
	v_add_co_u32_e32 v94, vcc, s46, v90
	v_lshlrev_b32_e32 v66, 16, v67
	s_nop 0
	v_addc_co_u32_e32 v95, vcc, 0, v91, vcc
	global_load_dwordx4 v[90:93], v[94:95], off
	s_nop 0
	global_load_dwordx4 v[94:97], v[94:95], off offset:256
	v_and_b32_e32 v67, 0xffff0000, v67
	v_lshlrev_b32_e32 v102, 16, v68
	v_and_b32_e32 v103, 0xffff0000, v68
	v_lshlrev_b32_e32 v68, 16, v69
	v_and_b32_e32 v69, 0xffff0000, v69
	v_pk_fma_f32 v[64:65], v[66:67], s[30:31], v[64:65] op_sel_hi:[1,0,1]
	v_pk_fma_f32 v[62:63], v[100:101], s[30:31], v[62:63] op_sel_hi:[1,0,1]
	v_pk_fma_f32 v[66:67], v[68:69], s[30:31], v[60:61] op_sel_hi:[1,0,1]
	v_pk_fma_f32 v[60:61], v[102:103], s[30:31], v[58:59] op_sel_hi:[1,0,1]
	v_cvt_pk_bf16_f32 v58, v62, v63
	v_cvt_pk_bf16_f32 v59, v64, v65
	v_cvt_pk_bf16_f32 v60, v60, v61
	v_cvt_pk_bf16_f32 v61, v66, v67
	v_lshl_add_u64 v[62:63], s[24:25], 0, v[98:99]
	global_store_dwordx4 v[62:63], v[58:61], off nt
	v_lshlrev_b32_e32 v64, 16, v72
	v_and_b32_e32 v65, 0xffff0000, v72
	v_lshlrev_b32_e32 v58, 16, v70
	v_and_b32_e32 v59, 0xffff0000, v70
	v_lshlrev_b32_e32 v60, 16, v71
	v_and_b32_e32 v61, 0xffff0000, v71
	v_lshlrev_b32_e32 v66, 16, v73
	v_and_b32_e32 v67, 0xffff0000, v73
	v_pk_fma_f32 v[56:57], v[60:61], s[30:31], v[56:57] op_sel_hi:[1,0,1]
	v_pk_fma_f32 v[54:55], v[58:59], s[30:31], v[54:55] op_sel_hi:[1,0,1]
	v_pk_fma_f32 v[58:59], v[66:67], s[30:31], v[48:49] op_sel_hi:[1,0,1]
	v_pk_fma_f32 v[48:49], v[64:65], s[30:31], v[46:47] op_sel_hi:[1,0,1]
	v_cvt_pk_bf16_f32 v46, v54, v55
	v_cvt_pk_bf16_f32 v47, v56, v57
	v_cvt_pk_bf16_f32 v48, v48, v49
	v_cvt_pk_bf16_f32 v49, v58, v59
	global_store_dwordx4 v[62:63], v[46:49], off offset:256 nt
	s_waitcnt vmcnt(0) lgkmcnt(0)
	v_lshlrev_b32_e32 v54, 16, v76
	v_lshlrev_b32_e32 v46, 16, v74
	v_and_b32_e32 v47, 0xffff0000, v74
	v_lshlrev_b32_e32 v48, 16, v75
	v_and_b32_e32 v49, 0xffff0000, v75
	v_and_b32_e32 v55, 0xffff0000, v76
	v_lshlrev_b32_e32 v56, 16, v77
	v_and_b32_e32 v57, 0xffff0000, v77
	v_pk_fma_f32 v[46:47], v[46:47], s[30:31], v[50:51] op_sel_hi:[1,0,1]
	v_pk_fma_f32 v[48:49], v[48:49], s[30:31], v[52:53] op_sel_hi:[1,0,1]
	v_pk_fma_f32 v[50:51], v[56:57], s[30:31], v[44:45] op_sel_hi:[1,0,1]
	v_pk_fma_f32 v[44:45], v[54:55], s[30:31], v[42:43] op_sel_hi:[1,0,1]
	v_cvt_pk_bf16_f32 v42, v46, v47
	v_add_co_u32_e32 v46, vcc, s47, v62
	v_cvt_pk_bf16_f32 v43, v48, v49
	v_cvt_pk_bf16_f32 v44, v44, v45
	v_cvt_pk_bf16_f32 v45, v50, v51
	v_addc_co_u32_e32 v47, vcc, 0, v63, vcc
	global_store_dwordx4 v[46:47], v[42:45], off nt
	v_lshlrev_b32_e32 v48, 16, v80
	v_and_b32_e32 v49, 0xffff0000, v80
	v_lshlrev_b32_e32 v42, 16, v78
	v_and_b32_e32 v43, 0xffff0000, v78
	v_lshlrev_b32_e32 v44, 16, v79
	v_and_b32_e32 v45, 0xffff0000, v79
	v_lshlrev_b32_e32 v50, 16, v81
	v_and_b32_e32 v51, 0xffff0000, v81
	v_pk_fma_f32 v[40:41], v[44:45], s[30:31], v[40:41] op_sel_hi:[1,0,1]
	v_pk_fma_f32 v[38:39], v[42:43], s[30:31], v[38:39] op_sel_hi:[1,0,1]
	v_pk_fma_f32 v[42:43], v[50:51], s[30:31], v[32:33] op_sel_hi:[1,0,1]
	v_pk_fma_f32 v[32:33], v[48:49], s[30:31], v[30:31] op_sel_hi:[1,0,1]
	v_cvt_pk_bf16_f32 v30, v38, v39
	v_cvt_pk_bf16_f32 v31, v40, v41
	v_cvt_pk_bf16_f32 v32, v32, v33
	v_cvt_pk_bf16_f32 v33, v42, v43
	global_store_dwordx4 v[46:47], v[30:33], off offset:256 nt
	v_lshlrev_b32_e32 v38, 16, v84
	v_and_b32_e32 v39, 0xffff0000, v84
	v_lshlrev_b32_e32 v30, 16, v82
	v_and_b32_e32 v31, 0xffff0000, v82
	v_lshlrev_b32_e32 v32, 16, v83
	v_and_b32_e32 v33, 0xffff0000, v83
	v_lshlrev_b32_e32 v40, 16, v85
	v_and_b32_e32 v41, 0xffff0000, v85
	v_pk_fma_f32 v[30:31], v[30:31], s[30:31], v[34:35] op_sel_hi:[1,0,1]
	v_pk_fma_f32 v[32:33], v[32:33], s[30:31], v[36:37] op_sel_hi:[1,0,1]
	v_pk_fma_f32 v[34:35], v[40:41], s[30:31], v[28:29] op_sel_hi:[1,0,1]
	v_pk_fma_f32 v[28:29], v[38:39], s[30:31], v[26:27] op_sel_hi:[1,0,1]
	v_cvt_pk_bf16_f32 v26, v30, v31
	v_add_co_u32_e32 v30, vcc, s31, v62
	v_cvt_pk_bf16_f32 v27, v32, v33
	v_cvt_pk_bf16_f32 v28, v28, v29
	v_cvt_pk_bf16_f32 v29, v34, v35
	v_addc_co_u32_e32 v31, vcc, 0, v63, vcc
	global_store_dwordx4 v[30:31], v[26:29], off nt
	v_lshlrev_b32_e32 v32, 16, v88
	v_and_b32_e32 v33, 0xffff0000, v88
	v_lshlrev_b32_e32 v26, 16, v86
	v_and_b32_e32 v27, 0xffff0000, v86
	v_lshlrev_b32_e32 v28, 16, v87
	v_and_b32_e32 v29, 0xffff0000, v87
	v_lshlrev_b32_e32 v34, 16, v89
	v_and_b32_e32 v35, 0xffff0000, v89
	v_pk_fma_f32 v[24:25], v[28:29], s[30:31], v[24:25] op_sel_hi:[1,0,1]
	v_pk_fma_f32 v[22:23], v[26:27], s[30:31], v[22:23] op_sel_hi:[1,0,1]
	v_pk_fma_f32 v[26:27], v[34:35], s[30:31], v[16:17] op_sel_hi:[1,0,1]
	v_pk_fma_f32 v[16:17], v[32:33], s[30:31], v[14:15] op_sel_hi:[1,0,1]
	v_cvt_pk_bf16_f32 v14, v22, v23
	v_cvt_pk_bf16_f32 v15, v24, v25
	v_cvt_pk_bf16_f32 v16, v16, v17
	v_cvt_pk_bf16_f32 v17, v26, v27
	global_store_dwordx4 v[30:31], v[14:17], off offset:256 nt
	v_lshlrev_b32_e32 v22, 16, v92
	v_and_b32_e32 v23, 0xffff0000, v92
	v_lshlrev_b32_e32 v14, 16, v90
	v_and_b32_e32 v15, 0xffff0000, v90
	v_lshlrev_b32_e32 v16, 16, v91
	v_and_b32_e32 v17, 0xffff0000, v91
	v_lshlrev_b32_e32 v24, 16, v93
	v_and_b32_e32 v25, 0xffff0000, v93
	v_pk_fma_f32 v[14:15], v[14:15], s[30:31], v[18:19] op_sel_hi:[1,0,1]
	v_pk_fma_f32 v[16:17], v[16:17], s[30:31], v[20:21] op_sel_hi:[1,0,1]
	v_pk_fma_f32 v[18:19], v[24:25], s[30:31], v[12:13] op_sel_hi:[1,0,1]
	v_pk_fma_f32 v[12:13], v[22:23], s[30:31], v[10:11] op_sel_hi:[1,0,1]
	v_cvt_pk_bf16_f32 v10, v14, v15
	v_add_co_u32_e32 v14, vcc, s46, v62
	v_cvt_pk_bf16_f32 v11, v16, v17
	v_cvt_pk_bf16_f32 v12, v12, v13
	v_cvt_pk_bf16_f32 v13, v18, v19
	v_addc_co_u32_e32 v15, vcc, 0, v63, vcc
	global_store_dwordx4 v[14:15], v[10:13], off nt
	v_lshlrev_b32_e32 v16, 16, v96
	v_and_b32_e32 v17, 0xffff0000, v96
	v_lshlrev_b32_e32 v10, 16, v94
	v_and_b32_e32 v11, 0xffff0000, v94
	v_lshlrev_b32_e32 v12, 16, v95
	v_and_b32_e32 v13, 0xffff0000, v95
	v_lshlrev_b32_e32 v18, 16, v97
	v_and_b32_e32 v19, 0xffff0000, v97
	v_pk_fma_f32 v[8:9], v[12:13], s[30:31], v[8:9] op_sel_hi:[1,0,1]
	v_pk_fma_f32 v[6:7], v[10:11], s[30:31], v[6:7] op_sel_hi:[1,0,1]
	v_pk_fma_f32 v[10:11], v[18:19], s[30:31], v[4:5] op_sel_hi:[1,0,1]
	v_pk_fma_f32 v[4:5], v[16:17], s[30:31], v[2:3] op_sel_hi:[1,0,1]
	v_cvt_pk_bf16_f32 v2, v6, v7
	v_cvt_pk_bf16_f32 v3, v8, v9
	v_cvt_pk_bf16_f32 v4, v4, v5
	v_cvt_pk_bf16_f32 v5, v10, v11
	s_and_b64 vcc, exec, s[34:35]
	global_store_dwordx4 v[14:15], v[2:5], off offset:256 nt
	s_cbranch_vccz .LBB0_1046
	s_waitcnt vmcnt(0)
	s_cmpk_gt_u32 s4, 0xff
	s_cbranch_scc1 .LBB0_1051
	s_barrier

.LBB0_1786:
	ds_read_b128 v[130:133], v168
	ds_read_b128 v[134:137], v168 offset:1024
	ds_read_b128 v[138:141], v168 offset:2048
	ds_read_b128 v[142:145], v168 offset:3072
	s_add_u32 s0, s38, 0xfffc0080
	s_addc_u32 s1, s39, -1
	s_cmp_eq_u32 s66, 12
	s_cselect_b32 s43, s60, s1
	s_cselect_b32 s42, s61, s0
	s_cselect_b32 s41, s62, s65
	s_cselect_b32 s40, s63, s64
	s_mov_b32 m0, s50
	v_lshl_add_u64 v[164:165], s[38:39], 0, v[162:163]
	ds_read_b128 v[146:149], v169
	ds_read_b128 v[172:175], v169 offset:1024
	ds_read_b128 v[176:179], v169 offset:2048
	ds_read_b128 v[180:183], v169 offset:3072
	ds_read_b128 v[184:187], v169 offset:4096
	ds_read_b128 v[188:191], v169 offset:5120
	ds_read_b128 v[192:195], v169 offset:6144
	ds_read_b128 v[196:199], v169 offset:7168
	global_load_lds_dwordx4 v[164:165], off
	v_lshl_add_u64 v[164:165], s[38:39], 0, v[160:161]
	s_mov_b32 m0, s51
	s_nop 0
	global_load_lds_dwordx4 v[164:165], off
	s_waitcnt lgkmcnt(8)
	s_waitcnt vmcnt(10)
	s_barrier
	s_waitcnt lgkmcnt(0)
	s_waitcnt lgkmcnt(0)
	v_mfma_f32_16x16x32_bf16 v[126:129], v[130:133], v[146:149], v[126:129]
	v_mfma_f32_16x16x32_bf16 v[122:125], v[138:141], v[146:149], v[122:125]
	v_mfma_f32_16x16x32_bf16 v[118:121], v[130:133], v[176:179], v[118:121]
	v_mfma_f32_16x16x32_bf16 v[110:113], v[138:141], v[176:179], v[110:113]
	v_mfma_f32_16x16x32_bf16 v[98:101], v[130:133], v[184:187], v[98:101]
	v_mfma_f32_16x16x32_bf16 v[90:93], v[138:141], v[184:187], v[90:93]
	v_mfma_f32_16x16x32_bf16 v[82:85], v[130:133], v[192:195], v[82:85]
	v_mfma_f32_16x16x32_bf16 v[74:77], v[138:141], v[192:195], v[74:77]
	v_mfma_f32_16x16x32_bf16 v[126:129], v[134:137], v[172:175], v[126:129]
	v_mfma_f32_16x16x32_bf16 v[122:125], v[142:145], v[172:175], v[122:125]
	v_mfma_f32_16x16x32_bf16 v[118:121], v[134:137], v[180:183], v[118:121]
	v_mfma_f32_16x16x32_bf16 v[110:113], v[142:145], v[180:183], v[110:113]
	v_mfma_f32_16x16x32_bf16 v[98:101], v[134:137], v[188:191], v[98:101]
	v_mfma_f32_16x16x32_bf16 v[90:93], v[142:145], v[188:191], v[90:93]
	v_mfma_f32_16x16x32_bf16 v[82:85], v[134:137], v[196:199], v[82:85]
	v_mfma_f32_16x16x32_bf16 v[74:77], v[142:145], v[196:199], v[74:77]
	s_barrier
	s_mov_b32 m0, s52
	v_lshl_add_u64 v[164:165], s[40:41], 0, v[156:157]
	ds_read_b128 v[200:203], v170
	ds_read_b128 v[204:207], v170 offset:1024
	ds_read_b128 v[208:211], v170 offset:2048
	ds_read_b128 v[212:215], v170 offset:3072
	global_load_lds_dwordx4 v[164:165], off
	v_lshl_add_u64 v[216:217], s[40:41], 0, v[152:153]
	s_mov_b32 m0, s53
	s_nop 0
	global_load_lds_dwordx4 v[216:217], off
	s_waitcnt vmcnt(10)
	s_barrier
	s_waitcnt lgkmcnt(0)
	s_waitcnt lgkmcnt(0)
	v_mfma_f32_16x16x32_bf16 v[114:117], v[200:203], v[146:149], v[114:117]
	v_mfma_f32_16x16x32_bf16 v[106:109], v[208:211], v[146:149], v[106:109]
	v_mfma_f32_16x16x32_bf16 v[102:105], v[200:203], v[176:179], v[102:105]
	v_mfma_f32_16x16x32_bf16 v[94:97], v[208:211], v[176:179], v[94:97]
	v_mfma_f32_16x16x32_bf16 v[86:89], v[200:203], v[184:187], v[86:89]
	v_mfma_f32_16x16x32_bf16 v[78:81], v[208:211], v[184:187], v[78:81]
	v_mfma_f32_16x16x32_bf16 v[70:73], v[200:203], v[192:195], v[70:73]
	v_mfma_f32_16x16x32_bf16 v[66:69], v[208:211], v[192:195], v[66:69]
	v_mfma_f32_16x16x32_bf16 v[114:117], v[204:207], v[172:175], v[114:117]
	v_mfma_f32_16x16x32_bf16 v[106:109], v[212:215], v[172:175], v[106:109]
	v_mfma_f32_16x16x32_bf16 v[102:105], v[204:207], v[180:183], v[102:105]
	v_mfma_f32_16x16x32_bf16 v[94:97], v[212:215], v[180:183], v[94:97]
	v_mfma_f32_16x16x32_bf16 v[86:89], v[204:207], v[188:191], v[86:89]
	v_mfma_f32_16x16x32_bf16 v[78:81], v[212:215], v[188:191], v[78:81]
	v_mfma_f32_16x16x32_bf16 v[70:73], v[204:207], v[196:199], v[70:73]
	v_mfma_f32_16x16x32_bf16 v[66:69], v[212:215], v[196:199], v[66:69]
	s_mov_b32 m0, s8
	v_lshl_add_u64 v[218:219], s[42:43], 0, v[158:159]
	s_barrier
	ds_read_b128 v[146:149], v169 offset:16384
	ds_read_b128 v[172:175], v169 offset:17408
	ds_read_b128 v[176:179], v169 offset:18432
	ds_read_b128 v[180:183], v169 offset:19456
	ds_read_b128 v[184:187], v169 offset:20480
	ds_read_b128 v[188:191], v169 offset:21504
	ds_read_b128 v[192:195], v169 offset:22528
	ds_read_b128 v[196:199], v169 offset:23552
	global_load_lds_dwordx4 v[218:219], off
	v_lshl_add_u64 v[220:221], s[42:43], 0, v[154:155]
	s_mov_b32 m0, s9
	s_nop 0
	global_load_lds_dwordx4 v[220:221], off
	s_waitcnt vmcnt(10)
	s_barrier
	s_waitcnt lgkmcnt(0)
	s_waitcnt lgkmcnt(0)
	v_mfma_f32_16x16x32_bf16 v[62:65], v[130:133], v[146:149], v[62:65]
	v_mfma_f32_16x16x32_bf16 v[58:61], v[138:141], v[146:149], v[58:61]
	v_mfma_f32_16x16x32_bf16 v[50:53], v[130:133], v[176:179], v[50:53]
	v_mfma_f32_16x16x32_bf16 v[42:45], v[138:141], v[176:179], v[42:45]
	v_mfma_f32_16x16x32_bf16 v[34:37], v[130:133], v[184:187], v[34:37]
	v_mfma_f32_16x16x32_bf16 v[26:29], v[138:141], v[184:187], v[26:29]
	v_mfma_f32_16x16x32_bf16 v[18:21], v[130:133], v[192:195], v[18:21]
	v_mfma_f32_16x16x32_bf16 v[10:13], v[138:141], v[192:195], v[10:13]
	v_mfma_f32_16x16x32_bf16 v[62:65], v[134:137], v[172:175], v[62:65]
	v_mfma_f32_16x16x32_bf16 v[58:61], v[142:145], v[172:175], v[58:61]
	v_mfma_f32_16x16x32_bf16 v[50:53], v[134:137], v[180:183], v[50:53]
	v_mfma_f32_16x16x32_bf16 v[42:45], v[142:145], v[180:183], v[42:45]
	v_mfma_f32_16x16x32_bf16 v[34:37], v[134:137], v[188:191], v[34:37]
	v_mfma_f32_16x16x32_bf16 v[26:29], v[142:145], v[188:191], v[26:29]
	v_mfma_f32_16x16x32_bf16 v[18:21], v[134:137], v[196:199], v[18:21]
	v_mfma_f32_16x16x32_bf16 v[10:13], v[142:145], v[196:199], v[10:13]
	s_barrier
	s_add_u32 s0, s40, 0x40000
	s_addc_u32 s1, s41, 0
	s_mov_b32 m0, s54
	v_lshl_add_u64 v[130:131], s[0:1], 0, v[156:157]
	global_load_lds_dwordx4 v[130:131], off
	v_lshl_add_u64 v[130:131], s[0:1], 0, v[152:153]
	s_add_i32 m0, s54, 0x2000
	s_nop 0
	global_load_lds_dwordx4 v[130:131], off
	s_waitcnt vmcnt(10)
	s_barrier
	v_mfma_f32_16x16x32_bf16 v[54:57], v[200:203], v[146:149], v[54:57]
	v_mfma_f32_16x16x32_bf16 v[46:49], v[208:211], v[146:149], v[46:49]
	v_mfma_f32_16x16x32_bf16 v[38:41], v[200:203], v[176:179], v[38:41]
	v_mfma_f32_16x16x32_bf16 v[30:33], v[208:211], v[176:179], v[30:33]
	v_mfma_f32_16x16x32_bf16 v[22:25], v[200:203], v[184:187], v[22:25]
	v_mfma_f32_16x16x32_bf16 v[14:17], v[208:211], v[184:187], v[14:17]
	v_mfma_f32_16x16x32_bf16 v[6:9], v[200:203], v[192:195], v[6:9]
	v_mfma_f32_16x16x32_bf16 v[2:5], v[208:211], v[192:195], v[2:5]
	v_mfma_f32_16x16x32_bf16 v[54:57], v[204:207], v[172:175], v[54:57]
	v_mfma_f32_16x16x32_bf16 v[46:49], v[212:215], v[172:175], v[46:49]
	v_mfma_f32_16x16x32_bf16 v[38:41], v[204:207], v[180:183], v[38:41]
	v_mfma_f32_16x16x32_bf16 v[30:33], v[212:215], v[180:183], v[30:33]
	v_mfma_f32_16x16x32_bf16 v[22:25], v[204:207], v[188:191], v[22:25]
	v_mfma_f32_16x16x32_bf16 v[14:17], v[212:215], v[188:191], v[14:17]
	v_mfma_f32_16x16x32_bf16 v[6:9], v[204:207], v[196:199], v[6:9]
	v_mfma_f32_16x16x32_bf16 v[2:5], v[212:215], v[196:199], v[2:5]
	s_add_i32 s67, 0, 0x18000
	v_add_u32_e32 v142, s67, v167
	s_barrier
	ds_read_b128 v[130:133], v142
	ds_read_b128 v[134:137], v142 offset:1024
	ds_read_b128 v[138:141], v142 offset:2048
	ds_read_b128 v[142:145], v142 offset:3072
	s_add_u32 s0, s42, 0x40000
	s_addc_u32 s1, s43, 0
	s_mov_b32 m0, s10
	v_lshl_add_u64 v[200:201], s[0:1], 0, v[158:159]
	ds_read_b128 v[146:149], v169 offset:32768
	ds_read_b128 v[172:175], v169 offset:33792
	ds_read_b128 v[176:179], v169 offset:34816
	ds_read_b128 v[180:183], v169 offset:35840
	ds_read_b128 v[184:187], v169 offset:36864
	ds_read_b128 v[188:191], v169 offset:37888
	ds_read_b128 v[192:195], v169 offset:38912
	ds_read_b128 v[196:199], v169 offset:39936
	global_load_lds_dwordx4 v[200:201], off
	v_lshl_add_u64 v[200:201], s[0:1], 0, v[154:155]
	s_mov_b32 m0, s11
	s_nop 0
	global_load_lds_dwordx4 v[200:201], off
	s_waitcnt lgkmcnt(8)
	s_waitcnt vmcnt(10)
	s_barrier
	s_waitcnt lgkmcnt(0)
	s_waitcnt lgkmcnt(0)
	v_mfma_f32_16x16x32_bf16 v[126:129], v[130:133], v[146:149], v[126:129]
	v_mfma_f32_16x16x32_bf16 v[122:125], v[138:141], v[146:149], v[122:125]
	v_mfma_f32_16x16x32_bf16 v[118:121], v[130:133], v[176:179], v[118:121]
	v_mfma_f32_16x16x32_bf16 v[110:113], v[138:141], v[176:179], v[110:113]
	v_mfma_f32_16x16x32_bf16 v[98:101], v[130:133], v[184:187], v[98:101]
	v_mfma_f32_16x16x32_bf16 v[90:93], v[138:141], v[184:187], v[90:93]
	v_mfma_f32_16x16x32_bf16 v[82:85], v[130:133], v[192:195], v[82:85]
	v_mfma_f32_16x16x32_bf16 v[74:77], v[138:141], v[192:195], v[74:77]
	v_mfma_f32_16x16x32_bf16 v[126:129], v[134:137], v[172:175], v[126:129]
	v_mfma_f32_16x16x32_bf16 v[122:125], v[142:145], v[172:175], v[122:125]
	v_mfma_f32_16x16x32_bf16 v[118:121], v[134:137], v[180:183], v[118:121]
	v_mfma_f32_16x16x32_bf16 v[110:113], v[142:145], v[180:183], v[110:113]
	v_mfma_f32_16x16x32_bf16 v[98:101], v[134:137], v[188:191], v[98:101]
	v_mfma_f32_16x16x32_bf16 v[90:93], v[142:145], v[188:191], v[90:93]
	v_mfma_f32_16x16x32_bf16 v[82:85], v[134:137], v[196:199], v[82:85]
	v_mfma_f32_16x16x32_bf16 v[74:77], v[142:145], v[196:199], v[74:77]
	s_barrier
	s_add_i32 s42, 0, 0x1c000
	s_add_i32 s0, s67, s7
	v_add_u32_e32 v171, s42, v167
	v_lshl_add_u64 v[164:165], v[164:165], 0, s[28:29]
	s_mov_b32 m0, s0
	ds_read_b128 v[200:203], v171
	ds_read_b128 v[204:207], v171 offset:1024
	ds_read_b128 v[208:211], v171 offset:2048
	ds_read_b128 v[212:215], v171 offset:3072
	global_load_lds_dwordx4 v[164:165], off
	v_lshl_add_u64 v[164:165], v[216:217], 0, s[28:29]
	s_add_i32 m0, s0, 0x2000
	s_nop 0
	global_load_lds_dwordx4 v[164:165], off
	s_waitcnt vmcnt(10)
	s_barrier
	s_waitcnt lgkmcnt(0)
	s_waitcnt lgkmcnt(0)
	v_mfma_f32_16x16x32_bf16 v[114:117], v[200:203], v[146:149], v[114:117]
	v_mfma_f32_16x16x32_bf16 v[106:109], v[208:211], v[146:149], v[106:109]
	v_mfma_f32_16x16x32_bf16 v[102:105], v[200:203], v[176:179], v[102:105]
	v_mfma_f32_16x16x32_bf16 v[94:97], v[208:211], v[176:179], v[94:97]
	v_mfma_f32_16x16x32_bf16 v[86:89], v[200:203], v[184:187], v[86:89]
	v_mfma_f32_16x16x32_bf16 v[78:81], v[208:211], v[184:187], v[78:81]
	v_mfma_f32_16x16x32_bf16 v[70:73], v[200:203], v[192:195], v[70:73]
	v_mfma_f32_16x16x32_bf16 v[66:69], v[208:211], v[192:195], v[66:69]
	v_mfma_f32_16x16x32_bf16 v[114:117], v[204:207], v[172:175], v[114:117]
	v_mfma_f32_16x16x32_bf16 v[106:109], v[212:215], v[172:175], v[106:109]
	v_mfma_f32_16x16x32_bf16 v[102:105], v[204:207], v[180:183], v[102:105]
	v_mfma_f32_16x16x32_bf16 v[94:97], v[212:215], v[180:183], v[94:97]
	v_mfma_f32_16x16x32_bf16 v[86:89], v[204:207], v[188:191], v[86:89]
	v_mfma_f32_16x16x32_bf16 v[78:81], v[212:215], v[188:191], v[78:81]
	v_mfma_f32_16x16x32_bf16 v[70:73], v[204:207], v[196:199], v[70:73]
	v_mfma_f32_16x16x32_bf16 v[66:69], v[212:215], v[196:199], v[66:69]
	s_mov_b32 m0, s48
	v_lshl_add_u64 v[164:165], v[218:219], 0, s[28:29]
	s_barrier
	ds_read_b128 v[146:149], v169 offset:49152
	ds_read_b128 v[172:175], v169 offset:50176
	ds_read_b128 v[176:179], v169 offset:51200
	ds_read_b128 v[180:183], v169 offset:52224
	ds_read_b128 v[184:187], v169 offset:53248
	ds_read_b128 v[188:191], v169 offset:54272
	ds_read_b128 v[192:195], v169 offset:55296
	ds_read_b128 v[196:199], v169 offset:56320
	global_load_lds_dwordx4 v[164:165], off
	v_lshl_add_u64 v[164:165], v[220:221], 0, s[28:29]
	s_mov_b32 m0, s49
	s_nop 0
	global_load_lds_dwordx4 v[164:165], off
	s_waitcnt vmcnt(10)
	s_barrier
	s_waitcnt lgkmcnt(0)
	s_waitcnt lgkmcnt(0)
	v_mfma_f32_16x16x32_bf16 v[62:65], v[130:133], v[146:149], v[62:65]
	v_mfma_f32_16x16x32_bf16 v[58:61], v[138:141], v[146:149], v[58:61]
	v_mfma_f32_16x16x32_bf16 v[50:53], v[130:133], v[176:179], v[50:53]
	v_mfma_f32_16x16x32_bf16 v[42:45], v[138:141], v[176:179], v[42:45]
	v_mfma_f32_16x16x32_bf16 v[34:37], v[130:133], v[184:187], v[34:37]
	v_mfma_f32_16x16x32_bf16 v[26:29], v[138:141], v[184:187], v[26:29]
	v_mfma_f32_16x16x32_bf16 v[18:21], v[130:133], v[192:195], v[18:21]
	v_mfma_f32_16x16x32_bf16 v[10:13], v[138:141], v[192:195], v[10:13]
	v_mfma_f32_16x16x32_bf16 v[62:65], v[134:137], v[172:175], v[62:65]
	v_mfma_f32_16x16x32_bf16 v[58:61], v[142:145], v[172:175], v[58:61]
	v_mfma_f32_16x16x32_bf16 v[50:53], v[134:137], v[180:183], v[50:53]
	v_mfma_f32_16x16x32_bf16 v[42:45], v[142:145], v[180:183], v[42:45]
	v_mfma_f32_16x16x32_bf16 v[34:37], v[134:137], v[188:191], v[34:37]
	v_mfma_f32_16x16x32_bf16 v[26:29], v[142:145], v[188:191], v[26:29]
	v_mfma_f32_16x16x32_bf16 v[18:21], v[134:137], v[196:199], v[18:21]
	v_mfma_f32_16x16x32_bf16 v[10:13], v[142:145], v[196:199], v[10:13]
	s_barrier
	s_add_u32 s0, s40, 0x40080
	s_addc_u32 s1, s41, 0
	s_add_i32 s40, s42, s7
	v_lshl_add_u64 v[130:131], s[0:1], 0, v[156:157]
	s_mov_b32 m0, s40
	s_nop 0
	global_load_lds_dwordx4 v[130:131], off
	v_lshl_add_u64 v[130:131], s[0:1], 0, v[152:153]
	s_add_i32 m0, s40, 0x2000
	s_nop 0
	global_load_lds_dwordx4 v[130:131], off
	s_waitcnt vmcnt(10)
	s_barrier
	v_mfma_f32_16x16x32_bf16 v[54:57], v[200:203], v[146:149], v[54:57]
	v_mfma_f32_16x16x32_bf16 v[46:49], v[208:211], v[146:149], v[46:49]
	v_mfma_f32_16x16x32_bf16 v[38:41], v[200:203], v[176:179], v[38:41]
	v_mfma_f32_16x16x32_bf16 v[30:33], v[208:211], v[176:179], v[30:33]
	v_mfma_f32_16x16x32_bf16 v[22:25], v[200:203], v[184:187], v[22:25]
	v_mfma_f32_16x16x32_bf16 v[14:17], v[208:211], v[184:187], v[14:17]
	v_mfma_f32_16x16x32_bf16 v[6:9], v[200:203], v[192:195], v[6:9]
	v_mfma_f32_16x16x32_bf16 v[2:5], v[208:211], v[192:195], v[2:5]
	v_mfma_f32_16x16x32_bf16 v[54:57], v[204:207], v[172:175], v[54:57]
	v_mfma_f32_16x16x32_bf16 v[46:49], v[212:215], v[172:175], v[46:49]
	v_mfma_f32_16x16x32_bf16 v[38:41], v[204:207], v[180:183], v[38:41]
	v_mfma_f32_16x16x32_bf16 v[30:33], v[212:215], v[180:183], v[30:33]
	v_mfma_f32_16x16x32_bf16 v[22:25], v[204:207], v[188:191], v[22:25]
	v_mfma_f32_16x16x32_bf16 v[14:17], v[212:215], v[188:191], v[14:17]
	v_mfma_f32_16x16x32_bf16 v[6:9], v[204:207], v[196:199], v[6:9]
	v_mfma_f32_16x16x32_bf16 v[2:5], v[212:215], v[196:199], v[2:5]
	s_add_i32 s66, s66, 2
	s_add_u32 s64, s64, 0x100
	s_addc_u32 s65, s65, 0
	s_add_u32 s38, s38, 0x100
	s_addc_u32 s39, s39, 0
	s_cmp_gt_u32 s66, 13
	s_barrier
	s_cbranch_scc0 .LBB0_1786
	s_lshl_b32 s0, s58, 8
	v_mov_b32_e32 v130, v151
	v_mov_b32_e32 v131, v166
	s_or_b32 s0, s0, s45
	s_mov_b32 s58, s57
	v_lshl_add_u32 v164, v131, 3, s0
	s_lshl_b32 s0, s59, 8
	s_add_i32 s0, s0, s44
	v_add_u32_e32 v171, s0, v130
	v_mov_b32_e32 v130, v171
	v_ashrrev_i32_e32 v165, 31, v164
	v_ashrrev_i32_e32 v131, 31, v130
	v_lshlrev_b64 v[130:131], 10, v[130:131]
	v_lshl_add_u64 v[130:131], v[130:131], 0, v[164:165]
	v_lshlrev_b64 v[184:185], 1, v[130:131]
	v_lshl_add_u64 v[130:131], s[14:15], 0, v[184:185]
	global_load_dwordx4 v[172:175], v[130:131], off
	global_load_dwordx4 v[176:179], v[130:131], off offset:256
	v_add_co_u32_e32 v132, vcc, s47, v130
	s_mov_b32 s59, s56
	s_nop 0
	v_addc_co_u32_e32 v133, vcc, 0, v131, vcc
	global_load_dwordx4 v[180:183], v[132:133], off
	global_load_dwordx4 v[146:149], v[132:133], off offset:256
	v_add_co_u32_e32 v132, vcc, s31, v130
	s_waitcnt vmcnt(0) lgkmcnt(0)
	v_lshlrev_b32_e32 v186, 16, v172
	v_addc_co_u32_e32 v133, vcc, 0, v131, vcc
	global_load_dwordx4 v[142:145], v[132:133], off
	global_load_dwordx4 v[138:141], v[132:133], off offset:256
	v_add_co_u32_e32 v130, vcc, s46, v130
	v_and_b32_e32 v187, 0xffff0000, v172
	s_nop 0
	v_addc_co_u32_e32 v131, vcc, 0, v131, vcc
	global_load_dwordx4 v[134:137], v[130:131], off
	s_nop 0
	global_load_dwordx4 v[130:133], v[130:131], off offset:256
	v_lshlrev_b32_e32 v172, 16, v173
	v_and_b32_e32 v173, 0xffff0000, v173
	v_lshlrev_b32_e32 v188, 16, v174
	v_and_b32_e32 v189, 0xffff0000, v174
	v_lshlrev_b32_e32 v174, 16, v175
	v_and_b32_e32 v175, 0xffff0000, v175
	v_pk_fma_f32 v[128:129], v[172:173], s[30:31], v[128:129] op_sel_hi:[1,0,1]
	v_pk_fma_f32 v[126:127], v[186:187], s[30:31], v[126:127] op_sel_hi:[1,0,1]
	v_pk_fma_f32 v[172:173], v[174:175], s[30:31], v[124:125] op_sel_hi:[1,0,1]
	v_pk_fma_f32 v[122:123], v[188:189], s[30:31], v[122:123] op_sel_hi:[1,0,1]
	v_cvt_pk_bf16_f32 v124, v126, v127
	v_cvt_pk_bf16_f32 v125, v128, v129
	v_cvt_pk_bf16_f32 v126, v122, v123
	v_cvt_pk_bf16_f32 v127, v172, v173
	v_lshl_add_u64 v[122:123], s[20:21], 0, v[184:185]
	global_store_dwordx4 v[122:123], v[124:127], off nt
	v_lshlrev_b32_e32 v128, 16, v178
	v_and_b32_e32 v129, 0xffff0000, v178
	v_lshlrev_b32_e32 v124, 16, v176
	v_and_b32_e32 v125, 0xffff0000, v176
	v_lshlrev_b32_e32 v126, 16, v177
	v_and_b32_e32 v127, 0xffff0000, v177
	v_lshlrev_b32_e32 v172, 16, v179
	v_and_b32_e32 v173, 0xffff0000, v179
	v_pk_fma_f32 v[116:117], v[126:127], s[30:31], v[116:117] op_sel_hi:[1,0,1]
	v_pk_fma_f32 v[114:115], v[124:125], s[30:31], v[114:115] op_sel_hi:[1,0,1]
	v_pk_fma_f32 v[124:125], v[172:173], s[30:31], v[108:109] op_sel_hi:[1,0,1]
	v_pk_fma_f32 v[108:109], v[128:129], s[30:31], v[106:107] op_sel_hi:[1,0,1]
	v_cvt_pk_bf16_f32 v106, v114, v115
	v_cvt_pk_bf16_f32 v107, v116, v117
	v_cvt_pk_bf16_f32 v108, v108, v109
	v_cvt_pk_bf16_f32 v109, v124, v125
	global_store_dwordx4 v[122:123], v[106:109], off offset:256 nt
	v_lshlrev_b32_e32 v114, 16, v182
	v_and_b32_e32 v115, 0xffff0000, v182
	v_lshlrev_b32_e32 v106, 16, v180
	v_and_b32_e32 v107, 0xffff0000, v180
	v_lshlrev_b32_e32 v108, 16, v181
	v_and_b32_e32 v109, 0xffff0000, v181
	v_lshlrev_b32_e32 v116, 16, v183
	v_and_b32_e32 v117, 0xffff0000, v183
	v_pk_fma_f32 v[108:109], v[108:109], s[30:31], v[120:121] op_sel_hi:[1,0,1]
	v_pk_fma_f32 v[106:107], v[106:107], s[30:31], v[118:119] op_sel_hi:[1,0,1]
	v_pk_fma_f32 v[110:111], v[114:115], s[30:31], v[110:111] op_sel_hi:[1,0,1]
	v_pk_fma_f32 v[112:113], v[116:117], s[30:31], v[112:113] op_sel_hi:[1,0,1]
	v_cvt_pk_bf16_f32 v106, v106, v107
	v_cvt_pk_bf16_f32 v107, v108, v109
	v_cvt_pk_bf16_f32 v108, v110, v111
	v_add_co_u32_e32 v110, vcc, s47, v122
	v_cvt_pk_bf16_f32 v109, v112, v113
	s_nop 0
	v_addc_co_u32_e32 v111, vcc, 0, v123, vcc
	global_store_dwordx4 v[110:111], v[106:109], off nt
	v_lshlrev_b32_e32 v112, 16, v148
	v_and_b32_e32 v113, 0xffff0000, v148
	v_lshlrev_b32_e32 v106, 16, v146
	v_and_b32_e32 v107, 0xffff0000, v146
	v_lshlrev_b32_e32 v108, 16, v147
	v_and_b32_e32 v109, 0xffff0000, v147
	v_lshlrev_b32_e32 v114, 16, v149
	v_and_b32_e32 v115, 0xffff0000, v149
	v_pk_fma_f32 v[104:105], v[108:109], s[30:31], v[104:105] op_sel_hi:[1,0,1]
	v_pk_fma_f32 v[102:103], v[106:107], s[30:31], v[102:103] op_sel_hi:[1,0,1]
	v_pk_fma_f32 v[106:107], v[114:115], s[30:31], v[96:97] op_sel_hi:[1,0,1]
	v_pk_fma_f32 v[96:97], v[112:113], s[30:31], v[94:95] op_sel_hi:[1,0,1]
	v_cvt_pk_bf16_f32 v94, v102, v103
	v_cvt_pk_bf16_f32 v95, v104, v105
	v_cvt_pk_bf16_f32 v96, v96, v97
	v_cvt_pk_bf16_f32 v97, v106, v107
	global_store_dwordx4 v[110:111], v[94:97], off offset:256 nt
	s_waitcnt vmcnt(0) lgkmcnt(0)
	v_lshlrev_b32_e32 v102, 16, v144
	v_lshlrev_b32_e32 v94, 16, v142
	v_and_b32_e32 v95, 0xffff0000, v142
	v_lshlrev_b32_e32 v96, 16, v143
	v_and_b32_e32 v97, 0xffff0000, v143
	v_and_b32_e32 v103, 0xffff0000, v144
	v_lshlrev_b32_e32 v104, 16, v145
	v_and_b32_e32 v105, 0xffff0000, v145
	v_pk_fma_f32 v[94:95], v[94:95], s[30:31], v[98:99] op_sel_hi:[1,0,1]
	v_pk_fma_f32 v[96:97], v[96:97], s[30:31], v[100:101] op_sel_hi:[1,0,1]
	v_pk_fma_f32 v[98:99], v[104:105], s[30:31], v[92:93] op_sel_hi:[1,0,1]
	v_pk_fma_f32 v[92:93], v[102:103], s[30:31], v[90:91] op_sel_hi:[1,0,1]
	v_cvt_pk_bf16_f32 v90, v94, v95
	v_add_co_u32_e32 v94, vcc, s31, v122
	v_cvt_pk_bf16_f32 v91, v96, v97
	v_cvt_pk_bf16_f32 v92, v92, v93
	v_cvt_pk_bf16_f32 v93, v98, v99
	v_addc_co_u32_e32 v95, vcc, 0, v123, vcc
	global_store_dwordx4 v[94:95], v[90:93], off nt
	v_lshlrev_b32_e32 v96, 16, v140
	v_and_b32_e32 v97, 0xffff0000, v140
	v_lshlrev_b32_e32 v90, 16, v138
	v_and_b32_e32 v91, 0xffff0000, v138
	v_lshlrev_b32_e32 v92, 16, v139
	v_and_b32_e32 v93, 0xffff0000, v139
	v_lshlrev_b32_e32 v98, 16, v141
	v_and_b32_e32 v99, 0xffff0000, v141
	v_pk_fma_f32 v[88:89], v[92:93], s[30:31], v[88:89] op_sel_hi:[1,0,1]
	v_pk_fma_f32 v[86:87], v[90:91], s[30:31], v[86:87] op_sel_hi:[1,0,1]
	v_pk_fma_f32 v[90:91], v[98:99], s[30:31], v[80:81] op_sel_hi:[1,0,1]
	v_pk_fma_f32 v[80:81], v[96:97], s[30:31], v[78:79] op_sel_hi:[1,0,1]
	v_cvt_pk_bf16_f32 v78, v86, v87
	v_cvt_pk_bf16_f32 v79, v88, v89
	v_cvt_pk_bf16_f32 v80, v80, v81
	v_cvt_pk_bf16_f32 v81, v90, v91
	global_store_dwordx4 v[94:95], v[78:81], off offset:256 nt
	v_lshlrev_b32_e32 v86, 16, v136
	v_and_b32_e32 v87, 0xffff0000, v136
	v_lshlrev_b32_e32 v78, 16, v134
	v_and_b32_e32 v79, 0xffff0000, v134
	v_lshlrev_b32_e32 v80, 16, v135
	v_and_b32_e32 v81, 0xffff0000, v135
	v_lshlrev_b32_e32 v88, 16, v137
	v_and_b32_e32 v89, 0xffff0000, v137
	v_pk_fma_f32 v[78:79], v[78:79], s[30:31], v[82:83] op_sel_hi:[1,0,1]
	v_pk_fma_f32 v[80:81], v[80:81], s[30:31], v[84:85] op_sel_hi:[1,0,1]
	v_pk_fma_f32 v[82:83], v[88:89], s[30:31], v[76:77] op_sel_hi:[1,0,1]
	v_pk_fma_f32 v[76:77], v[86:87], s[30:31], v[74:75] op_sel_hi:[1,0,1]
	v_cvt_pk_bf16_f32 v74, v78, v79
	v_add_co_u32_e32 v78, vcc, s46, v122
	v_cvt_pk_bf16_f32 v75, v80, v81
	v_cvt_pk_bf16_f32 v76, v76, v77
	v_cvt_pk_bf16_f32 v77, v82, v83
	v_addc_co_u32_e32 v79, vcc, 0, v123, vcc
	global_store_dwordx4 v[78:79], v[74:77], off nt
	v_lshlrev_b32_e32 v80, 16, v132
	v_and_b32_e32 v81, 0xffff0000, v132
	v_lshlrev_b32_e32 v74, 16, v130
	v_and_b32_e32 v75, 0xffff0000, v130
	v_lshlrev_b32_e32 v76, 16, v131
	v_and_b32_e32 v77, 0xffff0000, v131
	v_lshlrev_b32_e32 v82, 16, v133
	v_and_b32_e32 v83, 0xffff0000, v133
	v_pk_fma_f32 v[72:73], v[76:77], s[30:31], v[72:73] op_sel_hi:[1,0,1]
	v_pk_fma_f32 v[70:71], v[74:75], s[30:31], v[70:71] op_sel_hi:[1,0,1]
	v_pk_fma_f32 v[74:75], v[82:83], s[30:31], v[68:69] op_sel_hi:[1,0,1]
	v_pk_fma_f32 v[68:69], v[80:81], s[30:31], v[66:67] op_sel_hi:[1,0,1]
	v_cvt_pk_bf16_f32 v66, v70, v71
	v_cvt_pk_bf16_f32 v67, v72, v73
	v_cvt_pk_bf16_f32 v68, v68, v69
	v_cvt_pk_bf16_f32 v69, v74, v75
	global_store_dwordx4 v[78:79], v[66:69], off offset:256 nt
	s_nop 1
	v_add_u32_e32 v66, 0x80, v171
	s_nop 0
	v_ashrrev_i32_e32 v67, 31, v66
	v_lshlrev_b64 v[66:67], 10, v[66:67]
	v_lshl_add_u64 v[66:67], v[66:67], 0, v[164:165]
	v_lshlrev_b64 v[98:99], 1, v[66:67]
	v_lshl_add_u64 v[90:91], s[14:15], 0, v[98:99]
	global_load_dwordx4 v[66:69], v[90:91], off
	global_load_dwordx4 v[70:73], v[90:91], off offset:256
	v_add_co_u32_e32 v78, vcc, s47, v90
	s_waitcnt vmcnt(0) lgkmcnt(0)
	v_lshlrev_b32_e32 v100, 16, v66
	v_addc_co_u32_e32 v79, vcc, 0, v91, vcc
	global_load_dwordx4 v[74:77], v[78:79], off
	s_nop 0
	global_load_dwordx4 v[78:81], v[78:79], off offset:256
	v_add_co_u32_e32 v86, vcc, s31, v90
	v_and_b32_e32 v101, 0xffff0000, v66
	s_nop 0
	v_addc_co_u32_e32 v87, vcc, 0, v91, vcc
	global_load_dwordx4 v[82:85], v[86:87], off
	s_nop 0
	global_load_dwordx4 v[86:89], v[86:87], off offset:256
	v_add_co_u32_e32 v94, vcc, s46, v90
	v_lshlrev_b32_e32 v66, 16, v67
	s_nop 0
	v_addc_co_u32_e32 v95, vcc, 0, v91, vcc
	global_load_dwordx4 v[90:93], v[94:95], off
	s_nop 0
	global_load_dwordx4 v[94:97], v[94:95], off offset:256
	v_and_b32_e32 v67, 0xffff0000, v67
	v_lshlrev_b32_e32 v102, 16, v68
	v_and_b32_e32 v103, 0xffff0000, v68
	v_lshlrev_b32_e32 v68, 16, v69
	v_and_b32_e32 v69, 0xffff0000, v69
	v_pk_fma_f32 v[64:65], v[66:67], s[30:31], v[64:65] op_sel_hi:[1,0,1]
	v_pk_fma_f32 v[62:63], v[100:101], s[30:31], v[62:63] op_sel_hi:[1,0,1]
	v_pk_fma_f32 v[66:67], v[68:69], s[30:31], v[60:61] op_sel_hi:[1,0,1]
	v_pk_fma_f32 v[60:61], v[102:103], s[30:31], v[58:59] op_sel_hi:[1,0,1]
	v_cvt_pk_bf16_f32 v58, v62, v63
	v_cvt_pk_bf16_f32 v59, v64, v65
	v_cvt_pk_bf16_f32 v60, v60, v61
	v_cvt_pk_bf16_f32 v61, v66, v67
	v_lshl_add_u64 v[62:63], s[20:21], 0, v[98:99]
	global_store_dwordx4 v[62:63], v[58:61], off nt
	v_lshlrev_b32_e32 v64, 16, v72
	v_and_b32_e32 v65, 0xffff0000, v72
	v_lshlrev_b32_e32 v58, 16, v70
	v_and_b32_e32 v59, 0xffff0000, v70
	v_lshlrev_b32_e32 v60, 16, v71
	v_and_b32_e32 v61, 0xffff0000, v71
	v_lshlrev_b32_e32 v66, 16, v73
	v_and_b32_e32 v67, 0xffff0000, v73
	v_pk_fma_f32 v[56:57], v[60:61], s[30:31], v[56:57] op_sel_hi:[1,0,1]
	v_pk_fma_f32 v[54:55], v[58:59], s[30:31], v[54:55] op_sel_hi:[1,0,1]
	v_pk_fma_f32 v[58:59], v[66:67], s[30:31], v[48:49] op_sel_hi:[1,0,1]
	v_pk_fma_f32 v[48:49], v[64:65], s[30:31], v[46:47] op_sel_hi:[1,0,1]
	v_cvt_pk_bf16_f32 v46, v54, v55
	v_cvt_pk_bf16_f32 v47, v56, v57
	v_cvt_pk_bf16_f32 v48, v48, v49
	v_cvt_pk_bf16_f32 v49, v58, v59
	global_store_dwordx4 v[62:63], v[46:49], off offset:256 nt
	s_waitcnt vmcnt(0) lgkmcnt(0)
	v_lshlrev_b32_e32 v54, 16, v76
	v_lshlrev_b32_e32 v46, 16, v74
	v_and_b32_e32 v47, 0xffff0000, v74
	v_lshlrev_b32_e32 v48, 16, v75
	v_and_b32_e32 v49, 0xffff0000, v75
	v_and_b32_e32 v55, 0xffff0000, v76
	v_lshlrev_b32_e32 v56, 16, v77
	v_and_b32_e32 v57, 0xffff0000, v77
	v_pk_fma_f32 v[46:47], v[46:47], s[30:31], v[50:51] op_sel_hi:[1,0,1]
	v_pk_fma_f32 v[48:49], v[48:49], s[30:31], v[52:53] op_sel_hi:[1,0,1]
	v_pk_fma_f32 v[50:51], v[56:57], s[30:31], v[44:45] op_sel_hi:[1,0,1]
	v_pk_fma_f32 v[44:45], v[54:55], s[30:31], v[42:43] op_sel_hi:[1,0,1]
	v_cvt_pk_bf16_f32 v42, v46, v47
	v_add_co_u32_e32 v46, vcc, s47, v62
	v_cvt_pk_bf16_f32 v43, v48, v49
	v_cvt_pk_bf16_f32 v44, v44, v45
	v_cvt_pk_bf16_f32 v45, v50, v51
	v_addc_co_u32_e32 v47, vcc, 0, v63, vcc
	global_store_dwordx4 v[46:47], v[42:45], off nt
	v_lshlrev_b32_e32 v48, 16, v80
	v_and_b32_e32 v49, 0xffff0000, v80
	v_lshlrev_b32_e32 v42, 16, v78
	v_and_b32_e32 v43, 0xffff0000, v78
	v_lshlrev_b32_e32 v44, 16, v79
	v_and_b32_e32 v45, 0xffff0000, v79
	v_lshlrev_b32_e32 v50, 16, v81
	v_and_b32_e32 v51, 0xffff0000, v81
	v_pk_fma_f32 v[40:41], v[44:45], s[30:31], v[40:41] op_sel_hi:[1,0,1]
	v_pk_fma_f32 v[38:39], v[42:43], s[30:31], v[38:39] op_sel_hi:[1,0,1]
	v_pk_fma_f32 v[42:43], v[50:51], s[30:31], v[32:33] op_sel_hi:[1,0,1]
	v_pk_fma_f32 v[32:33], v[48:49], s[30:31], v[30:31] op_sel_hi:[1,0,1]
	v_cvt_pk_bf16_f32 v30, v38, v39
	v_cvt_pk_bf16_f32 v31, v40, v41
	v_cvt_pk_bf16_f32 v32, v32, v33
	v_cvt_pk_bf16_f32 v33, v42, v43
	global_store_dwordx4 v[46:47], v[30:33], off offset:256 nt
	v_lshlrev_b32_e32 v38, 16, v84
	v_and_b32_e32 v39, 0xffff0000, v84
	v_lshlrev_b32_e32 v30, 16, v82
	v_and_b32_e32 v31, 0xffff0000, v82
	v_lshlrev_b32_e32 v32, 16, v83
	v_and_b32_e32 v33, 0xffff0000, v83
	v_lshlrev_b32_e32 v40, 16, v85
	v_and_b32_e32 v41, 0xffff0000, v85
	v_pk_fma_f32 v[30:31], v[30:31], s[30:31], v[34:35] op_sel_hi:[1,0,1]
	v_pk_fma_f32 v[32:33], v[32:33], s[30:31], v[36:37] op_sel_hi:[1,0,1]
	v_pk_fma_f32 v[34:35], v[40:41], s[30:31], v[28:29] op_sel_hi:[1,0,1]
	v_pk_fma_f32 v[28:29], v[38:39], s[30:31], v[26:27] op_sel_hi:[1,0,1]
	v_cvt_pk_bf16_f32 v26, v30, v31
	v_add_co_u32_e32 v30, vcc, s31, v62
	v_cvt_pk_bf16_f32 v27, v32, v33
	v_cvt_pk_bf16_f32 v28, v28, v29
	v_cvt_pk_bf16_f32 v29, v34, v35
	v_addc_co_u32_e32 v31, vcc, 0, v63, vcc
	global_store_dwordx4 v[30:31], v[26:29], off nt
	v_lshlrev_b32_e32 v32, 16, v88
	v_and_b32_e32 v33, 0xffff0000, v88
	v_lshlrev_b32_e32 v26, 16, v86
	v_and_b32_e32 v27, 0xffff0000, v86
	v_lshlrev_b32_e32 v28, 16, v87
	v_and_b32_e32 v29, 0xffff0000, v87
	v_lshlrev_b32_e32 v34, 16, v89
	v_and_b32_e32 v35, 0xffff0000, v89
	v_pk_fma_f32 v[24:25], v[28:29], s[30:31], v[24:25] op_sel_hi:[1,0,1]
	v_pk_fma_f32 v[22:23], v[26:27], s[30:31], v[22:23] op_sel_hi:[1,0,1]
	v_pk_fma_f32 v[26:27], v[34:35], s[30:31], v[16:17] op_sel_hi:[1,0,1]
	v_pk_fma_f32 v[16:17], v[32:33], s[30:31], v[14:15] op_sel_hi:[1,0,1]
	v_cvt_pk_bf16_f32 v14, v22, v23
	v_cvt_pk_bf16_f32 v15, v24, v25
	v_cvt_pk_bf16_f32 v16, v16, v17
	v_cvt_pk_bf16_f32 v17, v26, v27
	global_store_dwordx4 v[30:31], v[14:17], off offset:256 nt
	v_lshlrev_b32_e32 v22, 16, v92
	v_and_b32_e32 v23, 0xffff0000, v92
	v_lshlrev_b32_e32 v14, 16, v90
	v_and_b32_e32 v15, 0xffff0000, v90
	v_lshlrev_b32_e32 v16, 16, v91
	v_and_b32_e32 v17, 0xffff0000, v91
	v_lshlrev_b32_e32 v24, 16, v93
	v_and_b32_e32 v25, 0xffff0000, v93
	v_pk_fma_f32 v[14:15], v[14:15], s[30:31], v[18:19] op_sel_hi:[1,0,1]
	v_pk_fma_f32 v[16:17], v[16:17], s[30:31], v[20:21] op_sel_hi:[1,0,1]
	v_pk_fma_f32 v[18:19], v[24:25], s[30:31], v[12:13] op_sel_hi:[1,0,1]
	v_pk_fma_f32 v[12:13], v[22:23], s[30:31], v[10:11] op_sel_hi:[1,0,1]
	v_cvt_pk_bf16_f32 v10, v14, v15
	v_add_co_u32_e32 v14, vcc, s46, v62
	v_cvt_pk_bf16_f32 v11, v16, v17
	v_cvt_pk_bf16_f32 v12, v12, v13
	v_cvt_pk_bf16_f32 v13, v18, v19
	v_addc_co_u32_e32 v15, vcc, 0, v63, vcc
	global_store_dwordx4 v[14:15], v[10:13], off nt
	v_lshlrev_b32_e32 v16, 16, v96
	v_and_b32_e32 v17, 0xffff0000, v96
	v_lshlrev_b32_e32 v10, 16, v94
	v_and_b32_e32 v11, 0xffff0000, v94
	v_lshlrev_b32_e32 v12, 16, v95
	v_and_b32_e32 v13, 0xffff0000, v95
	v_lshlrev_b32_e32 v18, 16, v97
	v_and_b32_e32 v19, 0xffff0000, v97
	v_pk_fma_f32 v[8:9], v[12:13], s[30:31], v[8:9] op_sel_hi:[1,0,1]
	v_pk_fma_f32 v[6:7], v[10:11], s[30:31], v[6:7] op_sel_hi:[1,0,1]
	v_pk_fma_f32 v[10:11], v[18:19], s[30:31], v[4:5] op_sel_hi:[1,0,1]
	v_pk_fma_f32 v[4:5], v[16:17], s[30:31], v[2:3] op_sel_hi:[1,0,1]
	v_cvt_pk_bf16_f32 v2, v6, v7
	v_cvt_pk_bf16_f32 v3, v8, v9
	v_cvt_pk_bf16_f32 v4, v4, v5
	v_cvt_pk_bf16_f32 v5, v10, v11
	s_and_b64 vcc, exec, s[34:35]
	global_store_dwordx4 v[14:15], v[2:5], off offset:256 nt
	s_cbranch_vccz .LBB0_1785
	s_waitcnt vmcnt(0)
	s_cmpk_gt_u32 s4, 0xff
	s_cbranch_scc1 .LBB0_1790
	s_barrier

.LBB0_2495:
	ds_read_b128 v[130:133], v168
	ds_read_b128 v[134:137], v168 offset:1024
	ds_read_b128 v[138:141], v168 offset:2048
	ds_read_b128 v[142:145], v168 offset:3072
	s_add_u32 s0, s36, 0xfffc0080
	s_addc_u32 s1, s37, -1
	s_cmp_eq_u32 s69, 12
	s_cselect_b32 s41, s61, s1
	s_cselect_b32 s40, s62, s0
	s_cselect_b32 s39, s63, s67
	s_cselect_b32 s38, s64, s65
	s_mov_b32 m0, s51
	v_lshl_add_u64 v[164:165], s[36:37], 0, v[162:163]
	ds_read_b128 v[146:149], v169
	ds_read_b128 v[172:175], v169 offset:1024
	ds_read_b128 v[176:179], v169 offset:2048
	ds_read_b128 v[180:183], v169 offset:3072
	ds_read_b128 v[184:187], v169 offset:4096
	ds_read_b128 v[188:191], v169 offset:5120
	ds_read_b128 v[192:195], v169 offset:6144
	ds_read_b128 v[196:199], v169 offset:7168
	global_load_lds_dwordx4 v[164:165], off
	v_lshl_add_u64 v[164:165], s[36:37], 0, v[160:161]
	s_mov_b32 m0, s52
	s_nop 0
	global_load_lds_dwordx4 v[164:165], off
	s_waitcnt lgkmcnt(8)
	s_waitcnt vmcnt(10)
	s_barrier
	s_waitcnt lgkmcnt(0)
	s_waitcnt lgkmcnt(0)
	v_mfma_f32_16x16x32_bf16 v[126:129], v[130:133], v[146:149], v[126:129]
	v_mfma_f32_16x16x32_bf16 v[122:125], v[138:141], v[146:149], v[122:125]
	v_mfma_f32_16x16x32_bf16 v[118:121], v[130:133], v[176:179], v[118:121]
	v_mfma_f32_16x16x32_bf16 v[110:113], v[138:141], v[176:179], v[110:113]
	v_mfma_f32_16x16x32_bf16 v[98:101], v[130:133], v[184:187], v[98:101]
	v_mfma_f32_16x16x32_bf16 v[90:93], v[138:141], v[184:187], v[90:93]
	v_mfma_f32_16x16x32_bf16 v[82:85], v[130:133], v[192:195], v[82:85]
	v_mfma_f32_16x16x32_bf16 v[74:77], v[138:141], v[192:195], v[74:77]
	v_mfma_f32_16x16x32_bf16 v[126:129], v[134:137], v[172:175], v[126:129]
	v_mfma_f32_16x16x32_bf16 v[122:125], v[142:145], v[172:175], v[122:125]
	v_mfma_f32_16x16x32_bf16 v[118:121], v[134:137], v[180:183], v[118:121]
	v_mfma_f32_16x16x32_bf16 v[110:113], v[142:145], v[180:183], v[110:113]
	v_mfma_f32_16x16x32_bf16 v[98:101], v[134:137], v[188:191], v[98:101]
	v_mfma_f32_16x16x32_bf16 v[90:93], v[142:145], v[188:191], v[90:93]
	v_mfma_f32_16x16x32_bf16 v[82:85], v[134:137], v[196:199], v[82:85]
	v_mfma_f32_16x16x32_bf16 v[74:77], v[142:145], v[196:199], v[74:77]
	s_barrier
	s_mov_b32 m0, s53
	v_lshl_add_u64 v[164:165], s[38:39], 0, v[156:157]
	ds_read_b128 v[200:203], v170
	ds_read_b128 v[204:207], v170 offset:1024
	ds_read_b128 v[208:211], v170 offset:2048
	ds_read_b128 v[212:215], v170 offset:3072
	global_load_lds_dwordx4 v[164:165], off
	v_lshl_add_u64 v[216:217], s[38:39], 0, v[152:153]
	s_mov_b32 m0, s54
	s_nop 0
	global_load_lds_dwordx4 v[216:217], off
	s_waitcnt vmcnt(10)
	s_barrier
	s_waitcnt lgkmcnt(0)
	s_waitcnt lgkmcnt(0)
	v_mfma_f32_16x16x32_bf16 v[114:117], v[200:203], v[146:149], v[114:117]
	v_mfma_f32_16x16x32_bf16 v[106:109], v[208:211], v[146:149], v[106:109]
	v_mfma_f32_16x16x32_bf16 v[102:105], v[200:203], v[176:179], v[102:105]
	v_mfma_f32_16x16x32_bf16 v[94:97], v[208:211], v[176:179], v[94:97]
	v_mfma_f32_16x16x32_bf16 v[86:89], v[200:203], v[184:187], v[86:89]
	v_mfma_f32_16x16x32_bf16 v[78:81], v[208:211], v[184:187], v[78:81]
	v_mfma_f32_16x16x32_bf16 v[70:73], v[200:203], v[192:195], v[70:73]
	v_mfma_f32_16x16x32_bf16 v[66:69], v[208:211], v[192:195], v[66:69]
	v_mfma_f32_16x16x32_bf16 v[114:117], v[204:207], v[172:175], v[114:117]
	v_mfma_f32_16x16x32_bf16 v[106:109], v[212:215], v[172:175], v[106:109]
	v_mfma_f32_16x16x32_bf16 v[102:105], v[204:207], v[180:183], v[102:105]
	v_mfma_f32_16x16x32_bf16 v[94:97], v[212:215], v[180:183], v[94:97]
	v_mfma_f32_16x16x32_bf16 v[86:89], v[204:207], v[188:191], v[86:89]
	v_mfma_f32_16x16x32_bf16 v[78:81], v[212:215], v[188:191], v[78:81]
	v_mfma_f32_16x16x32_bf16 v[70:73], v[204:207], v[196:199], v[70:73]
	v_mfma_f32_16x16x32_bf16 v[66:69], v[212:215], v[196:199], v[66:69]
	s_mov_b32 m0, s9
	v_lshl_add_u64 v[218:219], s[40:41], 0, v[158:159]
	s_barrier
	ds_read_b128 v[146:149], v169 offset:16384
	ds_read_b128 v[172:175], v169 offset:17408
	ds_read_b128 v[176:179], v169 offset:18432
	ds_read_b128 v[180:183], v169 offset:19456
	ds_read_b128 v[184:187], v169 offset:20480
	ds_read_b128 v[188:191], v169 offset:21504
	ds_read_b128 v[192:195], v169 offset:22528
	ds_read_b128 v[196:199], v169 offset:23552
	global_load_lds_dwordx4 v[218:219], off
	v_lshl_add_u64 v[220:221], s[40:41], 0, v[154:155]
	s_mov_b32 m0, s29
	s_nop 0
	global_load_lds_dwordx4 v[220:221], off
	s_waitcnt vmcnt(10)
	s_barrier
	s_waitcnt lgkmcnt(0)
	s_waitcnt lgkmcnt(0)
	v_mfma_f32_16x16x32_bf16 v[62:65], v[130:133], v[146:149], v[62:65]
	v_mfma_f32_16x16x32_bf16 v[58:61], v[138:141], v[146:149], v[58:61]
	v_mfma_f32_16x16x32_bf16 v[50:53], v[130:133], v[176:179], v[50:53]
	v_mfma_f32_16x16x32_bf16 v[42:45], v[138:141], v[176:179], v[42:45]
	v_mfma_f32_16x16x32_bf16 v[34:37], v[130:133], v[184:187], v[34:37]
	v_mfma_f32_16x16x32_bf16 v[26:29], v[138:141], v[184:187], v[26:29]
	v_mfma_f32_16x16x32_bf16 v[18:21], v[130:133], v[192:195], v[18:21]
	v_mfma_f32_16x16x32_bf16 v[10:13], v[138:141], v[192:195], v[10:13]
	v_mfma_f32_16x16x32_bf16 v[62:65], v[134:137], v[172:175], v[62:65]
	v_mfma_f32_16x16x32_bf16 v[58:61], v[142:145], v[172:175], v[58:61]
	v_mfma_f32_16x16x32_bf16 v[50:53], v[134:137], v[180:183], v[50:53]
	v_mfma_f32_16x16x32_bf16 v[42:45], v[142:145], v[180:183], v[42:45]
	v_mfma_f32_16x16x32_bf16 v[34:37], v[134:137], v[188:191], v[34:37]
	v_mfma_f32_16x16x32_bf16 v[26:29], v[142:145], v[188:191], v[26:29]
	v_mfma_f32_16x16x32_bf16 v[18:21], v[134:137], v[196:199], v[18:21]
	v_mfma_f32_16x16x32_bf16 v[10:13], v[142:145], v[196:199], v[10:13]
	s_barrier
	s_add_u32 s0, s38, 0x40000
	s_addc_u32 s1, s39, 0
	s_mov_b32 m0, s55
	v_lshl_add_u64 v[130:131], s[0:1], 0, v[156:157]
	global_load_lds_dwordx4 v[130:131], off
	v_lshl_add_u64 v[130:131], s[0:1], 0, v[152:153]
	s_add_i32 m0, s55, 0x2000
	s_nop 0
	global_load_lds_dwordx4 v[130:131], off
	s_waitcnt vmcnt(10)
	s_barrier
	v_mfma_f32_16x16x32_bf16 v[54:57], v[200:203], v[146:149], v[54:57]
	v_mfma_f32_16x16x32_bf16 v[46:49], v[208:211], v[146:149], v[46:49]
	v_mfma_f32_16x16x32_bf16 v[38:41], v[200:203], v[176:179], v[38:41]
	v_mfma_f32_16x16x32_bf16 v[30:33], v[208:211], v[176:179], v[30:33]
	v_mfma_f32_16x16x32_bf16 v[22:25], v[200:203], v[184:187], v[22:25]
	v_mfma_f32_16x16x32_bf16 v[14:17], v[208:211], v[184:187], v[14:17]
	v_mfma_f32_16x16x32_bf16 v[6:9], v[200:203], v[192:195], v[6:9]
	v_mfma_f32_16x16x32_bf16 v[2:5], v[208:211], v[192:195], v[2:5]
	v_mfma_f32_16x16x32_bf16 v[54:57], v[204:207], v[172:175], v[54:57]
	v_mfma_f32_16x16x32_bf16 v[46:49], v[212:215], v[172:175], v[46:49]
	v_mfma_f32_16x16x32_bf16 v[38:41], v[204:207], v[180:183], v[38:41]
	v_mfma_f32_16x16x32_bf16 v[30:33], v[212:215], v[180:183], v[30:33]
	v_mfma_f32_16x16x32_bf16 v[22:25], v[204:207], v[188:191], v[22:25]
	v_mfma_f32_16x16x32_bf16 v[14:17], v[212:215], v[188:191], v[14:17]
	v_mfma_f32_16x16x32_bf16 v[6:9], v[204:207], v[196:199], v[6:9]
	v_mfma_f32_16x16x32_bf16 v[2:5], v[212:215], v[196:199], v[2:5]
	s_add_i32 s70, 0, 0x18000
	v_add_u32_e32 v142, s70, v167
	s_barrier
	ds_read_b128 v[130:133], v142
	ds_read_b128 v[134:137], v142 offset:1024
	ds_read_b128 v[138:141], v142 offset:2048
	ds_read_b128 v[142:145], v142 offset:3072
	s_add_u32 s0, s40, 0x40000
	s_addc_u32 s1, s41, 0
	s_mov_b32 m0, s42
	v_lshl_add_u64 v[200:201], s[0:1], 0, v[158:159]
	ds_read_b128 v[146:149], v169 offset:32768
	ds_read_b128 v[172:175], v169 offset:33792
	ds_read_b128 v[176:179], v169 offset:34816
	ds_read_b128 v[180:183], v169 offset:35840
	ds_read_b128 v[184:187], v169 offset:36864
	ds_read_b128 v[188:191], v169 offset:37888
	ds_read_b128 v[192:195], v169 offset:38912
	ds_read_b128 v[196:199], v169 offset:39936
	global_load_lds_dwordx4 v[200:201], off
	v_lshl_add_u64 v[200:201], s[0:1], 0, v[154:155]
	s_mov_b32 m0, s43
	s_nop 0
	global_load_lds_dwordx4 v[200:201], off
	s_waitcnt lgkmcnt(8)
	s_waitcnt vmcnt(10)
	s_barrier
	s_waitcnt lgkmcnt(0)
	s_waitcnt lgkmcnt(0)
	v_mfma_f32_16x16x32_bf16 v[126:129], v[130:133], v[146:149], v[126:129]
	v_mfma_f32_16x16x32_bf16 v[122:125], v[138:141], v[146:149], v[122:125]
	v_mfma_f32_16x16x32_bf16 v[118:121], v[130:133], v[176:179], v[118:121]
	v_mfma_f32_16x16x32_bf16 v[110:113], v[138:141], v[176:179], v[110:113]
	v_mfma_f32_16x16x32_bf16 v[98:101], v[130:133], v[184:187], v[98:101]
	v_mfma_f32_16x16x32_bf16 v[90:93], v[138:141], v[184:187], v[90:93]
	v_mfma_f32_16x16x32_bf16 v[82:85], v[130:133], v[192:195], v[82:85]
	v_mfma_f32_16x16x32_bf16 v[74:77], v[138:141], v[192:195], v[74:77]
	v_mfma_f32_16x16x32_bf16 v[126:129], v[134:137], v[172:175], v[126:129]
	v_mfma_f32_16x16x32_bf16 v[122:125], v[142:145], v[172:175], v[122:125]
	v_mfma_f32_16x16x32_bf16 v[118:121], v[134:137], v[180:183], v[118:121]
	v_mfma_f32_16x16x32_bf16 v[110:113], v[142:145], v[180:183], v[110:113]
	v_mfma_f32_16x16x32_bf16 v[98:101], v[134:137], v[188:191], v[98:101]
	v_mfma_f32_16x16x32_bf16 v[90:93], v[142:145], v[188:191], v[90:93]
	v_mfma_f32_16x16x32_bf16 v[82:85], v[134:137], v[196:199], v[82:85]
	v_mfma_f32_16x16x32_bf16 v[74:77], v[142:145], v[196:199], v[74:77]
	s_barrier
	s_add_i32 s40, 0, 0x1c000
	s_add_i32 s0, s70, s8
	v_add_u32_e32 v171, s40, v167
	v_lshl_add_u64 v[164:165], v[164:165], 0, s[26:27]
	s_mov_b32 m0, s0
	ds_read_b128 v[200:203], v171
	ds_read_b128 v[204:207], v171 offset:1024
	ds_read_b128 v[208:211], v171 offset:2048
	ds_read_b128 v[212:215], v171 offset:3072
	global_load_lds_dwordx4 v[164:165], off
	v_lshl_add_u64 v[164:165], v[216:217], 0, s[26:27]
	s_add_i32 m0, s0, 0x2000
	s_nop 0
	global_load_lds_dwordx4 v[164:165], off
	s_waitcnt vmcnt(10)
	s_barrier
	s_waitcnt lgkmcnt(0)
	s_waitcnt lgkmcnt(0)
	v_mfma_f32_16x16x32_bf16 v[114:117], v[200:203], v[146:149], v[114:117]
	v_mfma_f32_16x16x32_bf16 v[106:109], v[208:211], v[146:149], v[106:109]
	v_mfma_f32_16x16x32_bf16 v[102:105], v[200:203], v[176:179], v[102:105]
	v_mfma_f32_16x16x32_bf16 v[94:97], v[208:211], v[176:179], v[94:97]
	v_mfma_f32_16x16x32_bf16 v[86:89], v[200:203], v[184:187], v[86:89]
	v_mfma_f32_16x16x32_bf16 v[78:81], v[208:211], v[184:187], v[78:81]
	v_mfma_f32_16x16x32_bf16 v[70:73], v[200:203], v[192:195], v[70:73]
	v_mfma_f32_16x16x32_bf16 v[66:69], v[208:211], v[192:195], v[66:69]
	v_mfma_f32_16x16x32_bf16 v[114:117], v[204:207], v[172:175], v[114:117]
	v_mfma_f32_16x16x32_bf16 v[106:109], v[212:215], v[172:175], v[106:109]
	v_mfma_f32_16x16x32_bf16 v[102:105], v[204:207], v[180:183], v[102:105]
	v_mfma_f32_16x16x32_bf16 v[94:97], v[212:215], v[180:183], v[94:97]
	v_mfma_f32_16x16x32_bf16 v[86:89], v[204:207], v[188:191], v[86:89]
	v_mfma_f32_16x16x32_bf16 v[78:81], v[212:215], v[188:191], v[78:81]
	v_mfma_f32_16x16x32_bf16 v[70:73], v[204:207], v[196:199], v[70:73]
	v_mfma_f32_16x16x32_bf16 v[66:69], v[212:215], v[196:199], v[66:69]
	s_mov_b32 m0, s49
	v_lshl_add_u64 v[164:165], v[218:219], 0, s[26:27]
	s_barrier
	ds_read_b128 v[146:149], v169 offset:49152
	ds_read_b128 v[172:175], v169 offset:50176
	ds_read_b128 v[176:179], v169 offset:51200
	ds_read_b128 v[180:183], v169 offset:52224
	ds_read_b128 v[184:187], v169 offset:53248
	ds_read_b128 v[188:191], v169 offset:54272
	ds_read_b128 v[192:195], v169 offset:55296
	ds_read_b128 v[196:199], v169 offset:56320
	global_load_lds_dwordx4 v[164:165], off
	v_lshl_add_u64 v[164:165], v[220:221], 0, s[26:27]
	s_mov_b32 m0, s50
	s_nop 0
	global_load_lds_dwordx4 v[164:165], off
	s_waitcnt vmcnt(10)
	s_barrier
	s_waitcnt lgkmcnt(0)
	s_waitcnt lgkmcnt(0)
	v_mfma_f32_16x16x32_bf16 v[62:65], v[130:133], v[146:149], v[62:65]
	v_mfma_f32_16x16x32_bf16 v[58:61], v[138:141], v[146:149], v[58:61]
	v_mfma_f32_16x16x32_bf16 v[50:53], v[130:133], v[176:179], v[50:53]
	v_mfma_f32_16x16x32_bf16 v[42:45], v[138:141], v[176:179], v[42:45]
	v_mfma_f32_16x16x32_bf16 v[34:37], v[130:133], v[184:187], v[34:37]
	v_mfma_f32_16x16x32_bf16 v[26:29], v[138:141], v[184:187], v[26:29]
	v_mfma_f32_16x16x32_bf16 v[18:21], v[130:133], v[192:195], v[18:21]
	v_mfma_f32_16x16x32_bf16 v[10:13], v[138:141], v[192:195], v[10:13]
	v_mfma_f32_16x16x32_bf16 v[62:65], v[134:137], v[172:175], v[62:65]
	v_mfma_f32_16x16x32_bf16 v[58:61], v[142:145], v[172:175], v[58:61]
	v_mfma_f32_16x16x32_bf16 v[50:53], v[134:137], v[180:183], v[50:53]
	v_mfma_f32_16x16x32_bf16 v[42:45], v[142:145], v[180:183], v[42:45]
	v_mfma_f32_16x16x32_bf16 v[34:37], v[134:137], v[188:191], v[34:37]
	v_mfma_f32_16x16x32_bf16 v[26:29], v[142:145], v[188:191], v[26:29]
	v_mfma_f32_16x16x32_bf16 v[18:21], v[134:137], v[196:199], v[18:21]
	v_mfma_f32_16x16x32_bf16 v[10:13], v[142:145], v[196:199], v[10:13]
	s_barrier
	s_add_u32 s0, s38, 0x40080
	s_addc_u32 s1, s39, 0
	s_add_i32 s38, s40, s8
	v_lshl_add_u64 v[130:131], s[0:1], 0, v[156:157]
	s_mov_b32 m0, s38
	s_nop 0
	global_load_lds_dwordx4 v[130:131], off
	v_lshl_add_u64 v[130:131], s[0:1], 0, v[152:153]
	s_add_i32 m0, s38, 0x2000
	s_nop 0
	global_load_lds_dwordx4 v[130:131], off
	s_waitcnt vmcnt(10)
	s_barrier
	v_mfma_f32_16x16x32_bf16 v[54:57], v[200:203], v[146:149], v[54:57]
	v_mfma_f32_16x16x32_bf16 v[46:49], v[208:211], v[146:149], v[46:49]
	v_mfma_f32_16x16x32_bf16 v[38:41], v[200:203], v[176:179], v[38:41]
	v_mfma_f32_16x16x32_bf16 v[30:33], v[208:211], v[176:179], v[30:33]
	v_mfma_f32_16x16x32_bf16 v[22:25], v[200:203], v[184:187], v[22:25]
	v_mfma_f32_16x16x32_bf16 v[14:17], v[208:211], v[184:187], v[14:17]
	v_mfma_f32_16x16x32_bf16 v[6:9], v[200:203], v[192:195], v[6:9]
	v_mfma_f32_16x16x32_bf16 v[2:5], v[208:211], v[192:195], v[2:5]
	v_mfma_f32_16x16x32_bf16 v[54:57], v[204:207], v[172:175], v[54:57]
	v_mfma_f32_16x16x32_bf16 v[46:49], v[212:215], v[172:175], v[46:49]
	v_mfma_f32_16x16x32_bf16 v[38:41], v[204:207], v[180:183], v[38:41]
	v_mfma_f32_16x16x32_bf16 v[30:33], v[212:215], v[180:183], v[30:33]
	v_mfma_f32_16x16x32_bf16 v[22:25], v[204:207], v[188:191], v[22:25]
	v_mfma_f32_16x16x32_bf16 v[14:17], v[212:215], v[188:191], v[14:17]
	v_mfma_f32_16x16x32_bf16 v[6:9], v[204:207], v[196:199], v[6:9]
	v_mfma_f32_16x16x32_bf16 v[2:5], v[212:215], v[196:199], v[2:5]
	s_add_i32 s69, s69, 2
	s_add_u32 s65, s65, 0x100
	s_addc_u32 s67, s67, 0
	s_add_u32 s36, s36, 0x100
	s_addc_u32 s37, s37, 0
	s_cmp_gt_u32 s69, 13
	s_barrier
	s_cbranch_scc0 .LBB0_2495
	s_lshl_b32 s0, s59, 8
	v_mov_b32_e32 v130, v151
	v_mov_b32_e32 v131, v166
	s_or_b32 s0, s0, s46
	s_mov_b32 s59, s58
	v_lshl_add_u32 v164, v131, 3, s0
	s_lshl_b32 s0, s60, 8
	s_add_i32 s0, s0, s45
	v_add_u32_e32 v171, s0, v130
	v_mov_b32_e32 v130, v171
	v_ashrrev_i32_e32 v165, 31, v164
	v_ashrrev_i32_e32 v131, 31, v130
	v_lshlrev_b64 v[130:131], 10, v[130:131]
	v_lshl_add_u64 v[130:131], v[130:131], 0, v[164:165]
	v_lshlrev_b64 v[184:185], 1, v[130:131]
	v_lshl_add_u64 v[130:131], s[10:11], 0, v[184:185]
	global_load_dwordx4 v[172:175], v[130:131], off
	global_load_dwordx4 v[176:179], v[130:131], off offset:256
	v_add_co_u32_e32 v132, vcc, s48, v130
	s_mov_b32 s60, s57
	s_nop 0
	v_addc_co_u32_e32 v133, vcc, 0, v131, vcc
	global_load_dwordx4 v[180:183], v[132:133], off
	global_load_dwordx4 v[146:149], v[132:133], off offset:256
	v_add_co_u32_e32 v132, vcc, s44, v130
	s_waitcnt vmcnt(0) lgkmcnt(0)
	v_lshlrev_b32_e32 v186, 16, v172
	v_addc_co_u32_e32 v133, vcc, 0, v131, vcc
	global_load_dwordx4 v[142:145], v[132:133], off
	global_load_dwordx4 v[138:141], v[132:133], off offset:256
	v_add_co_u32_e32 v130, vcc, s47, v130
	v_and_b32_e32 v187, 0xffff0000, v172
	s_nop 0
	v_addc_co_u32_e32 v131, vcc, 0, v131, vcc
	global_load_dwordx4 v[134:137], v[130:131], off
	s_nop 0
	global_load_dwordx4 v[130:133], v[130:131], off offset:256
	v_lshlrev_b32_e32 v172, 16, v173
	v_and_b32_e32 v173, 0xffff0000, v173
	v_lshlrev_b32_e32 v188, 16, v174
	v_and_b32_e32 v189, 0xffff0000, v174
	v_lshlrev_b32_e32 v174, 16, v175
	v_and_b32_e32 v175, 0xffff0000, v175
	v_pk_fma_f32 v[128:129], v[172:173], s[28:29], v[128:129] op_sel_hi:[1,0,1]
	v_pk_fma_f32 v[126:127], v[186:187], s[28:29], v[126:127] op_sel_hi:[1,0,1]
	v_pk_fma_f32 v[172:173], v[174:175], s[28:29], v[124:125] op_sel_hi:[1,0,1]
	v_pk_fma_f32 v[122:123], v[188:189], s[28:29], v[122:123] op_sel_hi:[1,0,1]
	v_cvt_pk_bf16_f32 v124, v126, v127
	v_cvt_pk_bf16_f32 v125, v128, v129
	v_cvt_pk_bf16_f32 v126, v122, v123
	v_cvt_pk_bf16_f32 v127, v172, v173
	v_lshl_add_u64 v[122:123], s[16:17], 0, v[184:185]
	global_store_dwordx4 v[122:123], v[124:127], off nt
	v_lshlrev_b32_e32 v128, 16, v178
	v_and_b32_e32 v129, 0xffff0000, v178
	v_lshlrev_b32_e32 v124, 16, v176
	v_and_b32_e32 v125, 0xffff0000, v176
	v_lshlrev_b32_e32 v126, 16, v177
	v_and_b32_e32 v127, 0xffff0000, v177
	v_lshlrev_b32_e32 v172, 16, v179
	v_and_b32_e32 v173, 0xffff0000, v179
	v_pk_fma_f32 v[116:117], v[126:127], s[28:29], v[116:117] op_sel_hi:[1,0,1]
	v_pk_fma_f32 v[114:115], v[124:125], s[28:29], v[114:115] op_sel_hi:[1,0,1]
	v_pk_fma_f32 v[124:125], v[172:173], s[28:29], v[108:109] op_sel_hi:[1,0,1]
	v_pk_fma_f32 v[108:109], v[128:129], s[28:29], v[106:107] op_sel_hi:[1,0,1]
	v_cvt_pk_bf16_f32 v106, v114, v115
	v_cvt_pk_bf16_f32 v107, v116, v117
	v_cvt_pk_bf16_f32 v108, v108, v109
	v_cvt_pk_bf16_f32 v109, v124, v125
	global_store_dwordx4 v[122:123], v[106:109], off offset:256 nt
	v_lshlrev_b32_e32 v114, 16, v182
	v_and_b32_e32 v115, 0xffff0000, v182
	v_lshlrev_b32_e32 v106, 16, v180
	v_and_b32_e32 v107, 0xffff0000, v180
	v_lshlrev_b32_e32 v108, 16, v181
	v_and_b32_e32 v109, 0xffff0000, v181
	v_lshlrev_b32_e32 v116, 16, v183
	v_and_b32_e32 v117, 0xffff0000, v183
	v_pk_fma_f32 v[108:109], v[108:109], s[28:29], v[120:121] op_sel_hi:[1,0,1]
	v_pk_fma_f32 v[106:107], v[106:107], s[28:29], v[118:119] op_sel_hi:[1,0,1]
	v_pk_fma_f32 v[110:111], v[114:115], s[28:29], v[110:111] op_sel_hi:[1,0,1]
	v_pk_fma_f32 v[112:113], v[116:117], s[28:29], v[112:113] op_sel_hi:[1,0,1]
	v_cvt_pk_bf16_f32 v106, v106, v107
	v_cvt_pk_bf16_f32 v107, v108, v109
	v_cvt_pk_bf16_f32 v108, v110, v111
	v_add_co_u32_e32 v110, vcc, s48, v122
	v_cvt_pk_bf16_f32 v109, v112, v113
	s_nop 0
	v_addc_co_u32_e32 v111, vcc, 0, v123, vcc
	global_store_dwordx4 v[110:111], v[106:109], off nt
	v_lshlrev_b32_e32 v112, 16, v148
	v_and_b32_e32 v113, 0xffff0000, v148
	v_lshlrev_b32_e32 v106, 16, v146
	v_and_b32_e32 v107, 0xffff0000, v146
	v_lshlrev_b32_e32 v108, 16, v147
	v_and_b32_e32 v109, 0xffff0000, v147
	v_lshlrev_b32_e32 v114, 16, v149
	v_and_b32_e32 v115, 0xffff0000, v149
	v_pk_fma_f32 v[104:105], v[108:109], s[28:29], v[104:105] op_sel_hi:[1,0,1]
	v_pk_fma_f32 v[102:103], v[106:107], s[28:29], v[102:103] op_sel_hi:[1,0,1]
	v_pk_fma_f32 v[106:107], v[114:115], s[28:29], v[96:97] op_sel_hi:[1,0,1]
	v_pk_fma_f32 v[96:97], v[112:113], s[28:29], v[94:95] op_sel_hi:[1,0,1]
	v_cvt_pk_bf16_f32 v94, v102, v103
	v_cvt_pk_bf16_f32 v95, v104, v105
	v_cvt_pk_bf16_f32 v96, v96, v97
	v_cvt_pk_bf16_f32 v97, v106, v107
	global_store_dwordx4 v[110:111], v[94:97], off offset:256 nt
	s_waitcnt vmcnt(0) lgkmcnt(0)
	v_lshlrev_b32_e32 v102, 16, v144
	v_lshlrev_b32_e32 v94, 16, v142
	v_and_b32_e32 v95, 0xffff0000, v142
	v_lshlrev_b32_e32 v96, 16, v143
	v_and_b32_e32 v97, 0xffff0000, v143
	v_and_b32_e32 v103, 0xffff0000, v144
	v_lshlrev_b32_e32 v104, 16, v145
	v_and_b32_e32 v105, 0xffff0000, v145
	v_pk_fma_f32 v[94:95], v[94:95], s[28:29], v[98:99] op_sel_hi:[1,0,1]
	v_pk_fma_f32 v[96:97], v[96:97], s[28:29], v[100:101] op_sel_hi:[1,0,1]
	v_pk_fma_f32 v[98:99], v[104:105], s[28:29], v[92:93] op_sel_hi:[1,0,1]
	v_pk_fma_f32 v[92:93], v[102:103], s[28:29], v[90:91] op_sel_hi:[1,0,1]
	v_cvt_pk_bf16_f32 v90, v94, v95
	v_add_co_u32_e32 v94, vcc, s44, v122
	v_cvt_pk_bf16_f32 v91, v96, v97
	v_cvt_pk_bf16_f32 v92, v92, v93
	v_cvt_pk_bf16_f32 v93, v98, v99
	v_addc_co_u32_e32 v95, vcc, 0, v123, vcc
	global_store_dwordx4 v[94:95], v[90:93], off nt
	v_lshlrev_b32_e32 v96, 16, v140
	v_and_b32_e32 v97, 0xffff0000, v140
	v_lshlrev_b32_e32 v90, 16, v138
	v_and_b32_e32 v91, 0xffff0000, v138
	v_lshlrev_b32_e32 v92, 16, v139
	v_and_b32_e32 v93, 0xffff0000, v139
	v_lshlrev_b32_e32 v98, 16, v141
	v_and_b32_e32 v99, 0xffff0000, v141
	v_pk_fma_f32 v[88:89], v[92:93], s[28:29], v[88:89] op_sel_hi:[1,0,1]
	v_pk_fma_f32 v[86:87], v[90:91], s[28:29], v[86:87] op_sel_hi:[1,0,1]
	v_pk_fma_f32 v[90:91], v[98:99], s[28:29], v[80:81] op_sel_hi:[1,0,1]
	v_pk_fma_f32 v[80:81], v[96:97], s[28:29], v[78:79] op_sel_hi:[1,0,1]
	v_cvt_pk_bf16_f32 v78, v86, v87
	v_cvt_pk_bf16_f32 v79, v88, v89
	v_cvt_pk_bf16_f32 v80, v80, v81
	v_cvt_pk_bf16_f32 v81, v90, v91
	global_store_dwordx4 v[94:95], v[78:81], off offset:256 nt
	v_lshlrev_b32_e32 v86, 16, v136
	v_and_b32_e32 v87, 0xffff0000, v136
	v_lshlrev_b32_e32 v78, 16, v134
	v_and_b32_e32 v79, 0xffff0000, v134
	v_lshlrev_b32_e32 v80, 16, v135
	v_and_b32_e32 v81, 0xffff0000, v135
	v_lshlrev_b32_e32 v88, 16, v137
	v_and_b32_e32 v89, 0xffff0000, v137
	v_pk_fma_f32 v[78:79], v[78:79], s[28:29], v[82:83] op_sel_hi:[1,0,1]
	v_pk_fma_f32 v[80:81], v[80:81], s[28:29], v[84:85] op_sel_hi:[1,0,1]
	v_pk_fma_f32 v[82:83], v[88:89], s[28:29], v[76:77] op_sel_hi:[1,0,1]
	v_pk_fma_f32 v[76:77], v[86:87], s[28:29], v[74:75] op_sel_hi:[1,0,1]
	v_cvt_pk_bf16_f32 v74, v78, v79
	v_add_co_u32_e32 v78, vcc, s47, v122
	v_cvt_pk_bf16_f32 v75, v80, v81
	v_cvt_pk_bf16_f32 v76, v76, v77
	v_cvt_pk_bf16_f32 v77, v82, v83
	v_addc_co_u32_e32 v79, vcc, 0, v123, vcc
	global_store_dwordx4 v[78:79], v[74:77], off nt
	v_lshlrev_b32_e32 v80, 16, v132
	v_and_b32_e32 v81, 0xffff0000, v132
	v_lshlrev_b32_e32 v74, 16, v130
	v_and_b32_e32 v75, 0xffff0000, v130
	v_lshlrev_b32_e32 v76, 16, v131
	v_and_b32_e32 v77, 0xffff0000, v131
	v_lshlrev_b32_e32 v82, 16, v133
	v_and_b32_e32 v83, 0xffff0000, v133
	v_pk_fma_f32 v[72:73], v[76:77], s[28:29], v[72:73] op_sel_hi:[1,0,1]
	v_pk_fma_f32 v[70:71], v[74:75], s[28:29], v[70:71] op_sel_hi:[1,0,1]
	v_pk_fma_f32 v[74:75], v[82:83], s[28:29], v[68:69] op_sel_hi:[1,0,1]
	v_pk_fma_f32 v[68:69], v[80:81], s[28:29], v[66:67] op_sel_hi:[1,0,1]
	v_cvt_pk_bf16_f32 v66, v70, v71
	v_cvt_pk_bf16_f32 v67, v72, v73
	v_cvt_pk_bf16_f32 v68, v68, v69
	v_cvt_pk_bf16_f32 v69, v74, v75
	global_store_dwordx4 v[78:79], v[66:69], off offset:256 nt
	s_nop 1
	v_add_u32_e32 v66, 0x80, v171
	s_nop 0
	v_ashrrev_i32_e32 v67, 31, v66
	v_lshlrev_b64 v[66:67], 10, v[66:67]
	v_lshl_add_u64 v[66:67], v[66:67], 0, v[164:165]
	v_lshlrev_b64 v[98:99], 1, v[66:67]
	v_lshl_add_u64 v[90:91], s[10:11], 0, v[98:99]
	global_load_dwordx4 v[66:69], v[90:91], off
	global_load_dwordx4 v[70:73], v[90:91], off offset:256
	v_add_co_u32_e32 v78, vcc, s48, v90
	s_waitcnt vmcnt(0) lgkmcnt(0)
	v_lshlrev_b32_e32 v100, 16, v66
	v_addc_co_u32_e32 v79, vcc, 0, v91, vcc
	global_load_dwordx4 v[74:77], v[78:79], off
	s_nop 0
	global_load_dwordx4 v[78:81], v[78:79], off offset:256
	v_add_co_u32_e32 v86, vcc, s44, v90
	v_and_b32_e32 v101, 0xffff0000, v66
	s_nop 0
	v_addc_co_u32_e32 v87, vcc, 0, v91, vcc
	global_load_dwordx4 v[82:85], v[86:87], off
	s_nop 0
	global_load_dwordx4 v[86:89], v[86:87], off offset:256
	v_add_co_u32_e32 v94, vcc, s47, v90
	v_lshlrev_b32_e32 v66, 16, v67
	s_nop 0
	v_addc_co_u32_e32 v95, vcc, 0, v91, vcc
	global_load_dwordx4 v[90:93], v[94:95], off
	s_nop 0
	global_load_dwordx4 v[94:97], v[94:95], off offset:256
	v_and_b32_e32 v67, 0xffff0000, v67
	v_lshlrev_b32_e32 v102, 16, v68
	v_and_b32_e32 v103, 0xffff0000, v68
	v_lshlrev_b32_e32 v68, 16, v69
	v_and_b32_e32 v69, 0xffff0000, v69
	v_pk_fma_f32 v[64:65], v[66:67], s[28:29], v[64:65] op_sel_hi:[1,0,1]
	v_pk_fma_f32 v[62:63], v[100:101], s[28:29], v[62:63] op_sel_hi:[1,0,1]
	v_pk_fma_f32 v[66:67], v[68:69], s[28:29], v[60:61] op_sel_hi:[1,0,1]
	v_pk_fma_f32 v[60:61], v[102:103], s[28:29], v[58:59] op_sel_hi:[1,0,1]
	v_cvt_pk_bf16_f32 v58, v62, v63
	v_cvt_pk_bf16_f32 v59, v64, v65
	v_cvt_pk_bf16_f32 v60, v60, v61
	v_cvt_pk_bf16_f32 v61, v66, v67
	v_lshl_add_u64 v[62:63], s[16:17], 0, v[98:99]
	global_store_dwordx4 v[62:63], v[58:61], off nt
	v_lshlrev_b32_e32 v64, 16, v72
	v_and_b32_e32 v65, 0xffff0000, v72
	v_lshlrev_b32_e32 v58, 16, v70
	v_and_b32_e32 v59, 0xffff0000, v70
	v_lshlrev_b32_e32 v60, 16, v71
	v_and_b32_e32 v61, 0xffff0000, v71
	v_lshlrev_b32_e32 v66, 16, v73
	v_and_b32_e32 v67, 0xffff0000, v73
	v_pk_fma_f32 v[56:57], v[60:61], s[28:29], v[56:57] op_sel_hi:[1,0,1]
	v_pk_fma_f32 v[54:55], v[58:59], s[28:29], v[54:55] op_sel_hi:[1,0,1]
	v_pk_fma_f32 v[58:59], v[66:67], s[28:29], v[48:49] op_sel_hi:[1,0,1]
	v_pk_fma_f32 v[48:49], v[64:65], s[28:29], v[46:47] op_sel_hi:[1,0,1]
	v_cvt_pk_bf16_f32 v46, v54, v55
	v_cvt_pk_bf16_f32 v47, v56, v57
	v_cvt_pk_bf16_f32 v48, v48, v49
	v_cvt_pk_bf16_f32 v49, v58, v59
	global_store_dwordx4 v[62:63], v[46:49], off offset:256 nt
	s_waitcnt vmcnt(0) lgkmcnt(0)
	v_lshlrev_b32_e32 v54, 16, v76
	v_lshlrev_b32_e32 v46, 16, v74
	v_and_b32_e32 v47, 0xffff0000, v74
	v_lshlrev_b32_e32 v48, 16, v75
	v_and_b32_e32 v49, 0xffff0000, v75
	v_and_b32_e32 v55, 0xffff0000, v76
	v_lshlrev_b32_e32 v56, 16, v77
	v_and_b32_e32 v57, 0xffff0000, v77
	v_pk_fma_f32 v[46:47], v[46:47], s[28:29], v[50:51] op_sel_hi:[1,0,1]
	v_pk_fma_f32 v[48:49], v[48:49], s[28:29], v[52:53] op_sel_hi:[1,0,1]
	v_pk_fma_f32 v[50:51], v[56:57], s[28:29], v[44:45] op_sel_hi:[1,0,1]
	v_pk_fma_f32 v[44:45], v[54:55], s[28:29], v[42:43] op_sel_hi:[1,0,1]
	v_cvt_pk_bf16_f32 v42, v46, v47
	v_add_co_u32_e32 v46, vcc, s48, v62
	v_cvt_pk_bf16_f32 v43, v48, v49
	v_cvt_pk_bf16_f32 v44, v44, v45
	v_cvt_pk_bf16_f32 v45, v50, v51
	v_addc_co_u32_e32 v47, vcc, 0, v63, vcc
	global_store_dwordx4 v[46:47], v[42:45], off nt
	v_lshlrev_b32_e32 v48, 16, v80
	v_and_b32_e32 v49, 0xffff0000, v80
	v_lshlrev_b32_e32 v42, 16, v78
	v_and_b32_e32 v43, 0xffff0000, v78
	v_lshlrev_b32_e32 v44, 16, v79
	v_and_b32_e32 v45, 0xffff0000, v79
	v_lshlrev_b32_e32 v50, 16, v81
	v_and_b32_e32 v51, 0xffff0000, v81
	v_pk_fma_f32 v[40:41], v[44:45], s[28:29], v[40:41] op_sel_hi:[1,0,1]
	v_pk_fma_f32 v[38:39], v[42:43], s[28:29], v[38:39] op_sel_hi:[1,0,1]
	v_pk_fma_f32 v[42:43], v[50:51], s[28:29], v[32:33] op_sel_hi:[1,0,1]
	v_pk_fma_f32 v[32:33], v[48:49], s[28:29], v[30:31] op_sel_hi:[1,0,1]
	v_cvt_pk_bf16_f32 v30, v38, v39
	v_cvt_pk_bf16_f32 v31, v40, v41
	v_cvt_pk_bf16_f32 v32, v32, v33
	v_cvt_pk_bf16_f32 v33, v42, v43
	global_store_dwordx4 v[46:47], v[30:33], off offset:256 nt
	v_lshlrev_b32_e32 v38, 16, v84
	v_and_b32_e32 v39, 0xffff0000, v84
	v_lshlrev_b32_e32 v30, 16, v82
	v_and_b32_e32 v31, 0xffff0000, v82
	v_lshlrev_b32_e32 v32, 16, v83
	v_and_b32_e32 v33, 0xffff0000, v83
	v_lshlrev_b32_e32 v40, 16, v85
	v_and_b32_e32 v41, 0xffff0000, v85
	v_pk_fma_f32 v[30:31], v[30:31], s[28:29], v[34:35] op_sel_hi:[1,0,1]
	v_pk_fma_f32 v[32:33], v[32:33], s[28:29], v[36:37] op_sel_hi:[1,0,1]
	v_pk_fma_f32 v[34:35], v[40:41], s[28:29], v[28:29] op_sel_hi:[1,0,1]
	v_pk_fma_f32 v[28:29], v[38:39], s[28:29], v[26:27] op_sel_hi:[1,0,1]
	v_cvt_pk_bf16_f32 v26, v30, v31
	v_add_co_u32_e32 v30, vcc, s44, v62
	v_cvt_pk_bf16_f32 v27, v32, v33
	v_cvt_pk_bf16_f32 v28, v28, v29
	v_cvt_pk_bf16_f32 v29, v34, v35
	v_addc_co_u32_e32 v31, vcc, 0, v63, vcc
	global_store_dwordx4 v[30:31], v[26:29], off nt
	v_lshlrev_b32_e32 v32, 16, v88
	v_and_b32_e32 v33, 0xffff0000, v88
	v_lshlrev_b32_e32 v26, 16, v86
	v_and_b32_e32 v27, 0xffff0000, v86
	v_lshlrev_b32_e32 v28, 16, v87
	v_and_b32_e32 v29, 0xffff0000, v87
	v_lshlrev_b32_e32 v34, 16, v89
	v_and_b32_e32 v35, 0xffff0000, v89
	v_pk_fma_f32 v[24:25], v[28:29], s[28:29], v[24:25] op_sel_hi:[1,0,1]
	v_pk_fma_f32 v[22:23], v[26:27], s[28:29], v[22:23] op_sel_hi:[1,0,1]
	v_pk_fma_f32 v[26:27], v[34:35], s[28:29], v[16:17] op_sel_hi:[1,0,1]
	v_pk_fma_f32 v[16:17], v[32:33], s[28:29], v[14:15] op_sel_hi:[1,0,1]
	v_cvt_pk_bf16_f32 v14, v22, v23
	v_cvt_pk_bf16_f32 v15, v24, v25
	v_cvt_pk_bf16_f32 v16, v16, v17
	v_cvt_pk_bf16_f32 v17, v26, v27
	global_store_dwordx4 v[30:31], v[14:17], off offset:256 nt
	v_lshlrev_b32_e32 v22, 16, v92
	v_and_b32_e32 v23, 0xffff0000, v92
	v_lshlrev_b32_e32 v14, 16, v90
	v_and_b32_e32 v15, 0xffff0000, v90
	v_lshlrev_b32_e32 v16, 16, v91
	v_and_b32_e32 v17, 0xffff0000, v91
	v_lshlrev_b32_e32 v24, 16, v93
	v_and_b32_e32 v25, 0xffff0000, v93
	v_pk_fma_f32 v[14:15], v[14:15], s[28:29], v[18:19] op_sel_hi:[1,0,1]
	v_pk_fma_f32 v[16:17], v[16:17], s[28:29], v[20:21] op_sel_hi:[1,0,1]
	v_pk_fma_f32 v[18:19], v[24:25], s[28:29], v[12:13] op_sel_hi:[1,0,1]
	v_pk_fma_f32 v[12:13], v[22:23], s[28:29], v[10:11] op_sel_hi:[1,0,1]
	v_cvt_pk_bf16_f32 v10, v14, v15
	v_add_co_u32_e32 v14, vcc, s47, v62
	v_cvt_pk_bf16_f32 v11, v16, v17
	v_cvt_pk_bf16_f32 v12, v12, v13
	v_cvt_pk_bf16_f32 v13, v18, v19
	v_addc_co_u32_e32 v15, vcc, 0, v63, vcc
	global_store_dwordx4 v[14:15], v[10:13], off nt
	v_lshlrev_b32_e32 v16, 16, v96
	v_and_b32_e32 v17, 0xffff0000, v96
	v_lshlrev_b32_e32 v10, 16, v94
	v_and_b32_e32 v11, 0xffff0000, v94
	v_lshlrev_b32_e32 v12, 16, v95
	v_and_b32_e32 v13, 0xffff0000, v95
	v_lshlrev_b32_e32 v18, 16, v97
	v_and_b32_e32 v19, 0xffff0000, v97
	v_pk_fma_f32 v[8:9], v[12:13], s[28:29], v[8:9] op_sel_hi:[1,0,1]
	v_pk_fma_f32 v[6:7], v[10:11], s[28:29], v[6:7] op_sel_hi:[1,0,1]
	v_pk_fma_f32 v[10:11], v[18:19], s[28:29], v[4:5] op_sel_hi:[1,0,1]
	v_pk_fma_f32 v[4:5], v[16:17], s[28:29], v[2:3] op_sel_hi:[1,0,1]
	v_cvt_pk_bf16_f32 v2, v6, v7
	v_cvt_pk_bf16_f32 v3, v8, v9
	v_cvt_pk_bf16_f32 v4, v4, v5
	v_cvt_pk_bf16_f32 v5, v10, v11
	s_and_b64 vcc, exec, s[30:31]
	global_store_dwordx4 v[14:15], v[2:5], off offset:256 nt
	s_cbranch_vccz .LBB0_2494
	s_waitcnt vmcnt(0)
	s_cmpk_gt_u32 s5, 0xff
	s_cbranch_scc1 .LBB0_2499
	s_barrier
